# v46 + snake order of the 16-MFMA groups in the GEMM K-loops (srcA toggles halved; results bitwise identical)
# baseline (speedup 1.0000x reference)
.LBB0_270:
	s_waitcnt lgkmcnt(0)
	s_barrier
	s_setprio 1
	s_waitcnt lgkmcnt(0)
	v_mfma_f32_16x16x32_bf16 v[58:61], v[146:149], v[186:189], v[58:61]
	v_mfma_f32_16x16x32_bf16 v[50:53], v[154:157], v[186:189], v[50:53]
	v_mfma_f32_16x16x32_bf16 v[34:37], v[154:157], v[178:181], v[34:37]
	v_mfma_f32_16x16x32_bf16 v[42:45], v[146:149], v[178:181], v[42:45]
	v_mfma_f32_16x16x32_bf16 v[26:29], v[146:149], v[170:173], v[26:29]
	v_mfma_f32_16x16x32_bf16 v[18:21], v[154:157], v[170:173], v[18:21]
	v_mfma_f32_16x16x32_bf16 v[2:5], v[154:157], v[162:165], v[2:5]
	v_mfma_f32_16x16x32_bf16 v[10:13], v[146:149], v[162:165], v[10:13]
	v_mfma_f32_16x16x32_bf16 v[58:61], v[150:153], v[190:193], v[58:61]
	v_mfma_f32_16x16x32_bf16 v[50:53], v[158:161], v[190:193], v[50:53]
	v_mfma_f32_16x16x32_bf16 v[34:37], v[158:161], v[182:185], v[34:37]
	v_mfma_f32_16x16x32_bf16 v[42:45], v[150:153], v[182:185], v[42:45]
	v_mfma_f32_16x16x32_bf16 v[26:29], v[150:153], v[174:177], v[26:29]
	v_mfma_f32_16x16x32_bf16 v[18:21], v[158:161], v[174:177], v[18:21]
	v_mfma_f32_16x16x32_bf16 v[2:5], v[158:161], v[166:169], v[2:5]
	v_mfma_f32_16x16x32_bf16 v[10:13], v[150:153], v[166:169], v[10:13]
	s_setprio 0
	s_setprio 1
	v_mfma_f32_16x16x32_bf16 v[62:65], v[130:133], v[186:189], v[62:65]
	v_mfma_f32_16x16x32_bf16 v[54:57], v[138:141], v[186:189], v[54:57]
	v_mfma_f32_16x16x32_bf16 v[38:41], v[138:141], v[178:181], v[38:41]
	v_mfma_f32_16x16x32_bf16 v[46:49], v[130:133], v[178:181], v[46:49]
	v_mfma_f32_16x16x32_bf16 v[30:33], v[130:133], v[170:173], v[30:33]
	v_mfma_f32_16x16x32_bf16 v[22:25], v[138:141], v[170:173], v[22:25]
	v_mfma_f32_16x16x32_bf16 v[6:9], v[138:141], v[162:165], v[6:9]
	v_mfma_f32_16x16x32_bf16 v[14:17], v[130:133], v[162:165], v[14:17]
	v_mfma_f32_16x16x32_bf16 v[62:65], v[134:137], v[190:193], v[62:65]
	v_mfma_f32_16x16x32_bf16 v[54:57], v[142:145], v[190:193], v[54:57]
	v_mfma_f32_16x16x32_bf16 v[38:41], v[142:145], v[182:185], v[38:41]
	v_mfma_f32_16x16x32_bf16 v[46:49], v[134:137], v[182:185], v[46:49]
	v_mfma_f32_16x16x32_bf16 v[30:33], v[134:137], v[174:177], v[30:33]
	v_mfma_f32_16x16x32_bf16 v[22:25], v[142:145], v[174:177], v[22:25]
	v_mfma_f32_16x16x32_bf16 v[6:9], v[142:145], v[166:169], v[6:9]
	v_mfma_f32_16x16x32_bf16 v[14:17], v[134:137], v[166:169], v[14:17]
	s_setprio 0
	s_barrier
	s_add_i32 s33, s33, 2
	s_add_u32 s42, s42, 0x100
	s_addc_u32 s43, s43, 0
	s_cmp_gt_u32 s33, 13
	s_cbranch_scc1 .LBB0_283
.LBB0_271:
	ds_read_b128 v[146:149], v222
	ds_read_b128 v[150:153], v222 offset:1024
	ds_read_b128 v[154:157], v222 offset:2048
	ds_read_b128 v[158:161], v222 offset:3072
	ds_read_b128 v[130:133], v223
	ds_read_b128 v[134:137], v223 offset:1024
	ds_read_b128 v[138:141], v223 offset:2048
	ds_read_b128 v[142:145], v223 offset:3072
	s_add_u32 s46, s90, s42
	s_addc_u32 s47, s91, s43
	s_cmpk_lg_i32 s42, 0x600
	s_cselect_b64 s[48:49], -1, 0
	s_and_b64 s[44:45], s[48:49], exec
	s_cselect_b32 s45, s47, s19
	s_cselect_b32 s44, s46, s29
	v_lshl_add_u64 v[214:215], v[212:213], 0, s[42:43]
	s_mov_b32 m0, s63
	v_lshl_add_u64 v[216:217], v[214:215], 0, s[12:13]
	ds_read_b128 v[162:165], v224
	ds_read_b128 v[166:169], v224 offset:1024
	ds_read_b128 v[170:173], v224 offset:2048
	ds_read_b128 v[174:177], v224 offset:3072
	ds_read_b128 v[178:181], v224 offset:4096
	ds_read_b128 v[182:185], v224 offset:5120
	ds_read_b128 v[186:189], v224 offset:6144
	ds_read_b128 v[190:193], v224 offset:7168
	global_load_lds_dwordx4 v[216:217], off
	v_lshl_add_u64 v[216:217], v[210:211], 0, s[42:43]
	v_lshl_add_u64 v[226:227], v[216:217], 0, s[12:13]
	s_mov_b32 m0, s64
	v_lshl_add_u64 v[214:215], v[214:215], 0, s[14:15]
	global_load_lds_dwordx4 v[226:227], off
	s_mov_b32 m0, s65
	s_nor_b64 s[46:47], s[4:5], s[48:49]
	global_load_lds_dwordx4 v[214:215], off
	v_lshl_add_u64 v[214:215], v[216:217], 0, s[14:15]
	s_mov_b32 m0, s66
	s_nop 0
	global_load_lds_dwordx4 v[214:215], off
	s_waitcnt vmcnt(8)
	s_waitcnt lgkmcnt(0)
	s_barrier
	s_setprio 1
	s_waitcnt lgkmcnt(0)
	v_mfma_f32_16x16x32_bf16 v[122:125], v[146:149], v[162:165], v[122:125]
	v_mfma_f32_16x16x32_bf16 v[114:117], v[154:157], v[162:165], v[114:117]
	v_mfma_f32_16x16x32_bf16 v[98:101], v[154:157], v[170:173], v[98:101]
	v_mfma_f32_16x16x32_bf16 v[106:109], v[146:149], v[170:173], v[106:109]
	v_mfma_f32_16x16x32_bf16 v[90:93], v[146:149], v[178:181], v[90:93]
	v_mfma_f32_16x16x32_bf16 v[82:85], v[154:157], v[178:181], v[82:85]
	v_mfma_f32_16x16x32_bf16 v[66:69], v[154:157], v[186:189], v[66:69]
	v_mfma_f32_16x16x32_bf16 v[74:77], v[146:149], v[186:189], v[74:77]
	v_mfma_f32_16x16x32_bf16 v[122:125], v[150:153], v[166:169], v[122:125]
	v_mfma_f32_16x16x32_bf16 v[114:117], v[158:161], v[166:169], v[114:117]
	v_mfma_f32_16x16x32_bf16 v[98:101], v[158:161], v[174:177], v[98:101]
	v_mfma_f32_16x16x32_bf16 v[106:109], v[150:153], v[174:177], v[106:109]
	v_mfma_f32_16x16x32_bf16 v[90:93], v[150:153], v[182:185], v[90:93]
	v_mfma_f32_16x16x32_bf16 v[82:85], v[158:161], v[182:185], v[82:85]
	v_mfma_f32_16x16x32_bf16 v[66:69], v[158:161], v[190:193], v[66:69]
	v_mfma_f32_16x16x32_bf16 v[74:77], v[150:153], v[190:193], v[74:77]
	s_setprio 0
	s_setprio 1
	v_mfma_f32_16x16x32_bf16 v[126:129], v[130:133], v[162:165], v[126:129]
	v_mfma_f32_16x16x32_bf16 v[118:121], v[138:141], v[162:165], v[118:121]
	v_mfma_f32_16x16x32_bf16 v[102:105], v[138:141], v[170:173], v[102:105]
	v_mfma_f32_16x16x32_bf16 v[110:113], v[130:133], v[170:173], v[110:113]
	v_mfma_f32_16x16x32_bf16 v[94:97], v[130:133], v[178:181], v[94:97]
	v_mfma_f32_16x16x32_bf16 v[86:89], v[138:141], v[178:181], v[86:89]
	v_mfma_f32_16x16x32_bf16 v[70:73], v[138:141], v[186:189], v[70:73]
	v_mfma_f32_16x16x32_bf16 v[78:81], v[130:133], v[186:189], v[78:81]
	v_mfma_f32_16x16x32_bf16 v[126:129], v[134:137], v[166:169], v[126:129]
	v_mfma_f32_16x16x32_bf16 v[118:121], v[142:145], v[166:169], v[118:121]
	v_mfma_f32_16x16x32_bf16 v[102:105], v[142:145], v[174:177], v[102:105]
	v_mfma_f32_16x16x32_bf16 v[110:113], v[134:137], v[174:177], v[110:113]
	v_mfma_f32_16x16x32_bf16 v[94:97], v[134:137], v[182:185], v[94:97]
	v_mfma_f32_16x16x32_bf16 v[86:89], v[142:145], v[182:185], v[86:89]
	v_mfma_f32_16x16x32_bf16 v[70:73], v[142:145], v[190:193], v[70:73]
	v_mfma_f32_16x16x32_bf16 v[78:81], v[134:137], v[190:193], v[78:81]
	s_setprio 0
	s_barrier
	ds_read_b128 v[186:189], v224 offset:16384
	ds_read_b128 v[190:193], v224 offset:17408
	ds_read_b128 v[178:181], v224 offset:18432
	ds_read_b128 v[182:185], v224 offset:19456
	ds_read_b128 v[170:173], v224 offset:20480
	ds_read_b128 v[174:177], v224 offset:21504
	ds_read_b128 v[162:165], v224 offset:22528
	ds_read_b128 v[166:169], v224 offset:23552
	s_mov_b64 s[50:51], -1
	s_and_b64 vcc, exec, s[46:47]
	s_cbranch_vccz .LBB0_273
	s_waitcnt vmcnt(2)
	s_mov_b64 s[50:51], 0

.LBB0_275:
	s_waitcnt lgkmcnt(0)
	s_barrier
	s_setprio 1
	s_waitcnt lgkmcnt(0)
	v_mfma_f32_16x16x32_bf16 v[58:61], v[146:149], v[186:189], v[58:61]
	v_mfma_f32_16x16x32_bf16 v[50:53], v[154:157], v[186:189], v[50:53]
	v_mfma_f32_16x16x32_bf16 v[34:37], v[154:157], v[178:181], v[34:37]
	v_mfma_f32_16x16x32_bf16 v[42:45], v[146:149], v[178:181], v[42:45]
	v_mfma_f32_16x16x32_bf16 v[26:29], v[146:149], v[170:173], v[26:29]
	v_mfma_f32_16x16x32_bf16 v[18:21], v[154:157], v[170:173], v[18:21]
	v_mfma_f32_16x16x32_bf16 v[2:5], v[154:157], v[162:165], v[2:5]
	v_mfma_f32_16x16x32_bf16 v[10:13], v[146:149], v[162:165], v[10:13]
	v_mfma_f32_16x16x32_bf16 v[58:61], v[150:153], v[190:193], v[58:61]
	v_mfma_f32_16x16x32_bf16 v[50:53], v[158:161], v[190:193], v[50:53]
	v_mfma_f32_16x16x32_bf16 v[34:37], v[158:161], v[182:185], v[34:37]
	v_mfma_f32_16x16x32_bf16 v[42:45], v[150:153], v[182:185], v[42:45]
	v_mfma_f32_16x16x32_bf16 v[26:29], v[150:153], v[174:177], v[26:29]
	v_mfma_f32_16x16x32_bf16 v[18:21], v[158:161], v[174:177], v[18:21]
	v_mfma_f32_16x16x32_bf16 v[2:5], v[158:161], v[166:169], v[2:5]
	v_mfma_f32_16x16x32_bf16 v[10:13], v[150:153], v[166:169], v[10:13]
	s_setprio 0
	s_setprio 1
	v_mfma_f32_16x16x32_bf16 v[62:65], v[130:133], v[186:189], v[62:65]
	v_mfma_f32_16x16x32_bf16 v[54:57], v[138:141], v[186:189], v[54:57]
	v_mfma_f32_16x16x32_bf16 v[38:41], v[138:141], v[178:181], v[38:41]
	v_mfma_f32_16x16x32_bf16 v[46:49], v[130:133], v[178:181], v[46:49]
	v_mfma_f32_16x16x32_bf16 v[30:33], v[130:133], v[170:173], v[30:33]
	v_mfma_f32_16x16x32_bf16 v[22:25], v[138:141], v[170:173], v[22:25]
	v_mfma_f32_16x16x32_bf16 v[6:9], v[138:141], v[162:165], v[6:9]
	v_mfma_f32_16x16x32_bf16 v[14:17], v[130:133], v[162:165], v[14:17]
	v_mfma_f32_16x16x32_bf16 v[62:65], v[134:137], v[190:193], v[62:65]
	v_mfma_f32_16x16x32_bf16 v[54:57], v[142:145], v[190:193], v[54:57]
	v_mfma_f32_16x16x32_bf16 v[38:41], v[142:145], v[182:185], v[38:41]
	v_mfma_f32_16x16x32_bf16 v[46:49], v[134:137], v[182:185], v[46:49]
	v_mfma_f32_16x16x32_bf16 v[30:33], v[134:137], v[174:177], v[30:33]
	v_mfma_f32_16x16x32_bf16 v[22:25], v[142:145], v[174:177], v[22:25]
	v_mfma_f32_16x16x32_bf16 v[6:9], v[142:145], v[166:169], v[6:9]
	v_mfma_f32_16x16x32_bf16 v[14:17], v[134:137], v[166:169], v[14:17]
	s_setprio 0
	s_barrier
	v_add_u32_e32 v130, 0x18000, v221
	v_add_u32_e32 v142, 0x1c000, v221
	ds_read_b128 v[146:149], v130
	ds_read_b128 v[150:153], v130 offset:1024
	ds_read_b128 v[154:157], v130 offset:2048
	ds_read_b128 v[158:161], v130 offset:3072
	ds_read_b128 v[130:133], v142
	ds_read_b128 v[134:137], v142 offset:1024
	ds_read_b128 v[138:141], v142 offset:2048
	ds_read_b128 v[142:145], v142 offset:3072
	ds_read_b128 v[186:189], v224 offset:32768
	ds_read_b128 v[190:193], v224 offset:33792
	ds_read_b128 v[178:181], v224 offset:34816
	ds_read_b128 v[182:185], v224 offset:35840
	ds_read_b128 v[170:173], v224 offset:36864
	ds_read_b128 v[174:177], v224 offset:37888
	ds_read_b128 v[162:165], v224 offset:38912
	ds_read_b128 v[166:169], v224 offset:39936
	s_mov_b64 s[50:51], -1
	s_and_b64 vcc, exec, s[46:47]
	s_cbranch_vccz .LBB0_277
	s_waitcnt vmcnt(0)
	s_mov_b64 s[50:51], 0

.LBB0_279:
	s_waitcnt lgkmcnt(0)
	s_barrier
	s_setprio 1
	s_waitcnt lgkmcnt(0)
	v_mfma_f32_16x16x32_bf16 v[122:125], v[146:149], v[186:189], v[122:125]
	v_mfma_f32_16x16x32_bf16 v[114:117], v[154:157], v[186:189], v[114:117]
	v_mfma_f32_16x16x32_bf16 v[98:101], v[154:157], v[178:181], v[98:101]
	v_mfma_f32_16x16x32_bf16 v[106:109], v[146:149], v[178:181], v[106:109]
	v_mfma_f32_16x16x32_bf16 v[90:93], v[146:149], v[170:173], v[90:93]
	v_mfma_f32_16x16x32_bf16 v[82:85], v[154:157], v[170:173], v[82:85]
	v_mfma_f32_16x16x32_bf16 v[66:69], v[154:157], v[162:165], v[66:69]
	v_mfma_f32_16x16x32_bf16 v[74:77], v[146:149], v[162:165], v[74:77]
	v_mfma_f32_16x16x32_bf16 v[122:125], v[150:153], v[190:193], v[122:125]
	v_mfma_f32_16x16x32_bf16 v[114:117], v[158:161], v[190:193], v[114:117]
	v_mfma_f32_16x16x32_bf16 v[98:101], v[158:161], v[182:185], v[98:101]
	v_mfma_f32_16x16x32_bf16 v[106:109], v[150:153], v[182:185], v[106:109]
	v_mfma_f32_16x16x32_bf16 v[90:93], v[150:153], v[174:177], v[90:93]
	v_mfma_f32_16x16x32_bf16 v[82:85], v[158:161], v[174:177], v[82:85]
	v_mfma_f32_16x16x32_bf16 v[66:69], v[158:161], v[166:169], v[66:69]
	v_mfma_f32_16x16x32_bf16 v[74:77], v[150:153], v[166:169], v[74:77]
	s_setprio 0
	s_setprio 1
	v_mfma_f32_16x16x32_bf16 v[126:129], v[130:133], v[186:189], v[126:129]
	v_mfma_f32_16x16x32_bf16 v[118:121], v[138:141], v[186:189], v[118:121]
	v_mfma_f32_16x16x32_bf16 v[102:105], v[138:141], v[178:181], v[102:105]
	v_mfma_f32_16x16x32_bf16 v[110:113], v[130:133], v[178:181], v[110:113]
	v_mfma_f32_16x16x32_bf16 v[94:97], v[130:133], v[170:173], v[94:97]
	v_mfma_f32_16x16x32_bf16 v[86:89], v[138:141], v[170:173], v[86:89]
	v_mfma_f32_16x16x32_bf16 v[70:73], v[138:141], v[162:165], v[70:73]
	v_mfma_f32_16x16x32_bf16 v[78:81], v[130:133], v[162:165], v[78:81]
	v_mfma_f32_16x16x32_bf16 v[126:129], v[134:137], v[190:193], v[126:129]
	v_mfma_f32_16x16x32_bf16 v[118:121], v[142:145], v[190:193], v[118:121]
	v_mfma_f32_16x16x32_bf16 v[102:105], v[142:145], v[182:185], v[102:105]
	v_mfma_f32_16x16x32_bf16 v[110:113], v[134:137], v[182:185], v[110:113]
	v_mfma_f32_16x16x32_bf16 v[94:97], v[134:137], v[174:177], v[94:97]
	v_mfma_f32_16x16x32_bf16 v[86:89], v[142:145], v[174:177], v[86:89]
	v_mfma_f32_16x16x32_bf16 v[70:73], v[142:145], v[166:169], v[70:73]
	v_mfma_f32_16x16x32_bf16 v[78:81], v[134:137], v[166:169], v[78:81]
	s_setprio 0
	s_barrier
	ds_read_b128 v[186:189], v224 offset:49152
	ds_read_b128 v[190:193], v224 offset:50176
	ds_read_b128 v[178:181], v224 offset:51200
	ds_read_b128 v[182:185], v224 offset:52224
	ds_read_b128 v[170:173], v224 offset:53248
	ds_read_b128 v[174:177], v224 offset:54272
	ds_read_b128 v[162:165], v224 offset:55296
	ds_read_b128 v[166:169], v224 offset:56320
	s_mov_b64 s[48:49], -1
	s_and_b64 vcc, exec, s[46:47]
	s_cbranch_vccz .LBB0_281
	s_waitcnt vmcnt(0)
	s_mov_b64 s[48:49], 0

.LBB0_381:
	s_waitcnt lgkmcnt(0)
	s_barrier
	s_setprio 1
	s_waitcnt lgkmcnt(0)
	v_mfma_f32_16x16x32_bf16 v[6:9], v[158:161], v[186:189], v[6:9]
	v_mfma_f32_16x16x32_bf16 v[10:13], v[166:169], v[186:189], v[10:13]
	v_mfma_f32_16x16x32_bf16 v[18:21], v[166:169], v[178:181], v[18:21]
	v_mfma_f32_16x16x32_bf16 v[14:17], v[158:161], v[178:181], v[14:17]
	v_mfma_f32_16x16x32_bf16 v[22:25], v[158:161], v[130:133], v[22:25]
	v_mfma_f32_16x16x32_bf16 v[26:29], v[166:169], v[130:133], v[26:29]
	v_mfma_f32_16x16x32_bf16 v[34:37], v[166:169], v[98:101], v[34:37]
	v_mfma_f32_16x16x32_bf16 v[30:33], v[158:161], v[98:101], v[30:33]
	v_mfma_f32_16x16x32_bf16 v[6:9], v[162:165], v[190:193], v[6:9]
	v_mfma_f32_16x16x32_bf16 v[10:13], v[170:173], v[190:193], v[10:13]
	v_mfma_f32_16x16x32_bf16 v[18:21], v[170:173], v[182:185], v[18:21]
	v_mfma_f32_16x16x32_bf16 v[14:17], v[162:165], v[182:185], v[14:17]
	v_mfma_f32_16x16x32_bf16 v[22:25], v[162:165], v[174:177], v[22:25]
	v_mfma_f32_16x16x32_bf16 v[26:29], v[170:173], v[174:177], v[26:29]
	v_mfma_f32_16x16x32_bf16 v[34:37], v[170:173], v[102:105], v[34:37]
	v_mfma_f32_16x16x32_bf16 v[30:33], v[162:165], v[102:105], v[30:33]
	s_setprio 0
	s_setprio 1
	v_mfma_f32_16x16x32_bf16 v[38:41], v[142:145], v[186:189], v[38:41]
	v_mfma_f32_16x16x32_bf16 v[42:45], v[150:153], v[186:189], v[42:45]
	v_mfma_f32_16x16x32_bf16 v[50:53], v[150:153], v[178:181], v[50:53]
	v_mfma_f32_16x16x32_bf16 v[46:49], v[142:145], v[178:181], v[46:49]
	v_mfma_f32_16x16x32_bf16 v[54:57], v[142:145], v[130:133], v[54:57]
	v_mfma_f32_16x16x32_bf16 v[62:65], v[150:153], v[130:133], v[62:65]
	v_mfma_f32_16x16x32_bf16 v[70:73], v[150:153], v[98:101], v[70:73]
	v_mfma_f32_16x16x32_bf16 v[66:69], v[142:145], v[98:101], v[66:69]
	v_mfma_f32_16x16x32_bf16 v[38:41], v[146:149], v[190:193], v[38:41]
	v_mfma_f32_16x16x32_bf16 v[42:45], v[154:157], v[190:193], v[42:45]
	v_mfma_f32_16x16x32_bf16 v[50:53], v[154:157], v[182:185], v[50:53]
	v_mfma_f32_16x16x32_bf16 v[46:49], v[146:149], v[182:185], v[46:49]
	v_mfma_f32_16x16x32_bf16 v[54:57], v[146:149], v[174:177], v[54:57]
	v_mfma_f32_16x16x32_bf16 v[62:65], v[154:157], v[174:177], v[62:65]
	v_mfma_f32_16x16x32_bf16 v[70:73], v[154:157], v[102:105], v[70:73]
	v_mfma_f32_16x16x32_bf16 v[66:69], v[146:149], v[102:105], v[66:69]
	s_setprio 0
	s_barrier
	s_add_i32 s33, s33, 2
	s_add_u32 s42, s42, 0x100
	s_addc_u32 s43, s43, 0
	s_cmp_gt_u32 s33, 41
	s_cbranch_scc1 .LBB0_394
.LBB0_382:
	ds_read_b128 v[158:161], v222
	ds_read_b128 v[162:165], v222 offset:1024
	ds_read_b128 v[166:169], v222 offset:2048
	ds_read_b128 v[170:173], v222 offset:3072
	ds_read_b128 v[142:145], v223
	ds_read_b128 v[146:149], v223 offset:1024
	ds_read_b128 v[150:153], v223 offset:2048
	ds_read_b128 v[154:157], v223 offset:3072
	s_add_u32 s46, s18, s42
	s_addc_u32 s47, s19, s43
	s_cmpk_lg_i32 s42, 0x1400
	s_cselect_b64 s[48:49], -1, 0
	s_and_b64 s[44:45], s[48:49], exec
	s_cselect_b32 s45, s47, s41
	s_cselect_b32 s44, s46, s40
	v_lshl_add_u64 v[98:99], v[210:211], 0, s[42:43]
	s_mov_b32 m0, s68
	v_lshl_add_u64 v[100:101], v[98:99], 0, s[30:31]
	ds_read_b128 v[102:105], v224
	ds_read_b128 v[130:133], v224 offset:1024
	ds_read_b128 v[174:177], v224 offset:2048
	ds_read_b128 v[178:181], v224 offset:3072
	ds_read_b128 v[182:185], v224 offset:4096
	ds_read_b128 v[186:189], v224 offset:5120
	ds_read_b128 v[190:193], v224 offset:6144
	ds_read_b128 v[194:197], v224 offset:7168
	global_load_lds_dwordx4 v[100:101], off
	v_lshl_add_u64 v[100:101], v[212:213], 0, s[42:43]
	v_lshl_add_u64 v[214:215], v[100:101], 0, s[30:31]
	s_mov_b32 m0, s69
	v_lshl_add_u64 v[98:99], v[98:99], 0, s[36:37]
	global_load_lds_dwordx4 v[214:215], off
	s_mov_b32 m0, s70
	s_nor_b64 s[46:47], s[6:7], s[48:49]
	global_load_lds_dwordx4 v[98:99], off
	v_lshl_add_u64 v[98:99], v[100:101], 0, s[36:37]
	s_mov_b32 m0, s71
	s_nop 0
	global_load_lds_dwordx4 v[98:99], off
	s_waitcnt vmcnt(8)
	s_waitcnt lgkmcnt(0)
	s_barrier
	s_setprio 1
	s_waitcnt lgkmcnt(0)
	v_mfma_f32_16x16x32_bf16 v[2:5], v[158:161], v[102:105], v[2:5]
	v_mfma_f32_16x16x32_bf16 v[58:61], v[166:169], v[102:105], v[58:61]
	v_mfma_f32_16x16x32_bf16 v[78:81], v[166:169], v[174:177], v[78:81]
	v_mfma_f32_16x16x32_bf16 v[74:77], v[158:161], v[174:177], v[74:77]
	v_mfma_f32_16x16x32_bf16 v[82:85], v[158:161], v[182:185], v[82:85]
	v_mfma_f32_16x16x32_bf16 v[86:89], v[166:169], v[182:185], v[86:89]
	v_mfma_f32_16x16x32_bf16 v[94:97], v[166:169], v[190:193], v[94:97]
	v_mfma_f32_16x16x32_bf16 v[90:93], v[158:161], v[190:193], v[90:93]
	v_mfma_f32_16x16x32_bf16 v[2:5], v[162:165], v[130:133], v[2:5]
	v_mfma_f32_16x16x32_bf16 v[58:61], v[170:173], v[130:133], v[58:61]
	v_mfma_f32_16x16x32_bf16 v[78:81], v[170:173], v[178:181], v[78:81]
	v_mfma_f32_16x16x32_bf16 v[74:77], v[162:165], v[178:181], v[74:77]
	v_mfma_f32_16x16x32_bf16 v[82:85], v[162:165], v[186:189], v[82:85]
	v_mfma_f32_16x16x32_bf16 v[86:89], v[170:173], v[186:189], v[86:89]
	v_mfma_f32_16x16x32_bf16 v[94:97], v[170:173], v[194:197], v[94:97]
	v_mfma_f32_16x16x32_bf16 v[90:93], v[162:165], v[194:197], v[90:93]
	s_setprio 0
	s_setprio 1
	v_mfma_f32_16x16x32_bf16 v[98:101], v[142:145], v[102:105], v[106:109]
	v_mfma_f32_16x16x32_bf16 v[106:109], v[142:145], v[174:177], v[114:117]
	v_mfma_f32_16x16x32_bf16 v[114:117], v[146:149], v[178:181], v[106:109]
	v_mfma_f32_16x16x32_bf16 v[106:109], v[150:153], v[174:177], v[118:121]
	v_mfma_f32_16x16x32_bf16 v[118:121], v[154:157], v[178:181], v[106:109]
	v_mfma_f32_16x16x32_bf16 v[106:109], v[142:145], v[182:185], v[122:125]
	v_mfma_f32_16x16x32_bf16 v[122:125], v[146:149], v[186:189], v[106:109]
	v_mfma_f32_16x16x32_bf16 v[106:109], v[150:153], v[182:185], v[126:129]
	v_mfma_f32_16x16x32_bf16 v[102:105], v[150:153], v[102:105], v[110:113]
	v_mfma_f32_16x16x32_bf16 v[126:129], v[154:157], v[186:189], v[106:109]
	v_mfma_f32_16x16x32_bf16 v[106:109], v[142:145], v[190:193], v[134:137]
	v_mfma_f32_16x16x32_bf16 v[98:101], v[146:149], v[130:133], v[98:101]
	v_mfma_f32_16x16x32_bf16 v[102:105], v[154:157], v[130:133], v[102:105]
	v_mfma_f32_16x16x32_bf16 v[130:133], v[146:149], v[194:197], v[106:109]
	v_mfma_f32_16x16x32_bf16 v[106:109], v[150:153], v[190:193], v[138:141]
	v_mfma_f32_16x16x32_bf16 v[138:141], v[154:157], v[194:197], v[106:109]
	s_setprio 0
	s_barrier
	ds_read_b128 v[186:189], v224 offset:16384
	ds_read_b128 v[190:193], v224 offset:17408
	ds_read_b128 v[178:181], v224 offset:18432
	ds_read_b128 v[182:185], v224 offset:19456
	ds_read_b128 v[134:137], v224 offset:20480
	ds_read_b128 v[174:177], v224 offset:21504
	ds_read_b128 v[106:109], v224 offset:22528
	ds_read_b128 v[110:113], v224 offset:23552
	s_mov_b64 s[50:51], -1
	s_and_b64 vcc, exec, s[46:47]
	s_cbranch_vccz .LBB0_384
	s_waitcnt vmcnt(2)
	s_mov_b64 s[50:51], 0

.LBB0_386:
	s_waitcnt lgkmcnt(0)
	s_barrier
	s_setprio 1
	s_waitcnt lgkmcnt(0)
	v_mfma_f32_16x16x32_bf16 v[6:9], v[158:161], v[186:189], v[6:9]
	v_mfma_f32_16x16x32_bf16 v[10:13], v[166:169], v[186:189], v[10:13]
	v_mfma_f32_16x16x32_bf16 v[18:21], v[166:169], v[178:181], v[18:21]
	v_mfma_f32_16x16x32_bf16 v[14:17], v[158:161], v[178:181], v[14:17]
	v_mfma_f32_16x16x32_bf16 v[22:25], v[158:161], v[134:137], v[22:25]
	v_mfma_f32_16x16x32_bf16 v[26:29], v[166:169], v[134:137], v[26:29]
	v_mfma_f32_16x16x32_bf16 v[34:37], v[166:169], v[106:109], v[34:37]
	v_mfma_f32_16x16x32_bf16 v[30:33], v[158:161], v[106:109], v[30:33]
	v_mfma_f32_16x16x32_bf16 v[6:9], v[162:165], v[190:193], v[6:9]
	v_mfma_f32_16x16x32_bf16 v[10:13], v[170:173], v[190:193], v[10:13]
	v_mfma_f32_16x16x32_bf16 v[18:21], v[170:173], v[182:185], v[18:21]
	v_mfma_f32_16x16x32_bf16 v[14:17], v[162:165], v[182:185], v[14:17]
	v_mfma_f32_16x16x32_bf16 v[22:25], v[162:165], v[174:177], v[22:25]
	v_mfma_f32_16x16x32_bf16 v[26:29], v[170:173], v[174:177], v[26:29]
	v_mfma_f32_16x16x32_bf16 v[34:37], v[170:173], v[110:113], v[34:37]
	v_mfma_f32_16x16x32_bf16 v[30:33], v[162:165], v[110:113], v[30:33]
	s_setprio 0
	s_setprio 1
	v_mfma_f32_16x16x32_bf16 v[38:41], v[142:145], v[186:189], v[38:41]
	v_mfma_f32_16x16x32_bf16 v[42:45], v[150:153], v[186:189], v[42:45]
	v_mfma_f32_16x16x32_bf16 v[50:53], v[150:153], v[178:181], v[50:53]
	v_mfma_f32_16x16x32_bf16 v[46:49], v[142:145], v[178:181], v[46:49]
	v_mfma_f32_16x16x32_bf16 v[54:57], v[142:145], v[134:137], v[54:57]
	v_mfma_f32_16x16x32_bf16 v[62:65], v[150:153], v[134:137], v[62:65]
	v_mfma_f32_16x16x32_bf16 v[70:73], v[150:153], v[106:109], v[70:73]
	v_mfma_f32_16x16x32_bf16 v[66:69], v[142:145], v[106:109], v[66:69]
	v_mfma_f32_16x16x32_bf16 v[38:41], v[146:149], v[190:193], v[38:41]
	v_mfma_f32_16x16x32_bf16 v[42:45], v[154:157], v[190:193], v[42:45]
	v_mfma_f32_16x16x32_bf16 v[50:53], v[154:157], v[182:185], v[50:53]
	v_mfma_f32_16x16x32_bf16 v[46:49], v[146:149], v[182:185], v[46:49]
	v_mfma_f32_16x16x32_bf16 v[54:57], v[146:149], v[174:177], v[54:57]
	v_mfma_f32_16x16x32_bf16 v[62:65], v[154:157], v[174:177], v[62:65]
	v_mfma_f32_16x16x32_bf16 v[70:73], v[154:157], v[110:113], v[70:73]
	v_mfma_f32_16x16x32_bf16 v[66:69], v[146:149], v[110:113], v[66:69]
	s_setprio 0
	s_barrier
	v_add_u32_e32 v106, 0x18000, v221
	ds_read_b128 v[158:161], v106
	ds_read_b128 v[162:165], v106 offset:1024
	ds_read_b128 v[166:169], v106 offset:2048
	ds_read_b128 v[170:173], v106 offset:3072
	v_add_u32_e32 v106, 0x1c000, v221
	ds_read_b128 v[142:145], v106
	ds_read_b128 v[146:149], v106 offset:1024
	ds_read_b128 v[150:153], v106 offset:2048
	ds_read_b128 v[154:157], v106 offset:3072
	ds_read_b128 v[110:113], v224 offset:32768
	ds_read_b128 v[194:197], v224 offset:33792
	ds_read_b128 v[186:189], v224 offset:34816
	ds_read_b128 v[190:193], v224 offset:35840
	ds_read_b128 v[134:137], v224 offset:36864
	ds_read_b128 v[182:185], v224 offset:37888
	ds_read_b128 v[174:177], v224 offset:38912
	ds_read_b128 v[178:181], v224 offset:39936
	s_mov_b64 s[50:51], -1
	s_and_b64 vcc, exec, s[46:47]
	s_cbranch_vccz .LBB0_388
	s_waitcnt vmcnt(0)
	s_mov_b64 s[50:51], 0

.LBB0_390:
	s_waitcnt lgkmcnt(0)
	s_barrier
	s_setprio 1
	s_waitcnt lgkmcnt(0)
	v_mfma_f32_16x16x32_bf16 v[2:5], v[158:161], v[110:113], v[2:5]
	v_mfma_f32_16x16x32_bf16 v[58:61], v[166:169], v[110:113], v[58:61]
	v_mfma_f32_16x16x32_bf16 v[78:81], v[166:169], v[186:189], v[78:81]
	v_mfma_f32_16x16x32_bf16 v[74:77], v[158:161], v[186:189], v[74:77]
	v_mfma_f32_16x16x32_bf16 v[82:85], v[158:161], v[134:137], v[82:85]
	v_mfma_f32_16x16x32_bf16 v[86:89], v[166:169], v[134:137], v[86:89]
	v_mfma_f32_16x16x32_bf16 v[94:97], v[166:169], v[174:177], v[94:97]
	v_mfma_f32_16x16x32_bf16 v[90:93], v[158:161], v[174:177], v[90:93]
	v_mfma_f32_16x16x32_bf16 v[2:5], v[162:165], v[194:197], v[2:5]
	v_mfma_f32_16x16x32_bf16 v[58:61], v[170:173], v[194:197], v[58:61]
	v_mfma_f32_16x16x32_bf16 v[78:81], v[170:173], v[190:193], v[78:81]
	v_mfma_f32_16x16x32_bf16 v[74:77], v[162:165], v[190:193], v[74:77]
	v_mfma_f32_16x16x32_bf16 v[82:85], v[162:165], v[182:185], v[82:85]
	v_mfma_f32_16x16x32_bf16 v[86:89], v[170:173], v[182:185], v[86:89]
	v_mfma_f32_16x16x32_bf16 v[94:97], v[170:173], v[178:181], v[94:97]
	v_mfma_f32_16x16x32_bf16 v[90:93], v[162:165], v[178:181], v[90:93]
	s_setprio 0
	s_setprio 1
	v_mfma_f32_16x16x32_bf16 v[98:101], v[142:145], v[110:113], v[98:101]
	v_mfma_f32_16x16x32_bf16 v[106:109], v[146:149], v[194:197], v[98:101]
	v_mfma_f32_16x16x32_bf16 v[98:101], v[150:153], v[110:113], v[102:105]
	v_mfma_f32_16x16x32_bf16 v[110:113], v[154:157], v[194:197], v[98:101]
	v_mfma_f32_16x16x32_bf16 v[98:101], v[142:145], v[186:189], v[114:117]
	v_mfma_f32_16x16x32_bf16 v[114:117], v[146:149], v[190:193], v[98:101]
	v_mfma_f32_16x16x32_bf16 v[98:101], v[150:153], v[186:189], v[118:121]
	v_mfma_f32_16x16x32_bf16 v[118:121], v[154:157], v[190:193], v[98:101]
	v_mfma_f32_16x16x32_bf16 v[98:101], v[142:145], v[134:137], v[122:125]
	v_mfma_f32_16x16x32_bf16 v[122:125], v[146:149], v[182:185], v[98:101]
	v_mfma_f32_16x16x32_bf16 v[98:101], v[150:153], v[134:137], v[126:129]
	v_mfma_f32_16x16x32_bf16 v[126:129], v[154:157], v[182:185], v[98:101]
	v_mfma_f32_16x16x32_bf16 v[98:101], v[142:145], v[174:177], v[130:133]
	v_mfma_f32_16x16x32_bf16 v[134:137], v[146:149], v[178:181], v[98:101]
	v_mfma_f32_16x16x32_bf16 v[98:101], v[150:153], v[174:177], v[138:141]
	v_mfma_f32_16x16x32_bf16 v[138:141], v[154:157], v[178:181], v[98:101]
	s_setprio 0
	s_barrier
	ds_read_b128 v[186:189], v224 offset:49152
	ds_read_b128 v[190:193], v224 offset:50176
	ds_read_b128 v[178:181], v224 offset:51200
	ds_read_b128 v[182:185], v224 offset:52224
	ds_read_b128 v[130:133], v224 offset:53248
	ds_read_b128 v[174:177], v224 offset:54272
	ds_read_b128 v[98:101], v224 offset:55296
	ds_read_b128 v[102:105], v224 offset:56320
	s_mov_b64 s[48:49], -1
	s_and_b64 vcc, exec, s[46:47]
	s_cbranch_vccz .LBB0_392
	s_waitcnt vmcnt(0)
	s_mov_b64 s[48:49], 0

.LBB0_460:
	s_waitcnt lgkmcnt(0)
	s_barrier
	s_setprio 1
	s_waitcnt lgkmcnt(0)
	v_mfma_f32_16x16x32_bf16 v[62:65], v[154:157], v[186:189], v[62:65]
	v_mfma_f32_16x16x32_bf16 v[54:57], v[146:149], v[186:189], v[54:57]
	v_mfma_f32_16x16x32_bf16 v[38:41], v[146:149], v[178:181], v[38:41]
	v_mfma_f32_16x16x32_bf16 v[46:49], v[154:157], v[178:181], v[46:49]
	v_mfma_f32_16x16x32_bf16 v[30:33], v[154:157], v[170:173], v[30:33]
	v_mfma_f32_16x16x32_bf16 v[22:25], v[146:149], v[170:173], v[22:25]
	v_mfma_f32_16x16x32_bf16 v[6:9], v[146:149], v[162:165], v[6:9]
	v_mfma_f32_16x16x32_bf16 v[14:17], v[154:157], v[162:165], v[14:17]
	v_mfma_f32_16x16x32_bf16 v[62:65], v[158:161], v[190:193], v[62:65]
	v_mfma_f32_16x16x32_bf16 v[54:57], v[150:153], v[190:193], v[54:57]
	v_mfma_f32_16x16x32_bf16 v[38:41], v[150:153], v[182:185], v[38:41]
	v_mfma_f32_16x16x32_bf16 v[46:49], v[158:161], v[182:185], v[46:49]
	v_mfma_f32_16x16x32_bf16 v[30:33], v[158:161], v[174:177], v[30:33]
	v_mfma_f32_16x16x32_bf16 v[22:25], v[150:153], v[174:177], v[22:25]
	v_mfma_f32_16x16x32_bf16 v[6:9], v[150:153], v[166:169], v[6:9]
	v_mfma_f32_16x16x32_bf16 v[14:17], v[158:161], v[166:169], v[14:17]
	s_setprio 0
	s_setprio 1
	v_mfma_f32_16x16x32_bf16 v[58:61], v[138:141], v[186:189], v[58:61]
	v_mfma_f32_16x16x32_bf16 v[50:53], v[130:133], v[186:189], v[50:53]
	v_mfma_f32_16x16x32_bf16 v[34:37], v[130:133], v[178:181], v[34:37]
	v_mfma_f32_16x16x32_bf16 v[42:45], v[138:141], v[178:181], v[42:45]
	v_mfma_f32_16x16x32_bf16 v[26:29], v[138:141], v[170:173], v[26:29]
	v_mfma_f32_16x16x32_bf16 v[18:21], v[130:133], v[170:173], v[18:21]
	v_mfma_f32_16x16x32_bf16 v[2:5], v[130:133], v[162:165], v[2:5]
	v_mfma_f32_16x16x32_bf16 v[10:13], v[138:141], v[162:165], v[10:13]
	v_mfma_f32_16x16x32_bf16 v[58:61], v[142:145], v[190:193], v[58:61]
	v_mfma_f32_16x16x32_bf16 v[50:53], v[134:137], v[190:193], v[50:53]
	v_mfma_f32_16x16x32_bf16 v[34:37], v[134:137], v[182:185], v[34:37]
	v_mfma_f32_16x16x32_bf16 v[42:45], v[142:145], v[182:185], v[42:45]
	v_mfma_f32_16x16x32_bf16 v[26:29], v[142:145], v[174:177], v[26:29]
	v_mfma_f32_16x16x32_bf16 v[18:21], v[134:137], v[174:177], v[18:21]
	v_mfma_f32_16x16x32_bf16 v[2:5], v[134:137], v[166:169], v[2:5]
	v_mfma_f32_16x16x32_bf16 v[10:13], v[142:145], v[166:169], v[10:13]
	s_setprio 0
	s_barrier
	s_add_i32 s58, s58, 2
	s_add_u32 s44, s44, 0x100
	s_addc_u32 s45, s45, 0
	s_cmp_gt_u32 s58, 41
	s_cbranch_scc1 .LBB0_473
.LBB0_461:
	ds_read_b128 v[146:149], v217
	ds_read_b128 v[150:153], v217 offset:1024
	ds_read_b128 v[154:157], v217 offset:2048
	ds_read_b128 v[158:161], v217 offset:3072
	ds_read_b128 v[130:133], v218
	ds_read_b128 v[134:137], v218 offset:1024
	ds_read_b128 v[138:141], v218 offset:2048
	ds_read_b128 v[142:145], v218 offset:3072
	s_add_u32 s33, s18, s44
	s_addc_u32 s48, s19, s45
	s_cmpk_lg_i32 s44, 0x1400
	s_cselect_b64 s[50:51], -1, 0
	s_and_b64 s[46:47], s[50:51], exec
	s_cselect_b32 s47, s48, s41
	s_cselect_b32 s46, s33, s40
	v_lshl_add_u64 v[202:203], v[206:207], 0, s[44:45]
	s_mov_b32 m0, s62
	v_lshl_add_u64 v[210:211], v[202:203], 0, s[30:31]
	ds_read_b128 v[162:165], v219
	ds_read_b128 v[166:169], v219 offset:1024
	ds_read_b128 v[170:173], v219 offset:2048
	ds_read_b128 v[174:177], v219 offset:3072
	ds_read_b128 v[178:181], v219 offset:4096
	ds_read_b128 v[182:185], v219 offset:5120
	ds_read_b128 v[186:189], v219 offset:6144
	ds_read_b128 v[190:193], v219 offset:7168
	global_load_lds_dwordx4 v[210:211], off
	v_lshl_add_u64 v[210:211], v[208:209], 0, s[44:45]
	v_lshl_add_u64 v[212:213], v[210:211], 0, s[30:31]
	s_mov_b32 m0, s21
	v_lshl_add_u64 v[202:203], v[202:203], 0, s[36:37]
	global_load_lds_dwordx4 v[212:213], off
	s_mov_b32 m0, s22
	s_nor_b64 s[48:49], s[8:9], s[50:51]
	global_load_lds_dwordx4 v[202:203], off
	v_lshl_add_u64 v[202:203], v[210:211], 0, s[36:37]
	s_mov_b32 m0, s23
	s_nop 0
	global_load_lds_dwordx4 v[202:203], off
	s_waitcnt vmcnt(8)
	s_waitcnt lgkmcnt(0)
	s_barrier
	s_setprio 1
	s_waitcnt lgkmcnt(0)
	v_mfma_f32_16x16x32_bf16 v[126:129], v[146:149], v[162:165], v[126:129]
	v_mfma_f32_16x16x32_bf16 v[118:121], v[154:157], v[162:165], v[118:121]
	v_mfma_f32_16x16x32_bf16 v[106:109], v[154:157], v[170:173], v[106:109]
	v_mfma_f32_16x16x32_bf16 v[110:113], v[146:149], v[170:173], v[110:113]
	v_mfma_f32_16x16x32_bf16 v[94:97], v[146:149], v[178:181], v[94:97]
	v_mfma_f32_16x16x32_bf16 v[90:93], v[154:157], v[178:181], v[90:93]
	v_mfma_f32_16x16x32_bf16 v[74:77], v[154:157], v[186:189], v[74:77]
	v_mfma_f32_16x16x32_bf16 v[78:81], v[146:149], v[186:189], v[78:81]
	v_mfma_f32_16x16x32_bf16 v[126:129], v[150:153], v[166:169], v[126:129]
	v_mfma_f32_16x16x32_bf16 v[118:121], v[158:161], v[166:169], v[118:121]
	v_mfma_f32_16x16x32_bf16 v[106:109], v[158:161], v[174:177], v[106:109]
	v_mfma_f32_16x16x32_bf16 v[110:113], v[150:153], v[174:177], v[110:113]
	v_mfma_f32_16x16x32_bf16 v[94:97], v[150:153], v[182:185], v[94:97]
	v_mfma_f32_16x16x32_bf16 v[90:93], v[158:161], v[182:185], v[90:93]
	v_mfma_f32_16x16x32_bf16 v[74:77], v[158:161], v[190:193], v[74:77]
	v_mfma_f32_16x16x32_bf16 v[78:81], v[150:153], v[190:193], v[78:81]
	s_setprio 0
	s_setprio 1
	v_mfma_f32_16x16x32_bf16 v[122:125], v[130:133], v[162:165], v[122:125]
	v_mfma_f32_16x16x32_bf16 v[114:117], v[138:141], v[162:165], v[114:117]
	v_mfma_f32_16x16x32_bf16 v[98:101], v[138:141], v[170:173], v[98:101]
	v_mfma_f32_16x16x32_bf16 v[102:105], v[130:133], v[170:173], v[102:105]
	v_mfma_f32_16x16x32_bf16 v[86:89], v[130:133], v[178:181], v[86:89]
	v_mfma_f32_16x16x32_bf16 v[82:85], v[138:141], v[178:181], v[82:85]
	v_mfma_f32_16x16x32_bf16 v[66:69], v[138:141], v[186:189], v[66:69]
	v_mfma_f32_16x16x32_bf16 v[70:73], v[130:133], v[186:189], v[70:73]
	v_mfma_f32_16x16x32_bf16 v[122:125], v[134:137], v[166:169], v[122:125]
	v_mfma_f32_16x16x32_bf16 v[114:117], v[142:145], v[166:169], v[114:117]
	v_mfma_f32_16x16x32_bf16 v[98:101], v[142:145], v[174:177], v[98:101]
	v_mfma_f32_16x16x32_bf16 v[102:105], v[134:137], v[174:177], v[102:105]
	v_mfma_f32_16x16x32_bf16 v[86:89], v[134:137], v[182:185], v[86:89]
	v_mfma_f32_16x16x32_bf16 v[82:85], v[142:145], v[182:185], v[82:85]
	v_mfma_f32_16x16x32_bf16 v[66:69], v[142:145], v[190:193], v[66:69]
	v_mfma_f32_16x16x32_bf16 v[70:73], v[134:137], v[190:193], v[70:73]
	s_setprio 0
	s_barrier
	ds_read_b128 v[186:189], v219 offset:16384
	ds_read_b128 v[190:193], v219 offset:17408
	ds_read_b128 v[178:181], v219 offset:18432
	ds_read_b128 v[182:185], v219 offset:19456
	ds_read_b128 v[170:173], v219 offset:20480
	ds_read_b128 v[174:177], v219 offset:21504
	ds_read_b128 v[162:165], v219 offset:22528
	ds_read_b128 v[166:169], v219 offset:23552
	s_mov_b64 s[52:53], -1
	s_and_b64 vcc, exec, s[48:49]
	s_cbranch_vccz .LBB0_463
	s_waitcnt vmcnt(2)
	s_mov_b64 s[52:53], 0

.LBB0_465:
	s_waitcnt lgkmcnt(0)
	s_barrier
	s_setprio 1
	s_waitcnt lgkmcnt(0)
	v_mfma_f32_16x16x32_bf16 v[62:65], v[146:149], v[186:189], v[62:65]
	v_mfma_f32_16x16x32_bf16 v[54:57], v[154:157], v[186:189], v[54:57]
	v_mfma_f32_16x16x32_bf16 v[38:41], v[154:157], v[178:181], v[38:41]
	v_mfma_f32_16x16x32_bf16 v[46:49], v[146:149], v[178:181], v[46:49]
	v_mfma_f32_16x16x32_bf16 v[30:33], v[146:149], v[170:173], v[30:33]
	v_mfma_f32_16x16x32_bf16 v[22:25], v[154:157], v[170:173], v[22:25]
	v_mfma_f32_16x16x32_bf16 v[6:9], v[154:157], v[162:165], v[6:9]
	v_mfma_f32_16x16x32_bf16 v[14:17], v[146:149], v[162:165], v[14:17]
	v_mfma_f32_16x16x32_bf16 v[62:65], v[150:153], v[190:193], v[62:65]
	v_mfma_f32_16x16x32_bf16 v[54:57], v[158:161], v[190:193], v[54:57]
	v_mfma_f32_16x16x32_bf16 v[38:41], v[158:161], v[182:185], v[38:41]
	v_mfma_f32_16x16x32_bf16 v[46:49], v[150:153], v[182:185], v[46:49]
	v_mfma_f32_16x16x32_bf16 v[30:33], v[150:153], v[174:177], v[30:33]
	v_mfma_f32_16x16x32_bf16 v[22:25], v[158:161], v[174:177], v[22:25]
	v_mfma_f32_16x16x32_bf16 v[6:9], v[158:161], v[166:169], v[6:9]
	v_mfma_f32_16x16x32_bf16 v[14:17], v[150:153], v[166:169], v[14:17]
	s_setprio 0
	s_setprio 1
	v_mfma_f32_16x16x32_bf16 v[58:61], v[130:133], v[186:189], v[58:61]
	v_mfma_f32_16x16x32_bf16 v[50:53], v[138:141], v[186:189], v[50:53]
	v_mfma_f32_16x16x32_bf16 v[34:37], v[138:141], v[178:181], v[34:37]
	v_mfma_f32_16x16x32_bf16 v[42:45], v[130:133], v[178:181], v[42:45]
	v_mfma_f32_16x16x32_bf16 v[26:29], v[130:133], v[170:173], v[26:29]
	v_mfma_f32_16x16x32_bf16 v[18:21], v[138:141], v[170:173], v[18:21]
	v_mfma_f32_16x16x32_bf16 v[2:5], v[138:141], v[162:165], v[2:5]
	v_mfma_f32_16x16x32_bf16 v[10:13], v[130:133], v[162:165], v[10:13]
	v_mfma_f32_16x16x32_bf16 v[58:61], v[134:137], v[190:193], v[58:61]
	v_mfma_f32_16x16x32_bf16 v[50:53], v[142:145], v[190:193], v[50:53]
	v_mfma_f32_16x16x32_bf16 v[34:37], v[142:145], v[182:185], v[34:37]
	v_mfma_f32_16x16x32_bf16 v[42:45], v[134:137], v[182:185], v[42:45]
	v_mfma_f32_16x16x32_bf16 v[26:29], v[134:137], v[174:177], v[26:29]
	v_mfma_f32_16x16x32_bf16 v[18:21], v[142:145], v[174:177], v[18:21]
	v_mfma_f32_16x16x32_bf16 v[2:5], v[142:145], v[166:169], v[2:5]
	v_mfma_f32_16x16x32_bf16 v[10:13], v[134:137], v[166:169], v[10:13]
	s_setprio 0
	s_barrier
	v_add_u32_e32 v130, 0x18000, v216
	v_add_u32_e32 v134, 0x1c000, v216
	ds_read_b128 v[154:157], v130
	ds_read_b128 v[158:161], v130 offset:1024
	ds_read_b128 v[146:149], v130 offset:2048
	ds_read_b128 v[150:153], v130 offset:3072
	ds_read_b128 v[138:141], v134
	ds_read_b128 v[142:145], v134 offset:1024
	ds_read_b128 v[130:133], v134 offset:2048
	ds_read_b128 v[134:137], v134 offset:3072
	ds_read_b128 v[186:189], v219 offset:32768
	ds_read_b128 v[190:193], v219 offset:33792
	ds_read_b128 v[178:181], v219 offset:34816
	ds_read_b128 v[182:185], v219 offset:35840
	ds_read_b128 v[170:173], v219 offset:36864
	ds_read_b128 v[174:177], v219 offset:37888
	ds_read_b128 v[162:165], v219 offset:38912
	ds_read_b128 v[166:169], v219 offset:39936
	s_mov_b64 s[52:53], -1
	s_and_b64 vcc, exec, s[48:49]
	s_cbranch_vccz .LBB0_467
	s_waitcnt vmcnt(0)
	s_mov_b64 s[52:53], 0

.LBB0_469:
	s_waitcnt lgkmcnt(0)
	s_barrier
	s_setprio 1
	s_waitcnt lgkmcnt(0)
	v_mfma_f32_16x16x32_bf16 v[126:129], v[154:157], v[186:189], v[126:129]
	v_mfma_f32_16x16x32_bf16 v[118:121], v[146:149], v[186:189], v[118:121]
	v_mfma_f32_16x16x32_bf16 v[106:109], v[146:149], v[178:181], v[106:109]
	v_mfma_f32_16x16x32_bf16 v[110:113], v[154:157], v[178:181], v[110:113]
	v_mfma_f32_16x16x32_bf16 v[94:97], v[154:157], v[170:173], v[94:97]
	v_mfma_f32_16x16x32_bf16 v[90:93], v[146:149], v[170:173], v[90:93]
	v_mfma_f32_16x16x32_bf16 v[74:77], v[146:149], v[162:165], v[74:77]
	v_mfma_f32_16x16x32_bf16 v[78:81], v[154:157], v[162:165], v[78:81]
	v_mfma_f32_16x16x32_bf16 v[126:129], v[158:161], v[190:193], v[126:129]
	v_mfma_f32_16x16x32_bf16 v[118:121], v[150:153], v[190:193], v[118:121]
	v_mfma_f32_16x16x32_bf16 v[106:109], v[150:153], v[182:185], v[106:109]
	v_mfma_f32_16x16x32_bf16 v[110:113], v[158:161], v[182:185], v[110:113]
	v_mfma_f32_16x16x32_bf16 v[94:97], v[158:161], v[174:177], v[94:97]
	v_mfma_f32_16x16x32_bf16 v[90:93], v[150:153], v[174:177], v[90:93]
	v_mfma_f32_16x16x32_bf16 v[74:77], v[150:153], v[166:169], v[74:77]
	v_mfma_f32_16x16x32_bf16 v[78:81], v[158:161], v[166:169], v[78:81]
	s_setprio 0
	s_setprio 1
	v_mfma_f32_16x16x32_bf16 v[122:125], v[138:141], v[186:189], v[122:125]
	v_mfma_f32_16x16x32_bf16 v[114:117], v[130:133], v[186:189], v[114:117]
	v_mfma_f32_16x16x32_bf16 v[98:101], v[130:133], v[178:181], v[98:101]
	v_mfma_f32_16x16x32_bf16 v[102:105], v[138:141], v[178:181], v[102:105]
	v_mfma_f32_16x16x32_bf16 v[86:89], v[138:141], v[170:173], v[86:89]
	v_mfma_f32_16x16x32_bf16 v[82:85], v[130:133], v[170:173], v[82:85]
	v_mfma_f32_16x16x32_bf16 v[66:69], v[130:133], v[162:165], v[66:69]
	v_mfma_f32_16x16x32_bf16 v[70:73], v[138:141], v[162:165], v[70:73]
	v_mfma_f32_16x16x32_bf16 v[122:125], v[142:145], v[190:193], v[122:125]
	v_mfma_f32_16x16x32_bf16 v[114:117], v[134:137], v[190:193], v[114:117]
	v_mfma_f32_16x16x32_bf16 v[98:101], v[134:137], v[182:185], v[98:101]
	v_mfma_f32_16x16x32_bf16 v[102:105], v[142:145], v[182:185], v[102:105]
	v_mfma_f32_16x16x32_bf16 v[86:89], v[142:145], v[174:177], v[86:89]
	v_mfma_f32_16x16x32_bf16 v[82:85], v[134:137], v[174:177], v[82:85]
	v_mfma_f32_16x16x32_bf16 v[66:69], v[134:137], v[166:169], v[66:69]
	v_mfma_f32_16x16x32_bf16 v[70:73], v[142:145], v[166:169], v[70:73]
	s_setprio 0
	s_barrier
	ds_read_b128 v[186:189], v219 offset:49152
	ds_read_b128 v[190:193], v219 offset:50176
	ds_read_b128 v[178:181], v219 offset:51200
	ds_read_b128 v[182:185], v219 offset:52224
	ds_read_b128 v[170:173], v219 offset:53248
	ds_read_b128 v[174:177], v219 offset:54272
	ds_read_b128 v[162:165], v219 offset:55296
	ds_read_b128 v[166:169], v219 offset:56320
	s_mov_b64 s[50:51], -1
	s_and_b64 vcc, exec, s[48:49]
	s_cbranch_vccz .LBB0_471
	s_waitcnt vmcnt(0)
	s_mov_b64 s[50:51], 0

.LBB0_789:
	s_ashr_i32 s73, s72, 31
	s_lshl_b64 s[16:17], s[72:73], 19
	s_add_u32 s28, s88, s16
	s_addc_u32 s29, s89, s17
	s_and_b64 s[16:17], s[4:5], exec
	s_cselect_b32 s68, s29, s79
	s_cselect_b32 s69, s28, s78
	s_ashr_i32 s75, s74, 31
	s_lshl_b64 s[16:17], s[74:75], 19
	s_add_u32 s50, s34, s16
	s_addc_u32 s51, s35, s17
	s_and_b64 s[16:17], s[4:5], exec
	s_cselect_b32 s73, s51, s81
	s_cselect_b32 s75, s50, s80
	s_waitcnt vmcnt(8)
	s_waitcnt lgkmcnt(0)
	s_barrier
	s_setprio 1
	s_waitcnt lgkmcnt(0)
	v_mfma_f32_16x16x32_bf16 v[126:129], v[146:149], v[186:189], v[126:129]
	v_mfma_f32_16x16x32_bf16 v[122:125], v[154:157], v[186:189], v[122:125]
	v_mfma_f32_16x16x32_bf16 v[114:117], v[154:157], v[178:181], v[114:117]
	v_mfma_f32_16x16x32_bf16 v[118:121], v[146:149], v[178:181], v[118:121]
	v_mfma_f32_16x16x32_bf16 v[110:113], v[146:149], v[170:173], v[110:113]
	v_mfma_f32_16x16x32_bf16 v[106:109], v[154:157], v[170:173], v[106:109]
	v_mfma_f32_16x16x32_bf16 v[98:101], v[154:157], v[162:165], v[98:101]
	v_mfma_f32_16x16x32_bf16 v[102:105], v[146:149], v[162:165], v[102:105]
	v_mfma_f32_16x16x32_bf16 v[126:129], v[150:153], v[190:193], v[126:129]
	v_mfma_f32_16x16x32_bf16 v[122:125], v[158:161], v[190:193], v[122:125]
	v_mfma_f32_16x16x32_bf16 v[114:117], v[158:161], v[182:185], v[114:117]
	v_mfma_f32_16x16x32_bf16 v[118:121], v[150:153], v[182:185], v[118:121]
	v_mfma_f32_16x16x32_bf16 v[110:113], v[150:153], v[174:177], v[110:113]
	v_mfma_f32_16x16x32_bf16 v[106:109], v[158:161], v[174:177], v[106:109]
	v_mfma_f32_16x16x32_bf16 v[98:101], v[158:161], v[166:169], v[98:101]
	v_mfma_f32_16x16x32_bf16 v[102:105], v[150:153], v[166:169], v[102:105]
	s_setprio 0
	s_setprio 1
	v_mfma_f32_16x16x32_bf16 v[94:97], v[130:133], v[186:189], v[94:97]
	v_mfma_f32_16x16x32_bf16 v[90:93], v[138:141], v[186:189], v[90:93]
	v_mfma_f32_16x16x32_bf16 v[82:85], v[138:141], v[178:181], v[82:85]
	v_mfma_f32_16x16x32_bf16 v[86:89], v[130:133], v[178:181], v[86:89]
	v_mfma_f32_16x16x32_bf16 v[78:81], v[130:133], v[170:173], v[78:81]
	v_mfma_f32_16x16x32_bf16 v[74:77], v[138:141], v[170:173], v[74:77]
	v_mfma_f32_16x16x32_bf16 v[58:61], v[138:141], v[162:165], v[58:61]
	v_mfma_f32_16x16x32_bf16 v[70:73], v[130:133], v[162:165], v[70:73]
	v_mfma_f32_16x16x32_bf16 v[94:97], v[134:137], v[190:193], v[94:97]
	v_mfma_f32_16x16x32_bf16 v[90:93], v[142:145], v[190:193], v[90:93]
	v_mfma_f32_16x16x32_bf16 v[82:85], v[142:145], v[182:185], v[82:85]
	v_mfma_f32_16x16x32_bf16 v[86:89], v[134:137], v[182:185], v[86:89]
	v_mfma_f32_16x16x32_bf16 v[78:81], v[134:137], v[174:177], v[78:81]
	v_mfma_f32_16x16x32_bf16 v[74:77], v[142:145], v[174:177], v[74:77]
	v_mfma_f32_16x16x32_bf16 v[58:61], v[142:145], v[166:169], v[58:61]
	v_mfma_f32_16x16x32_bf16 v[70:73], v[134:137], v[166:169], v[70:73]
	s_setprio 0
	s_barrier
	v_lshl_add_u64 v[224:225], s[80:81], 0, v[196:197]
	s_mov_b32 m0, s14
	v_lshl_add_u64 v[226:227], v[224:225], 0, s[46:47]
	ds_read_b128 v[162:165], v235 offset:16384
	ds_read_b128 v[166:169], v235 offset:17408
	ds_read_b128 v[170:173], v235 offset:18432
	ds_read_b128 v[174:177], v235 offset:19456
	ds_read_b128 v[178:181], v235 offset:20480
	ds_read_b128 v[182:185], v235 offset:21504
	ds_read_b128 v[186:189], v235 offset:22528
	ds_read_b128 v[190:193], v235 offset:23552
	global_load_lds_dwordx4 v[226:227], off
	v_lshl_add_u64 v[226:227], s[80:81], 0, v[200:201]
	s_add_u32 s16, s80, 0x40100
	v_lshl_add_u64 v[238:239], v[226:227], 0, s[46:47]
	s_mov_b32 m0, s15
	s_addc_u32 s17, s81, 0
	global_load_lds_dwordx4 v[238:239], off
	v_lshl_add_u64 v[238:239], s[16:17], 0, v[196:197]
	s_mov_b32 m0, s20
	s_nop 0
	global_load_lds_dwordx4 v[238:239], off
	v_lshl_add_u64 v[238:239], s[16:17], 0, v[200:201]
	s_mov_b32 m0, s21
	s_nop 0
	global_load_lds_dwordx4 v[238:239], off
	s_waitcnt vmcnt(6)
	s_waitcnt lgkmcnt(0)
	s_barrier
	s_setprio 1
	s_waitcnt lgkmcnt(0)
	v_mfma_f32_16x16x32_bf16 v[66:69], v[146:149], v[162:165], v[66:69]
	v_mfma_f32_16x16x32_bf16 v[62:65], v[154:157], v[162:165], v[62:65]
	v_mfma_f32_16x16x32_bf16 v[50:53], v[154:157], v[170:173], v[50:53]
	v_mfma_f32_16x16x32_bf16 v[54:57], v[146:149], v[170:173], v[54:57]
	v_mfma_f32_16x16x32_bf16 v[46:49], v[146:149], v[178:181], v[46:49]
	v_mfma_f32_16x16x32_bf16 v[42:45], v[154:157], v[178:181], v[42:45]
	v_mfma_f32_16x16x32_bf16 v[34:37], v[154:157], v[186:189], v[34:37]
	v_mfma_f32_16x16x32_bf16 v[38:41], v[146:149], v[186:189], v[38:41]
	v_mfma_f32_16x16x32_bf16 v[66:69], v[150:153], v[166:169], v[66:69]
	v_mfma_f32_16x16x32_bf16 v[62:65], v[158:161], v[166:169], v[62:65]
	v_mfma_f32_16x16x32_bf16 v[50:53], v[158:161], v[174:177], v[50:53]
	v_mfma_f32_16x16x32_bf16 v[54:57], v[150:153], v[174:177], v[54:57]
	v_mfma_f32_16x16x32_bf16 v[46:49], v[150:153], v[182:185], v[46:49]
	v_mfma_f32_16x16x32_bf16 v[42:45], v[158:161], v[182:185], v[42:45]
	v_mfma_f32_16x16x32_bf16 v[34:37], v[158:161], v[190:193], v[34:37]
	v_mfma_f32_16x16x32_bf16 v[38:41], v[150:153], v[190:193], v[38:41]
	s_setprio 0
	s_setprio 1
	v_mfma_f32_16x16x32_bf16 v[30:33], v[130:133], v[162:165], v[30:33]
	v_mfma_f32_16x16x32_bf16 v[26:29], v[138:141], v[162:165], v[26:29]
	v_mfma_f32_16x16x32_bf16 v[18:21], v[138:141], v[170:173], v[18:21]
	v_mfma_f32_16x16x32_bf16 v[22:25], v[130:133], v[170:173], v[22:25]
	v_mfma_f32_16x16x32_bf16 v[14:17], v[130:133], v[178:181], v[14:17]
	v_mfma_f32_16x16x32_bf16 v[10:13], v[138:141], v[178:181], v[10:13]
	v_mfma_f32_16x16x32_bf16 v[2:5], v[138:141], v[186:189], v[2:5]
	v_mfma_f32_16x16x32_bf16 v[6:9], v[130:133], v[186:189], v[6:9]
	v_mfma_f32_16x16x32_bf16 v[30:33], v[134:137], v[166:169], v[30:33]
	v_mfma_f32_16x16x32_bf16 v[26:29], v[142:145], v[166:169], v[26:29]
	v_mfma_f32_16x16x32_bf16 v[18:21], v[142:145], v[174:177], v[18:21]
	v_mfma_f32_16x16x32_bf16 v[22:25], v[134:137], v[174:177], v[22:25]
	v_mfma_f32_16x16x32_bf16 v[14:17], v[134:137], v[182:185], v[14:17]
	v_mfma_f32_16x16x32_bf16 v[10:13], v[142:145], v[182:185], v[10:13]
	v_mfma_f32_16x16x32_bf16 v[2:5], v[142:145], v[190:193], v[2:5]
	v_mfma_f32_16x16x32_bf16 v[6:9], v[134:137], v[190:193], v[6:9]
	s_setprio 0
	s_barrier
	s_add_i32 s18, 0, 0x18000
	s_add_i32 s19, 0, 0x1c000
	v_add_u32_e32 v142, s18, v205
	v_add_u32_e32 v158, s19, v205
	ds_read_b128 v[130:133], v142
	ds_read_b128 v[134:137], v142 offset:1024
	ds_read_b128 v[138:141], v142 offset:2048
	ds_read_b128 v[142:145], v142 offset:3072
	ds_read_b128 v[146:149], v158
	ds_read_b128 v[150:153], v158 offset:1024
	ds_read_b128 v[154:157], v158 offset:2048
	ds_read_b128 v[158:161], v158 offset:3072
	s_mov_b32 m0, s77
	v_lshl_add_u64 v[220:221], v[220:221], 0, s[46:47]
	s_add_u32 s16, s78, 0x40100
	ds_read_b128 v[162:165], v235 offset:32768
	ds_read_b128 v[166:169], v235 offset:33792
	ds_read_b128 v[170:173], v235 offset:34816
	ds_read_b128 v[174:177], v235 offset:35840
	ds_read_b128 v[178:181], v235 offset:36864
	ds_read_b128 v[182:185], v235 offset:37888
	ds_read_b128 v[186:189], v235 offset:38912
	ds_read_b128 v[190:193], v235 offset:39936
	global_load_lds_dwordx4 v[220:221], off
	v_lshl_add_u64 v[220:221], v[222:223], 0, s[46:47]
	s_mov_b32 m0, s26
	s_addc_u32 s17, s79, 0
	global_load_lds_dwordx4 v[220:221], off
	v_lshl_add_u64 v[220:221], s[16:17], 0, v[194:195]
	s_mov_b32 m0, s27
	s_nop 0
	global_load_lds_dwordx4 v[220:221], off
	v_lshl_add_u64 v[220:221], s[16:17], 0, v[198:199]
	s_mov_b32 m0, s44
	s_nop 0
	global_load_lds_dwordx4 v[220:221], off
	s_waitcnt vmcnt(8)
	s_waitcnt lgkmcnt(0)
	s_barrier
	s_setprio 1
	s_waitcnt lgkmcnt(0)
	v_mfma_f32_16x16x32_bf16 v[126:129], v[130:133], v[162:165], v[126:129]
	v_mfma_f32_16x16x32_bf16 v[122:125], v[138:141], v[162:165], v[122:125]
	v_mfma_f32_16x16x32_bf16 v[114:117], v[138:141], v[170:173], v[114:117]
	v_mfma_f32_16x16x32_bf16 v[118:121], v[130:133], v[170:173], v[118:121]
	v_mfma_f32_16x16x32_bf16 v[110:113], v[130:133], v[178:181], v[110:113]
	v_mfma_f32_16x16x32_bf16 v[106:109], v[138:141], v[178:181], v[106:109]
	v_mfma_f32_16x16x32_bf16 v[98:101], v[138:141], v[186:189], v[98:101]
	v_mfma_f32_16x16x32_bf16 v[102:105], v[130:133], v[186:189], v[102:105]
	v_mfma_f32_16x16x32_bf16 v[126:129], v[134:137], v[166:169], v[126:129]
	v_mfma_f32_16x16x32_bf16 v[122:125], v[142:145], v[166:169], v[122:125]
	v_mfma_f32_16x16x32_bf16 v[114:117], v[142:145], v[174:177], v[114:117]
	v_mfma_f32_16x16x32_bf16 v[118:121], v[134:137], v[174:177], v[118:121]
	v_mfma_f32_16x16x32_bf16 v[110:113], v[134:137], v[182:185], v[110:113]
	v_mfma_f32_16x16x32_bf16 v[106:109], v[142:145], v[182:185], v[106:109]
	v_mfma_f32_16x16x32_bf16 v[98:101], v[142:145], v[190:193], v[98:101]
	v_mfma_f32_16x16x32_bf16 v[102:105], v[134:137], v[190:193], v[102:105]
	s_setprio 0
	s_setprio 1
	v_mfma_f32_16x16x32_bf16 v[94:97], v[146:149], v[162:165], v[94:97]
	v_mfma_f32_16x16x32_bf16 v[90:93], v[154:157], v[162:165], v[90:93]
	v_mfma_f32_16x16x32_bf16 v[82:85], v[154:157], v[170:173], v[82:85]
	v_mfma_f32_16x16x32_bf16 v[86:89], v[146:149], v[170:173], v[86:89]
	v_mfma_f32_16x16x32_bf16 v[78:81], v[146:149], v[178:181], v[78:81]
	v_mfma_f32_16x16x32_bf16 v[74:77], v[154:157], v[178:181], v[74:77]
	v_mfma_f32_16x16x32_bf16 v[58:61], v[154:157], v[186:189], v[58:61]
	v_mfma_f32_16x16x32_bf16 v[70:73], v[146:149], v[186:189], v[70:73]
	v_mfma_f32_16x16x32_bf16 v[94:97], v[150:153], v[166:169], v[94:97]
	v_mfma_f32_16x16x32_bf16 v[90:93], v[158:161], v[166:169], v[90:93]
	v_mfma_f32_16x16x32_bf16 v[82:85], v[158:161], v[174:177], v[82:85]
	v_mfma_f32_16x16x32_bf16 v[86:89], v[150:153], v[174:177], v[86:89]
	v_mfma_f32_16x16x32_bf16 v[78:81], v[150:153], v[182:185], v[78:81]
	v_mfma_f32_16x16x32_bf16 v[74:77], v[158:161], v[182:185], v[74:77]
	v_mfma_f32_16x16x32_bf16 v[58:61], v[158:161], v[190:193], v[58:61]
	v_mfma_f32_16x16x32_bf16 v[70:73], v[150:153], v[190:193], v[70:73]
	s_setprio 0
	s_barrier
	s_add_i32 s16, s18, s31
	v_lshl_add_u64 v[220:221], v[224:225], 0, s[48:49]
	s_mov_b32 m0, s16
	ds_read_b128 v[162:165], v235 offset:49152
	ds_read_b128 v[166:169], v235 offset:50176
	ds_read_b128 v[170:173], v235 offset:51200
	ds_read_b128 v[174:177], v235 offset:52224
	ds_read_b128 v[178:181], v235 offset:53248
	ds_read_b128 v[182:185], v235 offset:54272
	ds_read_b128 v[186:189], v235 offset:55296
	ds_read_b128 v[190:193], v235 offset:56320
	global_load_lds_dwordx4 v[220:221], off
	s_add_i32 m0, s16, 0x2000
	s_add_u32 s16, s80, 0x40180
	v_lshl_add_u64 v[220:221], v[226:227], 0, s[48:49]
	s_addc_u32 s17, s81, 0
	s_add_i32 s18, s19, s31
	global_load_lds_dwordx4 v[220:221], off
	v_lshl_add_u64 v[220:221], s[16:17], 0, v[196:197]
	s_mov_b32 m0, s18
	s_nop 0
	global_load_lds_dwordx4 v[220:221], off
	v_lshl_add_u64 v[220:221], s[16:17], 0, v[200:201]
	s_add_i32 m0, s18, 0x2000
	s_nop 0
	global_load_lds_dwordx4 v[220:221], off
	s_waitcnt vmcnt(6)
	s_waitcnt lgkmcnt(0)
	s_barrier
	s_setprio 1
	s_waitcnt lgkmcnt(0)
	v_mfma_f32_16x16x32_bf16 v[66:69], v[130:133], v[162:165], v[66:69]
	v_mfma_f32_16x16x32_bf16 v[62:65], v[138:141], v[162:165], v[62:65]
	v_mfma_f32_16x16x32_bf16 v[50:53], v[138:141], v[170:173], v[50:53]
	v_mfma_f32_16x16x32_bf16 v[54:57], v[130:133], v[170:173], v[54:57]
	v_mfma_f32_16x16x32_bf16 v[46:49], v[130:133], v[178:181], v[46:49]
	v_mfma_f32_16x16x32_bf16 v[42:45], v[138:141], v[178:181], v[42:45]
	v_mfma_f32_16x16x32_bf16 v[34:37], v[138:141], v[186:189], v[34:37]
	v_mfma_f32_16x16x32_bf16 v[38:41], v[130:133], v[186:189], v[38:41]
	v_mfma_f32_16x16x32_bf16 v[66:69], v[134:137], v[166:169], v[66:69]
	v_mfma_f32_16x16x32_bf16 v[62:65], v[142:145], v[166:169], v[62:65]
	v_mfma_f32_16x16x32_bf16 v[50:53], v[142:145], v[174:177], v[50:53]
	v_mfma_f32_16x16x32_bf16 v[54:57], v[134:137], v[174:177], v[54:57]
	v_mfma_f32_16x16x32_bf16 v[46:49], v[134:137], v[182:185], v[46:49]
	v_mfma_f32_16x16x32_bf16 v[42:45], v[142:145], v[182:185], v[42:45]
	v_mfma_f32_16x16x32_bf16 v[34:37], v[142:145], v[190:193], v[34:37]
	v_mfma_f32_16x16x32_bf16 v[38:41], v[134:137], v[190:193], v[38:41]
	s_setprio 0
	s_setprio 1
	v_mfma_f32_16x16x32_bf16 v[30:33], v[146:149], v[162:165], v[30:33]
	v_mfma_f32_16x16x32_bf16 v[26:29], v[154:157], v[162:165], v[26:29]
	v_mfma_f32_16x16x32_bf16 v[18:21], v[154:157], v[170:173], v[18:21]
	v_mfma_f32_16x16x32_bf16 v[22:25], v[146:149], v[170:173], v[22:25]
	v_mfma_f32_16x16x32_bf16 v[14:17], v[146:149], v[178:181], v[14:17]
	v_mfma_f32_16x16x32_bf16 v[10:13], v[154:157], v[178:181], v[10:13]
	v_mfma_f32_16x16x32_bf16 v[2:5], v[154:157], v[186:189], v[2:5]
	v_mfma_f32_16x16x32_bf16 v[6:9], v[146:149], v[186:189], v[6:9]
	v_mfma_f32_16x16x32_bf16 v[30:33], v[150:153], v[166:169], v[30:33]
	v_mfma_f32_16x16x32_bf16 v[26:29], v[158:161], v[166:169], v[26:29]
	v_mfma_f32_16x16x32_bf16 v[18:21], v[158:161], v[174:177], v[18:21]
	v_mfma_f32_16x16x32_bf16 v[22:25], v[150:153], v[174:177], v[22:25]
	v_mfma_f32_16x16x32_bf16 v[14:17], v[150:153], v[182:185], v[14:17]
	v_mfma_f32_16x16x32_bf16 v[10:13], v[158:161], v[182:185], v[10:13]
	v_mfma_f32_16x16x32_bf16 v[2:5], v[158:161], v[190:193], v[2:5]
	v_mfma_f32_16x16x32_bf16 v[6:9], v[150:153], v[190:193], v[6:9]
	s_setprio 0
	s_barrier
	s_add_u32 s18, s80, 0x200
	v_lshl_add_u64 v[220:221], s[78:79], 0, v[212:213]
	v_lshl_add_u64 v[222:223], s[78:79], 0, v[214:215]
	s_addc_u32 s19, s81, 0
	s_mov_b32 s92, 0
	s_mov_b64 s[80:81], 0
	s_branch .LBB0_791
.LBB0_790:
	s_waitcnt lgkmcnt(0)
	s_barrier
	s_setprio 1
	s_waitcnt lgkmcnt(0)
	v_mfma_f32_16x16x32_bf16 v[66:69], v[154:157], v[186:189], v[66:69]
	v_mfma_f32_16x16x32_bf16 v[62:65], v[146:149], v[186:189], v[62:65]
	v_mfma_f32_16x16x32_bf16 v[50:53], v[146:149], v[178:181], v[50:53]
	v_mfma_f32_16x16x32_bf16 v[54:57], v[154:157], v[178:181], v[54:57]
	v_mfma_f32_16x16x32_bf16 v[46:49], v[154:157], v[170:173], v[46:49]
	v_mfma_f32_16x16x32_bf16 v[42:45], v[146:149], v[170:173], v[42:45]
	v_mfma_f32_16x16x32_bf16 v[34:37], v[146:149], v[162:165], v[34:37]
	v_mfma_f32_16x16x32_bf16 v[38:41], v[154:157], v[162:165], v[38:41]
	v_mfma_f32_16x16x32_bf16 v[66:69], v[158:161], v[190:193], v[66:69]
	v_mfma_f32_16x16x32_bf16 v[62:65], v[150:153], v[190:193], v[62:65]
	v_mfma_f32_16x16x32_bf16 v[50:53], v[150:153], v[182:185], v[50:53]
	v_mfma_f32_16x16x32_bf16 v[54:57], v[158:161], v[182:185], v[54:57]
	v_mfma_f32_16x16x32_bf16 v[46:49], v[158:161], v[174:177], v[46:49]
	v_mfma_f32_16x16x32_bf16 v[42:45], v[150:153], v[174:177], v[42:45]
	v_mfma_f32_16x16x32_bf16 v[34:37], v[150:153], v[166:169], v[34:37]
	v_mfma_f32_16x16x32_bf16 v[38:41], v[158:161], v[166:169], v[38:41]
	s_setprio 0
	s_setprio 1
	v_mfma_f32_16x16x32_bf16 v[30:33], v[138:141], v[186:189], v[30:33]
	v_mfma_f32_16x16x32_bf16 v[26:29], v[130:133], v[186:189], v[26:29]
	v_mfma_f32_16x16x32_bf16 v[18:21], v[130:133], v[178:181], v[18:21]
	v_mfma_f32_16x16x32_bf16 v[22:25], v[138:141], v[178:181], v[22:25]
	v_mfma_f32_16x16x32_bf16 v[14:17], v[138:141], v[170:173], v[14:17]
	v_mfma_f32_16x16x32_bf16 v[10:13], v[130:133], v[170:173], v[10:13]
	v_mfma_f32_16x16x32_bf16 v[2:5], v[130:133], v[162:165], v[2:5]
	v_mfma_f32_16x16x32_bf16 v[6:9], v[138:141], v[162:165], v[6:9]
	v_mfma_f32_16x16x32_bf16 v[30:33], v[142:145], v[190:193], v[30:33]
	v_mfma_f32_16x16x32_bf16 v[26:29], v[134:137], v[190:193], v[26:29]
	v_mfma_f32_16x16x32_bf16 v[18:21], v[134:137], v[182:185], v[18:21]
	v_mfma_f32_16x16x32_bf16 v[22:25], v[142:145], v[182:185], v[22:25]
	v_mfma_f32_16x16x32_bf16 v[14:17], v[142:145], v[174:177], v[14:17]
	v_mfma_f32_16x16x32_bf16 v[10:13], v[134:137], v[174:177], v[10:13]
	v_mfma_f32_16x16x32_bf16 v[2:5], v[134:137], v[166:169], v[2:5]
	v_mfma_f32_16x16x32_bf16 v[6:9], v[142:145], v[166:169], v[6:9]
	s_setprio 0
	s_barrier
	s_add_i32 s92, s92, 2
	s_add_u32 s80, s80, 0x100
	s_addc_u32 s81, s81, 0
	s_cmp_gt_u32 s92, 13
	s_cbranch_scc1 .LBB0_803
.LBB0_791:
	ds_read_b128 v[146:149], v236
	ds_read_b128 v[150:153], v236 offset:1024
	ds_read_b128 v[154:157], v236 offset:2048
	ds_read_b128 v[158:161], v236 offset:3072
	ds_read_b128 v[130:133], v237
	ds_read_b128 v[134:137], v237 offset:1024
	ds_read_b128 v[138:141], v237 offset:2048
	ds_read_b128 v[142:145], v237 offset:3072
	s_add_u32 s33, s18, s80
	s_addc_u32 s82, s19, s81
	s_cmpk_lg_i32 s80, 0x600
	s_cselect_b64 s[96:97], -1, 0
	s_and_b64 s[16:17], s[96:97], exec
	s_cselect_b32 s83, s82, s73
	s_cselect_b32 s82, s33, s75
	v_lshl_add_u64 v[224:225], v[222:223], 0, s[80:81]
	s_mov_b32 m0, s0
	v_lshl_add_u64 v[226:227], v[224:225], 0, s[48:49]
	ds_read_b128 v[162:165], v235
	ds_read_b128 v[166:169], v235 offset:1024
	ds_read_b128 v[170:173], v235 offset:2048
	ds_read_b128 v[174:177], v235 offset:3072
	ds_read_b128 v[178:181], v235 offset:4096
	ds_read_b128 v[182:185], v235 offset:5120
	ds_read_b128 v[186:189], v235 offset:6144
	ds_read_b128 v[190:193], v235 offset:7168
	global_load_lds_dwordx4 v[226:227], off
	v_lshl_add_u64 v[226:227], v[220:221], 0, s[80:81]
	v_lshl_add_u64 v[238:239], v[226:227], 0, s[48:49]
	s_mov_b32 m0, s7
	v_lshl_add_u64 v[224:225], v[224:225], 0, s[52:53]
	global_load_lds_dwordx4 v[238:239], off
	s_mov_b32 m0, s57
	s_nor_b64 s[94:95], s[4:5], s[96:97]
	global_load_lds_dwordx4 v[224:225], off
	v_lshl_add_u64 v[224:225], v[226:227], 0, s[52:53]
	s_mov_b32 m0, s58
	s_nop 0
	global_load_lds_dwordx4 v[224:225], off
	s_waitcnt vmcnt(8)
	s_waitcnt lgkmcnt(0)
	s_barrier
	s_setprio 1
	s_waitcnt lgkmcnt(0)
	v_mfma_f32_16x16x32_bf16 v[126:129], v[146:149], v[162:165], v[126:129]
	v_mfma_f32_16x16x32_bf16 v[122:125], v[154:157], v[162:165], v[122:125]
	v_mfma_f32_16x16x32_bf16 v[114:117], v[154:157], v[170:173], v[114:117]
	v_mfma_f32_16x16x32_bf16 v[118:121], v[146:149], v[170:173], v[118:121]
	v_mfma_f32_16x16x32_bf16 v[110:113], v[146:149], v[178:181], v[110:113]
	v_mfma_f32_16x16x32_bf16 v[106:109], v[154:157], v[178:181], v[106:109]
	v_mfma_f32_16x16x32_bf16 v[98:101], v[154:157], v[186:189], v[98:101]
	v_mfma_f32_16x16x32_bf16 v[102:105], v[146:149], v[186:189], v[102:105]
	v_mfma_f32_16x16x32_bf16 v[126:129], v[150:153], v[166:169], v[126:129]
	v_mfma_f32_16x16x32_bf16 v[122:125], v[158:161], v[166:169], v[122:125]
	v_mfma_f32_16x16x32_bf16 v[114:117], v[158:161], v[174:177], v[114:117]
	v_mfma_f32_16x16x32_bf16 v[118:121], v[150:153], v[174:177], v[118:121]
	v_mfma_f32_16x16x32_bf16 v[110:113], v[150:153], v[182:185], v[110:113]
	v_mfma_f32_16x16x32_bf16 v[106:109], v[158:161], v[182:185], v[106:109]
	v_mfma_f32_16x16x32_bf16 v[98:101], v[158:161], v[190:193], v[98:101]
	v_mfma_f32_16x16x32_bf16 v[102:105], v[150:153], v[190:193], v[102:105]
	s_setprio 0
	s_setprio 1
	v_mfma_f32_16x16x32_bf16 v[94:97], v[130:133], v[162:165], v[94:97]
	v_mfma_f32_16x16x32_bf16 v[90:93], v[138:141], v[162:165], v[90:93]
	v_mfma_f32_16x16x32_bf16 v[82:85], v[138:141], v[170:173], v[82:85]
	v_mfma_f32_16x16x32_bf16 v[86:89], v[130:133], v[170:173], v[86:89]
	v_mfma_f32_16x16x32_bf16 v[78:81], v[130:133], v[178:181], v[78:81]
	v_mfma_f32_16x16x32_bf16 v[74:77], v[138:141], v[178:181], v[74:77]
	v_mfma_f32_16x16x32_bf16 v[58:61], v[138:141], v[186:189], v[58:61]
	v_mfma_f32_16x16x32_bf16 v[70:73], v[130:133], v[186:189], v[70:73]
	v_mfma_f32_16x16x32_bf16 v[94:97], v[134:137], v[166:169], v[94:97]
	v_mfma_f32_16x16x32_bf16 v[90:93], v[142:145], v[166:169], v[90:93]
	v_mfma_f32_16x16x32_bf16 v[82:85], v[142:145], v[174:177], v[82:85]
	v_mfma_f32_16x16x32_bf16 v[86:89], v[134:137], v[174:177], v[86:89]
	v_mfma_f32_16x16x32_bf16 v[78:81], v[134:137], v[182:185], v[78:81]
	v_mfma_f32_16x16x32_bf16 v[74:77], v[142:145], v[182:185], v[74:77]
	v_mfma_f32_16x16x32_bf16 v[58:61], v[142:145], v[190:193], v[58:61]
	v_mfma_f32_16x16x32_bf16 v[70:73], v[134:137], v[190:193], v[70:73]
	s_setprio 0
	s_barrier
	ds_read_b128 v[186:189], v235 offset:16384
	ds_read_b128 v[190:193], v235 offset:17408
	ds_read_b128 v[178:181], v235 offset:18432
	ds_read_b128 v[182:185], v235 offset:19456
	ds_read_b128 v[170:173], v235 offset:20480
	ds_read_b128 v[174:177], v235 offset:21504
	ds_read_b128 v[162:165], v235 offset:22528
	ds_read_b128 v[166:169], v235 offset:23552
	s_mov_b64 s[16:17], -1
	s_and_b64 vcc, exec, s[94:95]
	s_cbranch_vccz .LBB0_793
	s_waitcnt vmcnt(2)
	s_mov_b64 s[16:17], 0

.LBB0_795:
	s_waitcnt lgkmcnt(0)
	s_barrier
	s_setprio 1
	s_waitcnt lgkmcnt(0)
	v_mfma_f32_16x16x32_bf16 v[66:69], v[146:149], v[186:189], v[66:69]
	v_mfma_f32_16x16x32_bf16 v[62:65], v[154:157], v[186:189], v[62:65]
	v_mfma_f32_16x16x32_bf16 v[50:53], v[154:157], v[178:181], v[50:53]
	v_mfma_f32_16x16x32_bf16 v[54:57], v[146:149], v[178:181], v[54:57]
	v_mfma_f32_16x16x32_bf16 v[46:49], v[146:149], v[170:173], v[46:49]
	v_mfma_f32_16x16x32_bf16 v[42:45], v[154:157], v[170:173], v[42:45]
	v_mfma_f32_16x16x32_bf16 v[34:37], v[154:157], v[162:165], v[34:37]
	v_mfma_f32_16x16x32_bf16 v[38:41], v[146:149], v[162:165], v[38:41]
	v_mfma_f32_16x16x32_bf16 v[66:69], v[150:153], v[190:193], v[66:69]
	v_mfma_f32_16x16x32_bf16 v[62:65], v[158:161], v[190:193], v[62:65]
	v_mfma_f32_16x16x32_bf16 v[50:53], v[158:161], v[182:185], v[50:53]
	v_mfma_f32_16x16x32_bf16 v[54:57], v[150:153], v[182:185], v[54:57]
	v_mfma_f32_16x16x32_bf16 v[46:49], v[150:153], v[174:177], v[46:49]
	v_mfma_f32_16x16x32_bf16 v[42:45], v[158:161], v[174:177], v[42:45]
	v_mfma_f32_16x16x32_bf16 v[34:37], v[158:161], v[166:169], v[34:37]
	v_mfma_f32_16x16x32_bf16 v[38:41], v[150:153], v[166:169], v[38:41]
	s_setprio 0
	s_setprio 1
	v_mfma_f32_16x16x32_bf16 v[30:33], v[130:133], v[186:189], v[30:33]
	v_mfma_f32_16x16x32_bf16 v[26:29], v[138:141], v[186:189], v[26:29]
	v_mfma_f32_16x16x32_bf16 v[18:21], v[138:141], v[178:181], v[18:21]
	v_mfma_f32_16x16x32_bf16 v[22:25], v[130:133], v[178:181], v[22:25]
	v_mfma_f32_16x16x32_bf16 v[14:17], v[130:133], v[170:173], v[14:17]
	v_mfma_f32_16x16x32_bf16 v[10:13], v[138:141], v[170:173], v[10:13]
	v_mfma_f32_16x16x32_bf16 v[2:5], v[138:141], v[162:165], v[2:5]
	v_mfma_f32_16x16x32_bf16 v[6:9], v[130:133], v[162:165], v[6:9]
	v_mfma_f32_16x16x32_bf16 v[30:33], v[134:137], v[190:193], v[30:33]
	v_mfma_f32_16x16x32_bf16 v[26:29], v[142:145], v[190:193], v[26:29]
	v_mfma_f32_16x16x32_bf16 v[18:21], v[142:145], v[182:185], v[18:21]
	v_mfma_f32_16x16x32_bf16 v[22:25], v[134:137], v[182:185], v[22:25]
	v_mfma_f32_16x16x32_bf16 v[14:17], v[134:137], v[174:177], v[14:17]
	v_mfma_f32_16x16x32_bf16 v[10:13], v[142:145], v[174:177], v[10:13]
	v_mfma_f32_16x16x32_bf16 v[2:5], v[142:145], v[166:169], v[2:5]
	v_mfma_f32_16x16x32_bf16 v[6:9], v[134:137], v[166:169], v[6:9]
	s_setprio 0
	s_barrier
	v_add_u32_e32 v130, 0x18000, v202
	v_add_u32_e32 v134, 0x1c000, v202
	ds_read_b128 v[154:157], v130
	ds_read_b128 v[158:161], v130 offset:1024
	ds_read_b128 v[146:149], v130 offset:2048
	ds_read_b128 v[150:153], v130 offset:3072
	ds_read_b128 v[138:141], v134
	ds_read_b128 v[142:145], v134 offset:1024
	ds_read_b128 v[130:133], v134 offset:2048
	ds_read_b128 v[134:137], v134 offset:3072
	ds_read_b128 v[186:189], v235 offset:32768
	ds_read_b128 v[190:193], v235 offset:33792
	ds_read_b128 v[178:181], v235 offset:34816
	ds_read_b128 v[182:185], v235 offset:35840
	ds_read_b128 v[170:173], v235 offset:36864
	ds_read_b128 v[174:177], v235 offset:37888
	ds_read_b128 v[162:165], v235 offset:38912
	ds_read_b128 v[166:169], v235 offset:39936
	s_mov_b64 s[16:17], -1
	s_and_b64 vcc, exec, s[94:95]
	s_cbranch_vccz .LBB0_797
	s_waitcnt vmcnt(0)
	s_mov_b64 s[16:17], 0

.LBB0_799:
	s_waitcnt lgkmcnt(0)
	s_barrier
	s_setprio 1
	s_waitcnt lgkmcnt(0)
	v_mfma_f32_16x16x32_bf16 v[126:129], v[154:157], v[186:189], v[126:129]
	v_mfma_f32_16x16x32_bf16 v[122:125], v[146:149], v[186:189], v[122:125]
	v_mfma_f32_16x16x32_bf16 v[114:117], v[146:149], v[178:181], v[114:117]
	v_mfma_f32_16x16x32_bf16 v[118:121], v[154:157], v[178:181], v[118:121]
	v_mfma_f32_16x16x32_bf16 v[110:113], v[154:157], v[170:173], v[110:113]
	v_mfma_f32_16x16x32_bf16 v[106:109], v[146:149], v[170:173], v[106:109]
	v_mfma_f32_16x16x32_bf16 v[98:101], v[146:149], v[162:165], v[98:101]
	v_mfma_f32_16x16x32_bf16 v[102:105], v[154:157], v[162:165], v[102:105]
	v_mfma_f32_16x16x32_bf16 v[126:129], v[158:161], v[190:193], v[126:129]
	v_mfma_f32_16x16x32_bf16 v[122:125], v[150:153], v[190:193], v[122:125]
	v_mfma_f32_16x16x32_bf16 v[114:117], v[150:153], v[182:185], v[114:117]
	v_mfma_f32_16x16x32_bf16 v[118:121], v[158:161], v[182:185], v[118:121]
	v_mfma_f32_16x16x32_bf16 v[110:113], v[158:161], v[174:177], v[110:113]
	v_mfma_f32_16x16x32_bf16 v[106:109], v[150:153], v[174:177], v[106:109]
	v_mfma_f32_16x16x32_bf16 v[98:101], v[150:153], v[166:169], v[98:101]
	v_mfma_f32_16x16x32_bf16 v[102:105], v[158:161], v[166:169], v[102:105]
	s_setprio 0
	s_setprio 1
	v_mfma_f32_16x16x32_bf16 v[94:97], v[138:141], v[186:189], v[94:97]
	v_mfma_f32_16x16x32_bf16 v[90:93], v[130:133], v[186:189], v[90:93]
	v_mfma_f32_16x16x32_bf16 v[82:85], v[130:133], v[178:181], v[82:85]
	v_mfma_f32_16x16x32_bf16 v[86:89], v[138:141], v[178:181], v[86:89]
	v_mfma_f32_16x16x32_bf16 v[78:81], v[138:141], v[170:173], v[78:81]
	v_mfma_f32_16x16x32_bf16 v[74:77], v[130:133], v[170:173], v[74:77]
	v_mfma_f32_16x16x32_bf16 v[58:61], v[130:133], v[162:165], v[58:61]
	v_mfma_f32_16x16x32_bf16 v[70:73], v[138:141], v[162:165], v[70:73]
	v_mfma_f32_16x16x32_bf16 v[94:97], v[142:145], v[190:193], v[94:97]
	v_mfma_f32_16x16x32_bf16 v[90:93], v[134:137], v[190:193], v[90:93]
	v_mfma_f32_16x16x32_bf16 v[82:85], v[134:137], v[182:185], v[82:85]
	v_mfma_f32_16x16x32_bf16 v[86:89], v[142:145], v[182:185], v[86:89]
	v_mfma_f32_16x16x32_bf16 v[78:81], v[142:145], v[174:177], v[78:81]
	v_mfma_f32_16x16x32_bf16 v[74:77], v[134:137], v[174:177], v[74:77]
	v_mfma_f32_16x16x32_bf16 v[58:61], v[134:137], v[166:169], v[58:61]
	v_mfma_f32_16x16x32_bf16 v[70:73], v[142:145], v[166:169], v[70:73]
	s_setprio 0
	s_barrier
	ds_read_b128 v[186:189], v235 offset:49152
	ds_read_b128 v[190:193], v235 offset:50176
	ds_read_b128 v[178:181], v235 offset:51200
	ds_read_b128 v[182:185], v235 offset:52224
	ds_read_b128 v[170:173], v235 offset:53248
	ds_read_b128 v[174:177], v235 offset:54272
	ds_read_b128 v[162:165], v235 offset:55296
	ds_read_b128 v[166:169], v235 offset:56320
	s_mov_b64 s[16:17], -1
	s_and_b64 vcc, exec, s[94:95]
	s_cbranch_vccz .LBB0_801
	s_waitcnt vmcnt(0)
	s_mov_b64 s[16:17], 0

.LBB0_1537:
	s_ashr_i32 s35, s34, 31
	s_lshl_b64 s[14:15], s[34:35], 18
	s_add_u32 s66, s63, s14
	s_mov_b64 s[0:1], -1
	s_addc_u32 s67, s33, s15
	s_waitcnt vmcnt(8)
	s_waitcnt lgkmcnt(0)
	s_barrier
	s_setprio 1
	s_waitcnt lgkmcnt(0)
	v_mfma_f32_16x16x32_bf16 v[14:17], v[146:149], v[186:189], v[14:17]
	v_mfma_f32_16x16x32_bf16 v[10:13], v[154:157], v[186:189], v[10:13]
	v_mfma_f32_16x16x32_bf16 v[22:25], v[154:157], v[178:181], v[22:25]
	v_mfma_f32_16x16x32_bf16 v[30:33], v[146:149], v[178:181], v[30:33]
	v_mfma_f32_16x16x32_bf16 v[46:49], v[146:149], v[170:173], v[46:49]
	v_mfma_f32_16x16x32_bf16 v[38:41], v[154:157], v[170:173], v[38:41]
	v_mfma_f32_16x16x32_bf16 v[54:57], v[154:157], v[162:165], v[54:57]
	v_mfma_f32_16x16x32_bf16 v[62:65], v[146:149], v[162:165], v[62:65]
	v_mfma_f32_16x16x32_bf16 v[14:17], v[150:153], v[190:193], v[14:17]
	v_mfma_f32_16x16x32_bf16 v[10:13], v[158:161], v[190:193], v[10:13]
	v_mfma_f32_16x16x32_bf16 v[22:25], v[158:161], v[182:185], v[22:25]
	v_mfma_f32_16x16x32_bf16 v[30:33], v[150:153], v[182:185], v[30:33]
	v_mfma_f32_16x16x32_bf16 v[46:49], v[150:153], v[174:177], v[46:49]
	v_mfma_f32_16x16x32_bf16 v[38:41], v[158:161], v[174:177], v[38:41]
	v_mfma_f32_16x16x32_bf16 v[54:57], v[158:161], v[166:169], v[54:57]
	v_mfma_f32_16x16x32_bf16 v[62:65], v[150:153], v[166:169], v[62:65]
	s_setprio 0
	s_setprio 1
	v_mfma_f32_16x16x32_bf16 v[2:5], v[138:141], v[186:189], v[2:5]
	v_mfma_f32_16x16x32_bf16 v[6:9], v[114:117], v[186:189], v[6:9]
	v_mfma_f32_16x16x32_bf16 v[186:189], v[142:145], v[190:193], v[2:5]
	v_mfma_f32_16x16x32_bf16 v[2:5], v[114:117], v[178:181], v[26:29]
	v_mfma_f32_16x16x32_bf16 v[26:29], v[118:121], v[182:185], v[2:5]
	v_mfma_f32_16x16x32_bf16 v[2:5], v[138:141], v[178:181], v[18:21]
	v_mfma_f32_16x16x32_bf16 v[18:21], v[142:145], v[182:185], v[2:5]
	v_mfma_f32_16x16x32_bf16 v[2:5], v[114:117], v[170:173], v[42:45]
	v_mfma_f32_16x16x32_bf16 v[42:45], v[118:121], v[174:177], v[2:5]
	v_mfma_f32_16x16x32_bf16 v[2:5], v[138:141], v[170:173], v[34:37]
	v_mfma_f32_16x16x32_bf16 v[34:37], v[142:145], v[174:177], v[2:5]
	v_mfma_f32_16x16x32_bf16 v[2:5], v[114:117], v[162:165], v[58:61]
	v_mfma_f32_16x16x32_bf16 v[58:61], v[118:121], v[166:169], v[2:5]
	v_mfma_f32_16x16x32_bf16 v[2:5], v[138:141], v[162:165], v[50:53]
	v_mfma_f32_16x16x32_bf16 v[198:201], v[118:121], v[190:193], v[6:9]
	v_mfma_f32_16x16x32_bf16 v[50:53], v[142:145], v[166:169], v[2:5]
	s_setprio 0
	s_barrier
	s_add_i32 s90, 0, 0x10000
	s_add_i32 s37, s90, s62
	s_nop 1
	v_lshl_add_u64 v[2:3], s[56:57], 0, v[220:221]
	s_add_i32 s14, s37, 0x2000
	v_lshl_add_u64 v[4:5], v[2:3], 0, s[48:49]
	s_mov_b32 m0, s37
	s_add_u32 s92, s56, 0x20100
	ds_read_b128 v[6:9], v229 offset:16384
	ds_read_b128 v[162:165], v229 offset:17408
	ds_read_b128 v[166:169], v229 offset:18432
	ds_read_b128 v[170:173], v229 offset:19456
	ds_read_b128 v[174:177], v229 offset:20480
	ds_read_b128 v[178:181], v229 offset:21504
	ds_read_b128 v[182:185], v229 offset:22528
	ds_read_b128 v[190:193], v229 offset:23552
	global_load_lds_dwordx4 v[4:5], off
	v_lshl_add_u64 v[4:5], s[56:57], 0, v[224:225]
	s_addc_u32 s93, s57, 0
	s_add_i32 s91, 0, 0x14000
	v_lshl_add_u64 v[202:203], v[4:5], 0, s[48:49]
	s_mov_b32 m0, s14
	s_add_i32 s15, s91, s62
	global_load_lds_dwordx4 v[202:203], off
	v_lshl_add_u64 v[202:203], s[92:93], 0, v[220:221]
	s_mov_b32 m0, s15
	s_add_i32 s35, s15, 0x2000
	global_load_lds_dwordx4 v[202:203], off
	v_lshl_add_u64 v[202:203], s[92:93], 0, v[224:225]
	s_mov_b32 m0, s35
	s_nop 0
	global_load_lds_dwordx4 v[202:203], off
	s_waitcnt vmcnt(6)
	s_waitcnt lgkmcnt(0)
	s_barrier
	s_setprio 1
	s_waitcnt lgkmcnt(0)
	v_mfma_f32_16x16x32_bf16 v[78:81], v[146:149], v[6:9], v[78:81]
	v_mfma_f32_16x16x32_bf16 v[70:73], v[154:157], v[6:9], v[70:73]
	v_mfma_f32_16x16x32_bf16 v[86:89], v[154:157], v[166:169], v[86:89]
	v_mfma_f32_16x16x32_bf16 v[134:137], v[146:149], v[182:185], v[134:137]
	v_mfma_f32_16x16x32_bf16 v[130:133], v[154:157], v[182:185], v[130:133]
	v_mfma_f32_16x16x32_bf16 v[78:81], v[150:153], v[162:165], v[78:81]
	v_mfma_f32_16x16x32_bf16 v[70:73], v[158:161], v[162:165], v[70:73]
	v_mfma_f32_16x16x32_bf16 v[94:97], v[146:149], v[166:169], v[94:97]
	v_mfma_f32_16x16x32_bf16 v[86:89], v[158:161], v[170:173], v[86:89]
	v_mfma_f32_16x16x32_bf16 v[110:113], v[146:149], v[174:177], v[110:113]
	v_mfma_f32_16x16x32_bf16 v[102:105], v[154:157], v[174:177], v[102:105]
	v_mfma_f32_16x16x32_bf16 v[134:137], v[150:153], v[190:193], v[134:137]
	v_mfma_f32_16x16x32_bf16 v[130:133], v[158:161], v[190:193], v[130:133]
	v_mfma_f32_16x16x32_bf16 v[94:97], v[150:153], v[170:173], v[94:97]
	v_mfma_f32_16x16x32_bf16 v[110:113], v[150:153], v[178:181], v[110:113]
	v_mfma_f32_16x16x32_bf16 v[102:105], v[158:161], v[178:181], v[102:105]
	s_setprio 0
	s_setprio 1
	v_mfma_f32_16x16x32_bf16 v[74:77], v[114:117], v[6:9], v[74:77]
	v_mfma_f32_16x16x32_bf16 v[6:9], v[138:141], v[6:9], v[66:69]
	v_mfma_f32_16x16x32_bf16 v[66:69], v[142:145], v[162:165], v[6:9]
	v_mfma_f32_16x16x32_bf16 v[6:9], v[114:117], v[166:169], v[90:93]
	v_mfma_f32_16x16x32_bf16 v[90:93], v[118:121], v[170:173], v[6:9]
	v_mfma_f32_16x16x32_bf16 v[6:9], v[138:141], v[166:169], v[82:85]
	v_mfma_f32_16x16x32_bf16 v[82:85], v[142:145], v[170:173], v[6:9]
	v_mfma_f32_16x16x32_bf16 v[6:9], v[114:117], v[174:177], v[106:109]
	v_mfma_f32_16x16x32_bf16 v[106:109], v[118:121], v[178:181], v[6:9]
	v_mfma_f32_16x16x32_bf16 v[6:9], v[138:141], v[174:177], v[98:101]
	v_mfma_f32_16x16x32_bf16 v[98:101], v[142:145], v[178:181], v[6:9]
	v_mfma_f32_16x16x32_bf16 v[6:9], v[114:117], v[182:185], v[126:129]
	v_mfma_f32_16x16x32_bf16 v[114:117], v[118:121], v[190:193], v[6:9]
	v_mfma_f32_16x16x32_bf16 v[6:9], v[138:141], v[182:185], v[122:125]
	v_mfma_f32_16x16x32_bf16 v[74:77], v[118:121], v[162:165], v[74:77]
	v_mfma_f32_16x16x32_bf16 v[118:121], v[142:145], v[190:193], v[6:9]
	s_setprio 0
	s_barrier
	s_add_i32 s65, 0, 0x18000
	s_add_i32 s83, 0, 0x1c000
	s_nop 1
	v_add_u32_e32 v6, s65, v228
	v_add_u32_e32 v7, s83, v228
	ds_read_b128 v[122:125], v6
	ds_read_b128 v[126:129], v6 offset:1024
	ds_read_b128 v[138:141], v6 offset:2048
	ds_read_b128 v[142:145], v6 offset:3072
	ds_read_b128 v[146:149], v7
	ds_read_b128 v[150:153], v7 offset:1024
	ds_read_b128 v[154:157], v7 offset:2048
	ds_read_b128 v[158:161], v7 offset:3072
	s_mov_b32 m0, s82
	v_lshl_add_u64 v[8:9], v[194:195], 0, s[48:49]
	s_add_u32 s92, s18, 0x20100
	ds_read_b128 v[162:165], v229 offset:32768
	ds_read_b128 v[166:169], v229 offset:33792
	ds_read_b128 v[170:173], v229 offset:34816
	ds_read_b128 v[174:177], v229 offset:35840
	ds_read_b128 v[178:181], v229 offset:36864
	ds_read_b128 v[182:185], v229 offset:37888
	ds_read_b128 v[190:193], v229 offset:38912
	ds_read_b128 v[202:205], v229 offset:39936
	global_load_lds_dwordx4 v[8:9], off
	v_lshl_add_u64 v[8:9], v[196:197], 0, s[48:49]
	s_mov_b32 m0, s70
	s_addc_u32 s93, s19, 0
	global_load_lds_dwordx4 v[8:9], off
	v_lshl_add_u64 v[8:9], s[92:93], 0, v[218:219]
	s_mov_b32 m0, s71
	s_nop 0
	global_load_lds_dwordx4 v[8:9], off
	v_lshl_add_u64 v[8:9], s[92:93], 0, v[222:223]
	s_mov_b32 m0, s72
	s_nop 0
	global_load_lds_dwordx4 v[8:9], off
	s_waitcnt vmcnt(8)
	s_waitcnt lgkmcnt(0)
	s_barrier
	s_setprio 1
	s_waitcnt lgkmcnt(0)
	v_mfma_f32_16x16x32_bf16 v[14:17], v[122:125], v[162:165], v[14:17]
	v_mfma_f32_16x16x32_bf16 v[8:11], v[138:141], v[162:165], v[10:13]
	v_mfma_f32_16x16x32_bf16 v[30:33], v[122:125], v[170:173], v[30:33]
	v_mfma_f32_16x16x32_bf16 v[22:25], v[138:141], v[170:173], v[22:25]
	v_mfma_f32_16x16x32_bf16 v[46:49], v[122:125], v[178:181], v[46:49]
	v_mfma_f32_16x16x32_bf16 v[38:41], v[138:141], v[178:181], v[38:41]
	v_mfma_f32_16x16x32_bf16 v[62:65], v[122:125], v[190:193], v[62:65]
	v_mfma_f32_16x16x32_bf16 v[54:57], v[138:141], v[190:193], v[54:57]
	v_mfma_f32_16x16x32_bf16 v[14:17], v[126:129], v[166:169], v[14:17]
	v_mfma_f32_16x16x32_bf16 v[10:13], v[142:145], v[166:169], v[8:11]
	v_mfma_f32_16x16x32_bf16 v[30:33], v[126:129], v[174:177], v[30:33]
	v_mfma_f32_16x16x32_bf16 v[22:25], v[142:145], v[174:177], v[22:25]
	v_mfma_f32_16x16x32_bf16 v[46:49], v[126:129], v[182:185], v[46:49]
	v_mfma_f32_16x16x32_bf16 v[38:41], v[142:145], v[182:185], v[38:41]
	v_mfma_f32_16x16x32_bf16 v[62:65], v[126:129], v[202:205], v[62:65]
	v_mfma_f32_16x16x32_bf16 v[54:57], v[142:145], v[202:205], v[54:57]
	s_setprio 0
	s_setprio 1
	v_mfma_f32_16x16x32_bf16 v[198:201], v[146:149], v[162:165], v[198:201]
	v_mfma_f32_16x16x32_bf16 v[162:165], v[154:157], v[162:165], v[186:189]
	v_mfma_f32_16x16x32_bf16 v[26:29], v[146:149], v[170:173], v[26:29]
	v_mfma_f32_16x16x32_bf16 v[18:21], v[154:157], v[170:173], v[18:21]
	v_mfma_f32_16x16x32_bf16 v[42:45], v[146:149], v[178:181], v[42:45]
	v_mfma_f32_16x16x32_bf16 v[34:37], v[154:157], v[178:181], v[34:37]
	v_mfma_f32_16x16x32_bf16 v[58:61], v[146:149], v[190:193], v[58:61]
	v_mfma_f32_16x16x32_bf16 v[50:53], v[154:157], v[190:193], v[50:53]
	v_mfma_f32_16x16x32_bf16 v[198:201], v[150:153], v[166:169], v[198:201]
	v_mfma_f32_16x16x32_bf16 v[162:165], v[158:161], v[166:169], v[162:165]
	v_mfma_f32_16x16x32_bf16 v[26:29], v[150:153], v[174:177], v[26:29]
	v_mfma_f32_16x16x32_bf16 v[18:21], v[158:161], v[174:177], v[18:21]
	v_mfma_f32_16x16x32_bf16 v[42:45], v[150:153], v[182:185], v[42:45]
	v_mfma_f32_16x16x32_bf16 v[34:37], v[158:161], v[182:185], v[34:37]
	v_mfma_f32_16x16x32_bf16 v[58:61], v[150:153], v[202:205], v[58:61]
	v_mfma_f32_16x16x32_bf16 v[50:53], v[158:161], v[202:205], v[50:53]
	s_setprio 0
	s_barrier
	s_add_i32 s93, s65, s62
	s_add_i32 s65, s93, 0x2000
	v_lshl_add_u64 v[8:9], v[2:3], 0, s[20:21]
	s_mov_b32 m0, s93
	s_add_u32 s94, s56, 0x20180
	ds_read_b128 v[166:169], v229 offset:49152
	ds_read_b128 v[170:173], v229 offset:50176
	ds_read_b128 v[174:177], v229 offset:51200
	ds_read_b128 v[178:181], v229 offset:52224
	ds_read_b128 v[182:185], v229 offset:53248
	ds_read_b128 v[186:189], v229 offset:54272
	ds_read_b128 v[190:193], v229 offset:55296
	ds_read_b128 v[202:205], v229 offset:56320
	global_load_lds_dwordx4 v[8:9], off
	v_lshl_add_u64 v[8:9], v[4:5], 0, s[20:21]
	s_mov_b32 m0, s65
	s_addc_u32 s95, s57, 0
	s_add_i32 s83, s83, s62
	global_load_lds_dwordx4 v[8:9], off
	v_lshl_add_u64 v[8:9], s[94:95], 0, v[220:221]
	s_mov_b32 m0, s83
	s_add_i32 s92, s83, 0x2000
	global_load_lds_dwordx4 v[8:9], off
	v_lshl_add_u64 v[8:9], s[94:95], 0, v[224:225]
	s_mov_b32 m0, s92
	s_nop 0
	global_load_lds_dwordx4 v[8:9], off
	s_waitcnt vmcnt(6)
	s_waitcnt lgkmcnt(0)
	s_barrier
	s_setprio 1
	s_waitcnt lgkmcnt(0)
	v_mfma_f32_16x16x32_bf16 v[78:81], v[122:125], v[166:169], v[78:81]
	v_mfma_f32_16x16x32_bf16 v[94:97], v[122:125], v[174:177], v[94:97]
	v_mfma_f32_16x16x32_bf16 v[110:113], v[122:125], v[182:185], v[110:113]
	v_mfma_f32_16x16x32_bf16 v[122:125], v[122:125], v[190:193], v[134:137]
	v_mfma_f32_16x16x32_bf16 v[78:81], v[126:129], v[170:173], v[78:81]
	v_mfma_f32_16x16x32_bf16 v[70:73], v[138:141], v[166:169], v[70:73]
	v_mfma_f32_16x16x32_bf16 v[94:97], v[126:129], v[178:181], v[94:97]
	v_mfma_f32_16x16x32_bf16 v[86:89], v[138:141], v[174:177], v[86:89]
	v_mfma_f32_16x16x32_bf16 v[110:113], v[126:129], v[186:189], v[110:113]
	v_mfma_f32_16x16x32_bf16 v[122:125], v[126:129], v[202:205], v[122:125]
	v_mfma_f32_16x16x32_bf16 v[126:129], v[138:141], v[190:193], v[130:133]
	v_mfma_f32_16x16x32_bf16 v[70:73], v[142:145], v[170:173], v[70:73]
	v_mfma_f32_16x16x32_bf16 v[86:89], v[142:145], v[178:181], v[86:89]
	v_mfma_f32_16x16x32_bf16 v[102:105], v[138:141], v[182:185], v[102:105]
	v_mfma_f32_16x16x32_bf16 v[126:129], v[142:145], v[202:205], v[126:129]
	v_mfma_f32_16x16x32_bf16 v[102:105], v[142:145], v[186:189], v[102:105]
	s_setprio 0
	s_setprio 1
	v_mfma_f32_16x16x32_bf16 v[74:77], v[146:149], v[166:169], v[74:77]
	v_mfma_f32_16x16x32_bf16 v[66:69], v[154:157], v[166:169], v[66:69]
	v_mfma_f32_16x16x32_bf16 v[82:85], v[154:157], v[174:177], v[82:85]
	v_mfma_f32_16x16x32_bf16 v[114:117], v[146:149], v[190:193], v[114:117]
	v_mfma_f32_16x16x32_bf16 v[118:121], v[154:157], v[190:193], v[118:121]
	v_mfma_f32_16x16x32_bf16 v[74:77], v[150:153], v[170:173], v[74:77]
	v_mfma_f32_16x16x32_bf16 v[66:69], v[158:161], v[170:173], v[66:69]
	v_mfma_f32_16x16x32_bf16 v[90:93], v[146:149], v[174:177], v[90:93]
	v_mfma_f32_16x16x32_bf16 v[82:85], v[158:161], v[178:181], v[82:85]
	v_mfma_f32_16x16x32_bf16 v[106:109], v[146:149], v[182:185], v[106:109]
	v_mfma_f32_16x16x32_bf16 v[98:101], v[154:157], v[182:185], v[98:101]
	v_mfma_f32_16x16x32_bf16 v[114:117], v[150:153], v[202:205], v[114:117]
	v_mfma_f32_16x16x32_bf16 v[118:121], v[158:161], v[202:205], v[118:121]
	v_mfma_f32_16x16x32_bf16 v[90:93], v[150:153], v[178:181], v[90:93]
	v_mfma_f32_16x16x32_bf16 v[106:109], v[150:153], v[186:189], v[106:109]
	v_mfma_f32_16x16x32_bf16 v[98:101], v[158:161], v[186:189], v[98:101]
	s_setprio 0
	s_barrier
	v_add_u32_e32 v8, s90, v228
	v_add_u32_e32 v9, s91, v228
	ds_read_b128 v[130:133], v8
	ds_read_b128 v[134:137], v8 offset:1024
	ds_read_b128 v[138:141], v8 offset:2048
	ds_read_b128 v[142:145], v8 offset:3072
	ds_read_b128 v[146:149], v9
	ds_read_b128 v[150:153], v9 offset:1024
	ds_read_b128 v[154:157], v9 offset:2048
	ds_read_b128 v[158:161], v9 offset:3072
	s_mov_b32 m0, s79
	v_lshl_add_u64 v[206:207], v[194:195], 0, s[20:21]
	s_add_u32 s90, s18, 0x20180
	ds_read_b128 v[166:169], v229
	ds_read_b128 v[170:173], v229 offset:1024
	ds_read_b128 v[174:177], v229 offset:2048
	ds_read_b128 v[178:181], v229 offset:3072
	ds_read_b128 v[182:185], v229 offset:4096
	ds_read_b128 v[186:189], v229 offset:5120
	ds_read_b128 v[190:193], v229 offset:6144
	ds_read_b128 v[202:205], v229 offset:7168
	global_load_lds_dwordx4 v[206:207], off
	v_lshl_add_u64 v[206:207], v[196:197], 0, s[20:21]
	s_mov_b32 m0, s51
	s_addc_u32 s91, s19, 0
	global_load_lds_dwordx4 v[206:207], off
	v_lshl_add_u64 v[206:207], s[90:91], 0, v[218:219]
	s_mov_b32 m0, s81
	s_nop 0
	global_load_lds_dwordx4 v[206:207], off
	v_lshl_add_u64 v[206:207], s[90:91], 0, v[222:223]
	s_mov_b32 m0, s80
	s_nop 0
	global_load_lds_dwordx4 v[206:207], off
	s_waitcnt vmcnt(8)
	s_waitcnt lgkmcnt(0)
	s_barrier
	s_setprio 1
	s_waitcnt lgkmcnt(0)
	v_mfma_f32_16x16x32_bf16 v[14:17], v[130:133], v[166:169], v[14:17]
	v_mfma_f32_16x16x32_bf16 v[10:13], v[138:141], v[166:169], v[10:13]
	v_mfma_f32_16x16x32_bf16 v[22:25], v[138:141], v[174:177], v[22:25]
	v_mfma_f32_16x16x32_bf16 v[30:33], v[130:133], v[174:177], v[30:33]
	v_mfma_f32_16x16x32_bf16 v[46:49], v[130:133], v[182:185], v[46:49]
	v_mfma_f32_16x16x32_bf16 v[38:41], v[138:141], v[182:185], v[38:41]
	v_mfma_f32_16x16x32_bf16 v[54:57], v[138:141], v[190:193], v[54:57]
	v_mfma_f32_16x16x32_bf16 v[62:65], v[130:133], v[190:193], v[62:65]
	v_mfma_f32_16x16x32_bf16 v[14:17], v[134:137], v[170:173], v[14:17]
	v_mfma_f32_16x16x32_bf16 v[10:13], v[142:145], v[170:173], v[10:13]
	v_mfma_f32_16x16x32_bf16 v[22:25], v[142:145], v[178:181], v[22:25]
	v_mfma_f32_16x16x32_bf16 v[30:33], v[134:137], v[178:181], v[30:33]
	v_mfma_f32_16x16x32_bf16 v[46:49], v[134:137], v[186:189], v[46:49]
	v_mfma_f32_16x16x32_bf16 v[38:41], v[142:145], v[186:189], v[38:41]
	v_mfma_f32_16x16x32_bf16 v[54:57], v[142:145], v[202:205], v[54:57]
	v_mfma_f32_16x16x32_bf16 v[62:65], v[134:137], v[202:205], v[62:65]
	s_setprio 0
	s_setprio 1
	v_mfma_f32_16x16x32_bf16 v[198:201], v[146:149], v[166:169], v[198:201]
	v_mfma_f32_16x16x32_bf16 v[162:165], v[154:157], v[166:169], v[162:165]
	v_mfma_f32_16x16x32_bf16 v[18:21], v[154:157], v[174:177], v[18:21]
	v_mfma_f32_16x16x32_bf16 v[26:29], v[146:149], v[174:177], v[26:29]
	v_mfma_f32_16x16x32_bf16 v[42:45], v[146:149], v[182:185], v[42:45]
	v_mfma_f32_16x16x32_bf16 v[34:37], v[154:157], v[182:185], v[34:37]
	v_mfma_f32_16x16x32_bf16 v[50:53], v[154:157], v[190:193], v[50:53]
	v_mfma_f32_16x16x32_bf16 v[58:61], v[146:149], v[190:193], v[58:61]
	v_mfma_f32_16x16x32_bf16 v[198:201], v[150:153], v[170:173], v[198:201]
	v_mfma_f32_16x16x32_bf16 v[162:165], v[158:161], v[170:173], v[162:165]
	v_mfma_f32_16x16x32_bf16 v[18:21], v[158:161], v[178:181], v[18:21]
	v_mfma_f32_16x16x32_bf16 v[26:29], v[150:153], v[178:181], v[26:29]
	v_mfma_f32_16x16x32_bf16 v[42:45], v[150:153], v[186:189], v[42:45]
	v_mfma_f32_16x16x32_bf16 v[34:37], v[158:161], v[186:189], v[34:37]
	v_mfma_f32_16x16x32_bf16 v[50:53], v[158:161], v[202:205], v[50:53]
	v_mfma_f32_16x16x32_bf16 v[58:61], v[150:153], v[202:205], v[58:61]
	s_setprio 0
	s_barrier
	s_mov_b32 m0, s37
	v_lshl_add_u64 v[206:207], v[2:3], 0, s[22:23]
	s_add_u32 s90, s56, 0x20200
	ds_read_b128 v[166:169], v229 offset:16384
	ds_read_b128 v[170:173], v229 offset:17408
	ds_read_b128 v[174:177], v229 offset:18432
	ds_read_b128 v[178:181], v229 offset:19456
	ds_read_b128 v[182:185], v229 offset:20480
	ds_read_b128 v[186:189], v229 offset:21504
	ds_read_b128 v[190:193], v229 offset:22528
	ds_read_b128 v[202:205], v229 offset:23552
	global_load_lds_dwordx4 v[206:207], off
	v_lshl_add_u64 v[206:207], v[4:5], 0, s[22:23]
	s_mov_b32 m0, s14
	s_addc_u32 s91, s57, 0
	global_load_lds_dwordx4 v[206:207], off
	v_lshl_add_u64 v[206:207], s[90:91], 0, v[220:221]
	s_mov_b32 m0, s15
	s_nop 0
	global_load_lds_dwordx4 v[206:207], off
	v_lshl_add_u64 v[206:207], s[90:91], 0, v[224:225]
	s_mov_b32 m0, s35
	s_nop 0
	global_load_lds_dwordx4 v[206:207], off
	s_waitcnt vmcnt(6)
	s_waitcnt lgkmcnt(0)
	s_barrier
	s_setprio 1
	s_waitcnt lgkmcnt(0)
	v_mfma_f32_16x16x32_bf16 v[78:81], v[130:133], v[166:169], v[78:81]
	v_mfma_f32_16x16x32_bf16 v[70:73], v[138:141], v[166:169], v[70:73]
	v_mfma_f32_16x16x32_bf16 v[86:89], v[138:141], v[174:177], v[86:89]
	v_mfma_f32_16x16x32_bf16 v[122:125], v[130:133], v[190:193], v[122:125]
	v_mfma_f32_16x16x32_bf16 v[126:129], v[138:141], v[190:193], v[126:129]
	v_mfma_f32_16x16x32_bf16 v[78:81], v[134:137], v[170:173], v[78:81]
	v_mfma_f32_16x16x32_bf16 v[70:73], v[142:145], v[170:173], v[70:73]
	v_mfma_f32_16x16x32_bf16 v[94:97], v[130:133], v[174:177], v[94:97]
	v_mfma_f32_16x16x32_bf16 v[86:89], v[142:145], v[178:181], v[86:89]
	v_mfma_f32_16x16x32_bf16 v[110:113], v[130:133], v[182:185], v[110:113]
	v_mfma_f32_16x16x32_bf16 v[102:105], v[138:141], v[182:185], v[102:105]
	v_mfma_f32_16x16x32_bf16 v[122:125], v[134:137], v[202:205], v[122:125]
	v_mfma_f32_16x16x32_bf16 v[126:129], v[142:145], v[202:205], v[126:129]
	v_mfma_f32_16x16x32_bf16 v[94:97], v[134:137], v[178:181], v[94:97]
	v_mfma_f32_16x16x32_bf16 v[110:113], v[134:137], v[186:189], v[110:113]
	v_mfma_f32_16x16x32_bf16 v[102:105], v[142:145], v[186:189], v[102:105]
	s_setprio 0
	s_setprio 1
	v_mfma_f32_16x16x32_bf16 v[74:77], v[146:149], v[166:169], v[74:77]
	v_mfma_f32_16x16x32_bf16 v[66:69], v[154:157], v[166:169], v[66:69]
	v_mfma_f32_16x16x32_bf16 v[82:85], v[154:157], v[174:177], v[82:85]
	v_mfma_f32_16x16x32_bf16 v[114:117], v[146:149], v[190:193], v[114:117]
	v_mfma_f32_16x16x32_bf16 v[118:121], v[154:157], v[190:193], v[118:121]
	v_mfma_f32_16x16x32_bf16 v[74:77], v[150:153], v[170:173], v[74:77]
	v_mfma_f32_16x16x32_bf16 v[66:69], v[158:161], v[170:173], v[66:69]
	v_mfma_f32_16x16x32_bf16 v[90:93], v[146:149], v[174:177], v[90:93]
	v_mfma_f32_16x16x32_bf16 v[82:85], v[158:161], v[178:181], v[82:85]
	v_mfma_f32_16x16x32_bf16 v[106:109], v[146:149], v[182:185], v[106:109]
	v_mfma_f32_16x16x32_bf16 v[98:101], v[154:157], v[182:185], v[98:101]
	v_mfma_f32_16x16x32_bf16 v[114:117], v[150:153], v[202:205], v[114:117]
	v_mfma_f32_16x16x32_bf16 v[118:121], v[158:161], v[202:205], v[118:121]
	v_mfma_f32_16x16x32_bf16 v[90:93], v[150:153], v[178:181], v[90:93]
	v_mfma_f32_16x16x32_bf16 v[106:109], v[150:153], v[186:189], v[106:109]
	v_mfma_f32_16x16x32_bf16 v[98:101], v[158:161], v[186:189], v[98:101]
	s_setprio 0
	s_barrier
	ds_read_b128 v[130:133], v6
	ds_read_b128 v[134:137], v6 offset:1024
	ds_read_b128 v[138:141], v6 offset:2048
	ds_read_b128 v[142:145], v6 offset:3072
	ds_read_b128 v[146:149], v7
	ds_read_b128 v[150:153], v7 offset:1024
	ds_read_b128 v[154:157], v7 offset:2048
	ds_read_b128 v[158:161], v7 offset:3072
	s_mov_b32 m0, s82
	v_lshl_add_u64 v[206:207], v[194:195], 0, s[22:23]
	s_add_u32 s90, s18, 0x20200
	ds_read_b128 v[166:169], v229 offset:32768
	ds_read_b128 v[170:173], v229 offset:33792
	ds_read_b128 v[174:177], v229 offset:34816
	ds_read_b128 v[178:181], v229 offset:35840
	ds_read_b128 v[182:185], v229 offset:36864
	ds_read_b128 v[186:189], v229 offset:37888
	ds_read_b128 v[190:193], v229 offset:38912
	ds_read_b128 v[202:205], v229 offset:39936
	global_load_lds_dwordx4 v[206:207], off
	v_lshl_add_u64 v[206:207], v[196:197], 0, s[22:23]
	s_mov_b32 m0, s70
	s_addc_u32 s91, s19, 0
	global_load_lds_dwordx4 v[206:207], off
	v_lshl_add_u64 v[206:207], s[90:91], 0, v[218:219]
	s_mov_b32 m0, s71
	s_nop 0
	global_load_lds_dwordx4 v[206:207], off
	v_lshl_add_u64 v[206:207], s[90:91], 0, v[222:223]
	s_mov_b32 m0, s72
	s_nop 0
	global_load_lds_dwordx4 v[206:207], off
	s_waitcnt vmcnt(8)
	s_waitcnt lgkmcnt(0)
	s_barrier
	s_setprio 1
	s_waitcnt lgkmcnt(0)
	v_mfma_f32_16x16x32_bf16 v[14:17], v[130:133], v[166:169], v[14:17]
	v_mfma_f32_16x16x32_bf16 v[10:13], v[138:141], v[166:169], v[10:13]
	v_mfma_f32_16x16x32_bf16 v[22:25], v[138:141], v[174:177], v[22:25]
	v_mfma_f32_16x16x32_bf16 v[30:33], v[130:133], v[174:177], v[30:33]
	v_mfma_f32_16x16x32_bf16 v[46:49], v[130:133], v[182:185], v[46:49]
	v_mfma_f32_16x16x32_bf16 v[38:41], v[138:141], v[182:185], v[38:41]
	v_mfma_f32_16x16x32_bf16 v[54:57], v[138:141], v[190:193], v[54:57]
	v_mfma_f32_16x16x32_bf16 v[62:65], v[130:133], v[190:193], v[62:65]
	v_mfma_f32_16x16x32_bf16 v[14:17], v[134:137], v[170:173], v[14:17]
	v_mfma_f32_16x16x32_bf16 v[10:13], v[142:145], v[170:173], v[10:13]
	v_mfma_f32_16x16x32_bf16 v[22:25], v[142:145], v[178:181], v[22:25]
	v_mfma_f32_16x16x32_bf16 v[30:33], v[134:137], v[178:181], v[30:33]
	v_mfma_f32_16x16x32_bf16 v[46:49], v[134:137], v[186:189], v[46:49]
	v_mfma_f32_16x16x32_bf16 v[38:41], v[142:145], v[186:189], v[38:41]
	v_mfma_f32_16x16x32_bf16 v[54:57], v[142:145], v[202:205], v[54:57]
	v_mfma_f32_16x16x32_bf16 v[62:65], v[134:137], v[202:205], v[62:65]
	s_setprio 0
	s_setprio 1
	v_mfma_f32_16x16x32_bf16 v[198:201], v[146:149], v[166:169], v[198:201]
	v_mfma_f32_16x16x32_bf16 v[162:165], v[154:157], v[166:169], v[162:165]
	v_mfma_f32_16x16x32_bf16 v[18:21], v[154:157], v[174:177], v[18:21]
	v_mfma_f32_16x16x32_bf16 v[26:29], v[146:149], v[174:177], v[26:29]
	v_mfma_f32_16x16x32_bf16 v[42:45], v[146:149], v[182:185], v[42:45]
	v_mfma_f32_16x16x32_bf16 v[34:37], v[154:157], v[182:185], v[34:37]
	v_mfma_f32_16x16x32_bf16 v[50:53], v[154:157], v[190:193], v[50:53]
	v_mfma_f32_16x16x32_bf16 v[58:61], v[146:149], v[190:193], v[58:61]
	v_mfma_f32_16x16x32_bf16 v[198:201], v[150:153], v[170:173], v[198:201]
	v_mfma_f32_16x16x32_bf16 v[162:165], v[158:161], v[170:173], v[162:165]
	v_mfma_f32_16x16x32_bf16 v[18:21], v[158:161], v[178:181], v[18:21]
	v_mfma_f32_16x16x32_bf16 v[26:29], v[150:153], v[178:181], v[26:29]
	v_mfma_f32_16x16x32_bf16 v[42:45], v[150:153], v[186:189], v[42:45]
	v_mfma_f32_16x16x32_bf16 v[34:37], v[158:161], v[186:189], v[34:37]
	v_mfma_f32_16x16x32_bf16 v[50:53], v[158:161], v[202:205], v[50:53]
	v_mfma_f32_16x16x32_bf16 v[58:61], v[150:153], v[202:205], v[58:61]
	s_setprio 0
	s_barrier
	s_mov_b32 m0, s93
	v_lshl_add_u64 v[206:207], v[2:3], 0, s[24:25]
	s_add_u32 s90, s56, 0x20280
	ds_read_b128 v[166:169], v229 offset:49152
	ds_read_b128 v[170:173], v229 offset:50176
	ds_read_b128 v[174:177], v229 offset:51200
	ds_read_b128 v[178:181], v229 offset:52224
	ds_read_b128 v[182:185], v229 offset:53248
	ds_read_b128 v[186:189], v229 offset:54272
	ds_read_b128 v[190:193], v229 offset:55296
	ds_read_b128 v[202:205], v229 offset:56320
	global_load_lds_dwordx4 v[206:207], off
	v_lshl_add_u64 v[206:207], v[4:5], 0, s[24:25]
	s_mov_b32 m0, s65
	s_addc_u32 s91, s57, 0
	global_load_lds_dwordx4 v[206:207], off
	v_lshl_add_u64 v[206:207], s[90:91], 0, v[220:221]
	s_mov_b32 m0, s83
	s_nop 0
	global_load_lds_dwordx4 v[206:207], off
	v_lshl_add_u64 v[206:207], s[90:91], 0, v[224:225]
	s_mov_b32 m0, s92
	s_nop 0
	global_load_lds_dwordx4 v[206:207], off
	s_waitcnt vmcnt(6)
	s_waitcnt lgkmcnt(0)
	s_barrier
	s_setprio 1
	s_waitcnt lgkmcnt(0)
	v_mfma_f32_16x16x32_bf16 v[78:81], v[130:133], v[166:169], v[78:81]
	v_mfma_f32_16x16x32_bf16 v[70:73], v[138:141], v[166:169], v[70:73]
	v_mfma_f32_16x16x32_bf16 v[86:89], v[138:141], v[174:177], v[86:89]
	v_mfma_f32_16x16x32_bf16 v[122:125], v[130:133], v[190:193], v[122:125]
	v_mfma_f32_16x16x32_bf16 v[126:129], v[138:141], v[190:193], v[126:129]
	v_mfma_f32_16x16x32_bf16 v[78:81], v[134:137], v[170:173], v[78:81]
	v_mfma_f32_16x16x32_bf16 v[70:73], v[142:145], v[170:173], v[70:73]
	v_mfma_f32_16x16x32_bf16 v[94:97], v[130:133], v[174:177], v[94:97]
	v_mfma_f32_16x16x32_bf16 v[86:89], v[142:145], v[178:181], v[86:89]
	v_mfma_f32_16x16x32_bf16 v[110:113], v[130:133], v[182:185], v[110:113]
	v_mfma_f32_16x16x32_bf16 v[102:105], v[138:141], v[182:185], v[102:105]
	v_mfma_f32_16x16x32_bf16 v[122:125], v[134:137], v[202:205], v[122:125]
	v_mfma_f32_16x16x32_bf16 v[126:129], v[142:145], v[202:205], v[126:129]
	v_mfma_f32_16x16x32_bf16 v[94:97], v[134:137], v[178:181], v[94:97]
	v_mfma_f32_16x16x32_bf16 v[110:113], v[134:137], v[186:189], v[110:113]
	v_mfma_f32_16x16x32_bf16 v[102:105], v[142:145], v[186:189], v[102:105]
	s_setprio 0
	s_setprio 1
	v_mfma_f32_16x16x32_bf16 v[74:77], v[146:149], v[166:169], v[74:77]
	v_mfma_f32_16x16x32_bf16 v[66:69], v[154:157], v[166:169], v[66:69]
	v_mfma_f32_16x16x32_bf16 v[82:85], v[154:157], v[174:177], v[82:85]
	v_mfma_f32_16x16x32_bf16 v[114:117], v[146:149], v[190:193], v[114:117]
	v_mfma_f32_16x16x32_bf16 v[118:121], v[154:157], v[190:193], v[118:121]
	v_mfma_f32_16x16x32_bf16 v[74:77], v[150:153], v[170:173], v[74:77]
	v_mfma_f32_16x16x32_bf16 v[66:69], v[158:161], v[170:173], v[66:69]
	v_mfma_f32_16x16x32_bf16 v[90:93], v[146:149], v[174:177], v[90:93]
	v_mfma_f32_16x16x32_bf16 v[82:85], v[158:161], v[178:181], v[82:85]
	v_mfma_f32_16x16x32_bf16 v[106:109], v[146:149], v[182:185], v[106:109]
	v_mfma_f32_16x16x32_bf16 v[98:101], v[154:157], v[182:185], v[98:101]
	v_mfma_f32_16x16x32_bf16 v[114:117], v[150:153], v[202:205], v[114:117]
	v_mfma_f32_16x16x32_bf16 v[118:121], v[158:161], v[202:205], v[118:121]
	v_mfma_f32_16x16x32_bf16 v[90:93], v[150:153], v[178:181], v[90:93]
	v_mfma_f32_16x16x32_bf16 v[106:109], v[150:153], v[186:189], v[106:109]
	v_mfma_f32_16x16x32_bf16 v[98:101], v[158:161], v[186:189], v[98:101]
	s_setprio 0
	s_barrier
	ds_read_b128 v[130:133], v8
	ds_read_b128 v[134:137], v8 offset:1024
	ds_read_b128 v[138:141], v8 offset:2048
	ds_read_b128 v[142:145], v8 offset:3072
	ds_read_b128 v[146:149], v9
	ds_read_b128 v[150:153], v9 offset:1024
	ds_read_b128 v[154:157], v9 offset:2048
	ds_read_b128 v[158:161], v9 offset:3072
	s_mov_b32 m0, s79
	v_lshl_add_u64 v[206:207], v[194:195], 0, s[24:25]
	s_add_u32 s90, s18, 0x20280
	ds_read_b128 v[166:169], v229
	ds_read_b128 v[170:173], v229 offset:1024
	ds_read_b128 v[174:177], v229 offset:2048
	ds_read_b128 v[178:181], v229 offset:3072
	ds_read_b128 v[182:185], v229 offset:4096
	ds_read_b128 v[186:189], v229 offset:5120
	ds_read_b128 v[190:193], v229 offset:6144
	ds_read_b128 v[202:205], v229 offset:7168
	global_load_lds_dwordx4 v[206:207], off
	v_lshl_add_u64 v[206:207], v[196:197], 0, s[24:25]
	s_mov_b32 m0, s51
	s_addc_u32 s91, s19, 0
	global_load_lds_dwordx4 v[206:207], off
	v_lshl_add_u64 v[206:207], s[90:91], 0, v[218:219]
	s_mov_b32 m0, s81
	s_nop 0
	global_load_lds_dwordx4 v[206:207], off
	v_lshl_add_u64 v[206:207], s[90:91], 0, v[222:223]
	s_mov_b32 m0, s80
	s_nop 0
	global_load_lds_dwordx4 v[206:207], off
	s_waitcnt vmcnt(8)
	s_waitcnt lgkmcnt(0)
	s_barrier
	s_setprio 1
	s_waitcnt lgkmcnt(0)
	v_mfma_f32_16x16x32_bf16 v[14:17], v[130:133], v[166:169], v[14:17]
	v_mfma_f32_16x16x32_bf16 v[10:13], v[138:141], v[166:169], v[10:13]
	v_mfma_f32_16x16x32_bf16 v[22:25], v[138:141], v[174:177], v[22:25]
	v_mfma_f32_16x16x32_bf16 v[30:33], v[130:133], v[174:177], v[30:33]
	v_mfma_f32_16x16x32_bf16 v[46:49], v[130:133], v[182:185], v[46:49]
	v_mfma_f32_16x16x32_bf16 v[38:41], v[138:141], v[182:185], v[38:41]
	v_mfma_f32_16x16x32_bf16 v[54:57], v[138:141], v[190:193], v[54:57]
	v_mfma_f32_16x16x32_bf16 v[62:65], v[130:133], v[190:193], v[62:65]
	v_mfma_f32_16x16x32_bf16 v[14:17], v[134:137], v[170:173], v[14:17]
	v_mfma_f32_16x16x32_bf16 v[10:13], v[142:145], v[170:173], v[10:13]
	v_mfma_f32_16x16x32_bf16 v[22:25], v[142:145], v[178:181], v[22:25]
	v_mfma_f32_16x16x32_bf16 v[30:33], v[134:137], v[178:181], v[30:33]
	v_mfma_f32_16x16x32_bf16 v[46:49], v[134:137], v[186:189], v[46:49]
	v_mfma_f32_16x16x32_bf16 v[38:41], v[142:145], v[186:189], v[38:41]
	v_mfma_f32_16x16x32_bf16 v[54:57], v[142:145], v[202:205], v[54:57]
	v_mfma_f32_16x16x32_bf16 v[62:65], v[134:137], v[202:205], v[62:65]
	s_setprio 0
	s_setprio 1
	v_mfma_f32_16x16x32_bf16 v[198:201], v[146:149], v[166:169], v[198:201]
	v_mfma_f32_16x16x32_bf16 v[162:165], v[154:157], v[166:169], v[162:165]
	v_mfma_f32_16x16x32_bf16 v[18:21], v[154:157], v[174:177], v[18:21]
	v_mfma_f32_16x16x32_bf16 v[26:29], v[146:149], v[174:177], v[26:29]
	v_mfma_f32_16x16x32_bf16 v[42:45], v[146:149], v[182:185], v[42:45]
	v_mfma_f32_16x16x32_bf16 v[34:37], v[154:157], v[182:185], v[34:37]
	v_mfma_f32_16x16x32_bf16 v[50:53], v[154:157], v[190:193], v[50:53]
	v_mfma_f32_16x16x32_bf16 v[58:61], v[146:149], v[190:193], v[58:61]
	v_mfma_f32_16x16x32_bf16 v[198:201], v[150:153], v[170:173], v[198:201]
	v_mfma_f32_16x16x32_bf16 v[162:165], v[158:161], v[170:173], v[162:165]
	v_mfma_f32_16x16x32_bf16 v[18:21], v[158:161], v[178:181], v[18:21]
	v_mfma_f32_16x16x32_bf16 v[26:29], v[150:153], v[178:181], v[26:29]
	v_mfma_f32_16x16x32_bf16 v[42:45], v[150:153], v[186:189], v[42:45]
	v_mfma_f32_16x16x32_bf16 v[34:37], v[158:161], v[186:189], v[34:37]
	v_mfma_f32_16x16x32_bf16 v[50:53], v[158:161], v[202:205], v[50:53]
	v_mfma_f32_16x16x32_bf16 v[58:61], v[150:153], v[202:205], v[58:61]
	s_setprio 0
	s_barrier
	s_mov_b32 m0, s37
	v_lshl_add_u64 v[206:207], v[2:3], 0, s[26:27]
	s_add_u32 s90, s56, 0x20300
	ds_read_b128 v[166:169], v229 offset:16384
	ds_read_b128 v[170:173], v229 offset:17408
	ds_read_b128 v[174:177], v229 offset:18432
	ds_read_b128 v[178:181], v229 offset:19456
	ds_read_b128 v[182:185], v229 offset:20480
	ds_read_b128 v[186:189], v229 offset:21504
	ds_read_b128 v[190:193], v229 offset:22528
	ds_read_b128 v[202:205], v229 offset:23552
	global_load_lds_dwordx4 v[206:207], off
	v_lshl_add_u64 v[206:207], v[4:5], 0, s[26:27]
	s_mov_b32 m0, s14
	s_addc_u32 s91, s57, 0
	global_load_lds_dwordx4 v[206:207], off
	v_lshl_add_u64 v[206:207], s[90:91], 0, v[220:221]
	s_mov_b32 m0, s15
	s_nop 0
	global_load_lds_dwordx4 v[206:207], off
	v_lshl_add_u64 v[206:207], s[90:91], 0, v[224:225]
	s_mov_b32 m0, s35
	s_nop 0
	global_load_lds_dwordx4 v[206:207], off
	s_waitcnt vmcnt(6)
	s_waitcnt lgkmcnt(0)
	s_barrier
	s_setprio 1
	s_waitcnt lgkmcnt(0)
	v_mfma_f32_16x16x32_bf16 v[78:81], v[130:133], v[166:169], v[78:81]
	v_mfma_f32_16x16x32_bf16 v[70:73], v[138:141], v[166:169], v[70:73]
	v_mfma_f32_16x16x32_bf16 v[86:89], v[138:141], v[174:177], v[86:89]
	v_mfma_f32_16x16x32_bf16 v[122:125], v[130:133], v[190:193], v[122:125]
	v_mfma_f32_16x16x32_bf16 v[126:129], v[138:141], v[190:193], v[126:129]
	v_mfma_f32_16x16x32_bf16 v[78:81], v[134:137], v[170:173], v[78:81]
	v_mfma_f32_16x16x32_bf16 v[70:73], v[142:145], v[170:173], v[70:73]
	v_mfma_f32_16x16x32_bf16 v[94:97], v[130:133], v[174:177], v[94:97]
	v_mfma_f32_16x16x32_bf16 v[86:89], v[142:145], v[178:181], v[86:89]
	v_mfma_f32_16x16x32_bf16 v[110:113], v[130:133], v[182:185], v[110:113]
	v_mfma_f32_16x16x32_bf16 v[102:105], v[138:141], v[182:185], v[102:105]
	v_mfma_f32_16x16x32_bf16 v[122:125], v[134:137], v[202:205], v[122:125]
	v_mfma_f32_16x16x32_bf16 v[126:129], v[142:145], v[202:205], v[126:129]
	v_mfma_f32_16x16x32_bf16 v[94:97], v[134:137], v[178:181], v[94:97]
	v_mfma_f32_16x16x32_bf16 v[110:113], v[134:137], v[186:189], v[110:113]
	v_mfma_f32_16x16x32_bf16 v[102:105], v[142:145], v[186:189], v[102:105]
	s_setprio 0
	s_setprio 1
	v_mfma_f32_16x16x32_bf16 v[114:117], v[146:149], v[190:193], v[114:117]
	v_mfma_f32_16x16x32_bf16 v[74:77], v[146:149], v[166:169], v[74:77]
	v_mfma_f32_16x16x32_bf16 v[66:69], v[154:157], v[166:169], v[66:69]
	v_mfma_f32_16x16x32_bf16 v[82:85], v[154:157], v[174:177], v[82:85]
	v_mfma_f32_16x16x32_bf16 v[130:133], v[150:153], v[202:205], v[114:117]
	v_mfma_f32_16x16x32_bf16 v[114:117], v[154:157], v[190:193], v[118:121]
	v_mfma_f32_16x16x32_bf16 v[74:77], v[150:153], v[170:173], v[74:77]
	v_mfma_f32_16x16x32_bf16 v[66:69], v[158:161], v[170:173], v[66:69]
	v_mfma_f32_16x16x32_bf16 v[90:93], v[146:149], v[174:177], v[90:93]
	v_mfma_f32_16x16x32_bf16 v[82:85], v[158:161], v[178:181], v[82:85]
	v_mfma_f32_16x16x32_bf16 v[106:109], v[146:149], v[182:185], v[106:109]
	v_mfma_f32_16x16x32_bf16 v[98:101], v[154:157], v[182:185], v[98:101]
	v_mfma_f32_16x16x32_bf16 v[134:137], v[158:161], v[202:205], v[114:117]
	v_mfma_f32_16x16x32_bf16 v[90:93], v[150:153], v[178:181], v[90:93]
	v_mfma_f32_16x16x32_bf16 v[106:109], v[150:153], v[186:189], v[106:109]
	v_mfma_f32_16x16x32_bf16 v[98:101], v[158:161], v[186:189], v[98:101]
	s_setprio 0
	s_barrier
	ds_read_b128 v[114:117], v6
	ds_read_b128 v[118:121], v6 offset:1024
	ds_read_b128 v[138:141], v6 offset:2048
	ds_read_b128 v[142:145], v6 offset:3072
	ds_read_b128 v[154:157], v7
	ds_read_b128 v[158:161], v7 offset:1024
	ds_read_b128 v[166:169], v7 offset:2048
	ds_read_b128 v[170:173], v7 offset:3072
	s_mov_b32 m0, s82
	v_lshl_add_u64 v[6:7], v[194:195], 0, s[26:27]
	s_add_u32 s14, s18, 0x20300
	ds_read_b128 v[146:149], v229 offset:32768
	ds_read_b128 v[150:153], v229 offset:33792
	ds_read_b128 v[174:177], v229 offset:34816
	ds_read_b128 v[178:181], v229 offset:35840
	ds_read_b128 v[182:185], v229 offset:36864
	ds_read_b128 v[186:189], v229 offset:37888
	ds_read_b128 v[190:193], v229 offset:38912
	ds_read_b128 v[202:205], v229 offset:39936
	global_load_lds_dwordx4 v[6:7], off
	v_lshl_add_u64 v[6:7], v[196:197], 0, s[26:27]
	s_mov_b32 m0, s70
	s_addc_u32 s15, s19, 0
	global_load_lds_dwordx4 v[6:7], off
	v_lshl_add_u64 v[6:7], s[14:15], 0, v[218:219]
	s_mov_b32 m0, s71
	s_nop 0
	global_load_lds_dwordx4 v[6:7], off
	v_lshl_add_u64 v[6:7], s[14:15], 0, v[222:223]
	s_mov_b32 m0, s72
	s_nop 0
	global_load_lds_dwordx4 v[6:7], off
	s_waitcnt vmcnt(8)
	s_waitcnt lgkmcnt(0)
	s_barrier
	s_setprio 1
	s_waitcnt lgkmcnt(0)
	v_mfma_f32_16x16x32_bf16 v[14:17], v[114:117], v[146:149], v[14:17]
	v_mfma_f32_16x16x32_bf16 v[10:13], v[138:141], v[146:149], v[10:13]
	v_mfma_f32_16x16x32_bf16 v[22:25], v[138:141], v[174:177], v[22:25]
	v_mfma_f32_16x16x32_bf16 v[30:33], v[114:117], v[174:177], v[30:33]
	v_mfma_f32_16x16x32_bf16 v[46:49], v[114:117], v[182:185], v[46:49]
	v_mfma_f32_16x16x32_bf16 v[38:41], v[138:141], v[182:185], v[38:41]
	v_mfma_f32_16x16x32_bf16 v[54:57], v[138:141], v[190:193], v[54:57]
	v_mfma_f32_16x16x32_bf16 v[62:65], v[114:117], v[190:193], v[62:65]
	v_mfma_f32_16x16x32_bf16 v[14:17], v[118:121], v[150:153], v[14:17]
	v_mfma_f32_16x16x32_bf16 v[10:13], v[142:145], v[150:153], v[10:13]
	v_mfma_f32_16x16x32_bf16 v[22:25], v[142:145], v[178:181], v[22:25]
	v_mfma_f32_16x16x32_bf16 v[30:33], v[118:121], v[178:181], v[30:33]
	v_mfma_f32_16x16x32_bf16 v[46:49], v[118:121], v[186:189], v[46:49]
	v_mfma_f32_16x16x32_bf16 v[38:41], v[142:145], v[186:189], v[38:41]
	v_mfma_f32_16x16x32_bf16 v[54:57], v[142:145], v[202:205], v[54:57]
	v_mfma_f32_16x16x32_bf16 v[62:65], v[118:121], v[202:205], v[62:65]
	s_setprio 0
	s_setprio 1
	v_mfma_f32_16x16x32_bf16 v[18:21], v[166:169], v[174:177], v[18:21]
	v_mfma_f32_16x16x32_bf16 v[214:217], v[170:173], v[178:181], v[18:21]
	v_mfma_f32_16x16x32_bf16 v[18:21], v[154:157], v[182:185], v[42:45]
	v_mfma_f32_16x16x32_bf16 v[234:237], v[158:161], v[186:189], v[18:21]
	v_mfma_f32_16x16x32_bf16 v[18:21], v[166:169], v[182:185], v[34:37]
	v_mfma_f32_16x16x32_bf16 v[186:189], v[170:173], v[186:189], v[18:21]
	v_mfma_f32_16x16x32_bf16 v[18:21], v[154:157], v[190:193], v[58:61]
	v_mfma_f32_16x16x32_bf16 v[198:201], v[154:157], v[146:149], v[198:201]
	v_mfma_f32_16x16x32_bf16 v[146:149], v[166:169], v[146:149], v[162:165]
	v_mfma_f32_16x16x32_bf16 v[26:29], v[154:157], v[174:177], v[26:29]
	v_mfma_f32_16x16x32_bf16 v[238:241], v[158:161], v[202:205], v[18:21]
	v_mfma_f32_16x16x32_bf16 v[18:21], v[166:169], v[190:193], v[50:53]
	v_mfma_f32_16x16x32_bf16 v[198:201], v[158:161], v[150:153], v[198:201]
	v_mfma_f32_16x16x32_bf16 v[206:209], v[170:173], v[150:153], v[146:149]
	v_mfma_f32_16x16x32_bf16 v[210:213], v[158:161], v[178:181], v[26:29]
	v_mfma_f32_16x16x32_bf16 v[190:193], v[170:173], v[202:205], v[18:21]
	s_setprio 0
	s_barrier
	s_mov_b32 m0, s93
	v_lshl_add_u64 v[2:3], v[2:3], 0, s[30:31]
	s_add_u32 s14, s56, 0x20380
	ds_read_b128 v[146:149], v229 offset:49152
	ds_read_b128 v[150:153], v229 offset:50176
	ds_read_b128 v[162:165], v229 offset:51200
	ds_read_b128 v[174:177], v229 offset:52224
	ds_read_b128 v[178:181], v229 offset:53248
	ds_read_b128 v[182:185], v229 offset:54272
	ds_read_b128 v[202:205], v229 offset:55296
	ds_read_b128 v[242:245], v229 offset:56320
	global_load_lds_dwordx4 v[2:3], off
	v_lshl_add_u64 v[2:3], v[4:5], 0, s[30:31]
	s_mov_b32 m0, s65
	s_addc_u32 s15, s57, 0
	global_load_lds_dwordx4 v[2:3], off
	v_lshl_add_u64 v[2:3], s[14:15], 0, v[220:221]
	s_mov_b32 m0, s83
	s_nop 0
	global_load_lds_dwordx4 v[2:3], off
	v_lshl_add_u64 v[2:3], s[14:15], 0, v[224:225]
	s_mov_b32 m0, s92
	s_nop 0
	global_load_lds_dwordx4 v[2:3], off
	s_waitcnt vmcnt(6)
	s_waitcnt lgkmcnt(0)
	s_barrier
	s_setprio 1
	s_waitcnt lgkmcnt(0)
	v_mfma_f32_16x16x32_bf16 v[2:5], v[114:117], v[146:149], v[78:81]
	v_mfma_f32_16x16x32_bf16 v[18:21], v[118:121], v[150:153], v[2:5]
	v_mfma_f32_16x16x32_bf16 v[2:5], v[138:141], v[146:149], v[70:73]
	v_mfma_f32_16x16x32_bf16 v[26:29], v[142:145], v[150:153], v[2:5]
	v_mfma_f32_16x16x32_bf16 v[2:5], v[114:117], v[162:165], v[94:97]
	v_mfma_f32_16x16x32_bf16 v[34:37], v[118:121], v[174:177], v[2:5]
	v_mfma_f32_16x16x32_bf16 v[2:5], v[138:141], v[162:165], v[86:89]
	v_mfma_f32_16x16x32_bf16 v[42:45], v[142:145], v[174:177], v[2:5]
	v_mfma_f32_16x16x32_bf16 v[2:5], v[114:117], v[178:181], v[110:113]
	v_mfma_f32_16x16x32_bf16 v[50:53], v[118:121], v[182:185], v[2:5]
	v_mfma_f32_16x16x32_bf16 v[2:5], v[138:141], v[178:181], v[102:105]
	v_mfma_f32_16x16x32_bf16 v[58:61], v[142:145], v[182:185], v[2:5]
	v_mfma_f32_16x16x32_bf16 v[2:5], v[114:117], v[202:205], v[122:125]
	v_mfma_f32_16x16x32_bf16 v[114:117], v[118:121], v[242:245], v[2:5]
	v_mfma_f32_16x16x32_bf16 v[2:5], v[138:141], v[202:205], v[126:129]
	v_mfma_f32_16x16x32_bf16 v[118:121], v[142:145], v[242:245], v[2:5]
	s_setprio 0
	s_setprio 1
	v_mfma_f32_16x16x32_bf16 v[2:5], v[154:157], v[146:149], v[74:77]
	v_mfma_f32_16x16x32_bf16 v[122:125], v[158:161], v[150:153], v[2:5]
	v_mfma_f32_16x16x32_bf16 v[2:5], v[166:169], v[146:149], v[66:69]
	v_mfma_f32_16x16x32_bf16 v[126:129], v[170:173], v[150:153], v[2:5]
	v_mfma_f32_16x16x32_bf16 v[2:5], v[154:157], v[162:165], v[90:93]
	v_mfma_f32_16x16x32_bf16 v[138:141], v[158:161], v[174:177], v[2:5]
	v_mfma_f32_16x16x32_bf16 v[2:5], v[166:169], v[162:165], v[82:85]
	v_mfma_f32_16x16x32_bf16 v[142:145], v[170:173], v[174:177], v[2:5]
	v_mfma_f32_16x16x32_bf16 v[2:5], v[154:157], v[178:181], v[106:109]
	v_mfma_f32_16x16x32_bf16 v[146:149], v[158:161], v[182:185], v[2:5]
	v_mfma_f32_16x16x32_bf16 v[2:5], v[166:169], v[178:181], v[98:101]
	v_mfma_f32_16x16x32_bf16 v[150:153], v[170:173], v[182:185], v[2:5]
	v_mfma_f32_16x16x32_bf16 v[2:5], v[154:157], v[202:205], v[130:133]
	v_mfma_f32_16x16x32_bf16 v[154:157], v[158:161], v[242:245], v[2:5]
	v_mfma_f32_16x16x32_bf16 v[2:5], v[166:169], v[202:205], v[134:137]
	v_mfma_f32_16x16x32_bf16 v[158:161], v[170:173], v[242:245], v[2:5]
	s_setprio 0
	s_barrier
	ds_read_b128 v[130:133], v8
	ds_read_b128 v[134:137], v8 offset:1024
	ds_read_b128 v[178:181], v8 offset:2048
	ds_read_b128 v[182:185], v8 offset:3072
	ds_read_b128 v[162:165], v9
	ds_read_b128 v[166:169], v9 offset:1024
	ds_read_b128 v[170:173], v9 offset:2048
	ds_read_b128 v[174:177], v9 offset:3072
	s_mov_b32 m0, s79
	v_lshl_add_u64 v[2:3], v[194:195], 0, s[30:31]
	s_add_u32 s14, s18, 0x20380
	ds_read_b128 v[66:69], v229
	ds_read_b128 v[70:73], v229 offset:1024
	ds_read_b128 v[74:77], v229 offset:2048
	ds_read_b128 v[78:81], v229 offset:3072
	ds_read_b128 v[82:85], v229 offset:4096
	ds_read_b128 v[86:89], v229 offset:5120
	ds_read_b128 v[90:93], v229 offset:6144
	ds_read_b128 v[94:97], v229 offset:7168
	global_load_lds_dwordx4 v[2:3], off
	v_lshl_add_u64 v[2:3], v[196:197], 0, s[30:31]
	s_mov_b32 m0, s51
	s_addc_u32 s15, s19, 0
	global_load_lds_dwordx4 v[2:3], off
	v_lshl_add_u64 v[2:3], s[14:15], 0, v[218:219]
	s_mov_b32 m0, s81
	s_nop 0
	global_load_lds_dwordx4 v[2:3], off
	v_lshl_add_u64 v[2:3], s[14:15], 0, v[222:223]
	s_mov_b32 m0, s80
	s_nop 0
	global_load_lds_dwordx4 v[2:3], off
	s_waitcnt vmcnt(8)
	s_waitcnt lgkmcnt(0)
	s_barrier
	s_setprio 1
	s_waitcnt lgkmcnt(0)
	v_mfma_f32_16x16x32_bf16 v[2:5], v[130:133], v[66:69], v[14:17]
	v_mfma_f32_16x16x32_bf16 v[6:9], v[178:181], v[66:69], v[10:13]
	v_mfma_f32_16x16x32_bf16 v[10:13], v[130:133], v[74:77], v[30:33]
	v_mfma_f32_16x16x32_bf16 v[14:17], v[178:181], v[74:77], v[22:25]
	v_mfma_f32_16x16x32_bf16 v[22:25], v[130:133], v[82:85], v[46:49]
	v_mfma_f32_16x16x32_bf16 v[30:33], v[178:181], v[82:85], v[38:41]
	v_mfma_f32_16x16x32_bf16 v[38:41], v[130:133], v[90:93], v[62:65]
	v_mfma_f32_16x16x32_bf16 v[46:49], v[178:181], v[90:93], v[54:57]
	v_mfma_f32_16x16x32_bf16 v[2:5], v[134:137], v[70:73], v[2:5]
	v_mfma_f32_16x16x32_bf16 v[6:9], v[182:185], v[70:73], v[6:9]
	v_mfma_f32_16x16x32_bf16 v[10:13], v[134:137], v[78:81], v[10:13]
	v_mfma_f32_16x16x32_bf16 v[14:17], v[182:185], v[78:81], v[14:17]
	v_mfma_f32_16x16x32_bf16 v[22:25], v[134:137], v[86:89], v[22:25]
	v_mfma_f32_16x16x32_bf16 v[30:33], v[182:185], v[86:89], v[30:33]
	v_mfma_f32_16x16x32_bf16 v[38:41], v[134:137], v[94:97], v[38:41]
	v_mfma_f32_16x16x32_bf16 v[46:49], v[182:185], v[94:97], v[46:49]
	s_setprio 0
	s_setprio 1
	v_mfma_f32_16x16x32_bf16 v[54:57], v[162:165], v[66:69], v[198:201]
	v_mfma_f32_16x16x32_bf16 v[62:65], v[170:173], v[66:69], v[206:209]
	v_mfma_f32_16x16x32_bf16 v[54:57], v[166:169], v[70:73], v[54:57]
	v_mfma_f32_16x16x32_bf16 v[62:65], v[174:177], v[70:73], v[62:65]
	v_mfma_f32_16x16x32_bf16 v[66:69], v[162:165], v[74:77], v[210:213]
	v_mfma_f32_16x16x32_bf16 v[70:73], v[170:173], v[74:77], v[214:217]
	v_mfma_f32_16x16x32_bf16 v[66:69], v[166:169], v[78:81], v[66:69]
	v_mfma_f32_16x16x32_bf16 v[70:73], v[174:177], v[78:81], v[70:73]
	v_mfma_f32_16x16x32_bf16 v[74:77], v[162:165], v[82:85], v[234:237]
	v_mfma_f32_16x16x32_bf16 v[78:81], v[170:173], v[82:85], v[186:189]
	v_mfma_f32_16x16x32_bf16 v[74:77], v[166:169], v[86:89], v[74:77]
	v_mfma_f32_16x16x32_bf16 v[78:81], v[174:177], v[86:89], v[78:81]
	v_mfma_f32_16x16x32_bf16 v[82:85], v[162:165], v[90:93], v[238:241]
	v_mfma_f32_16x16x32_bf16 v[86:89], v[170:173], v[90:93], v[190:193]
	v_mfma_f32_16x16x32_bf16 v[82:85], v[166:169], v[94:97], v[82:85]
	v_mfma_f32_16x16x32_bf16 v[86:89], v[174:177], v[94:97], v[86:89]
	s_setprio 0
	s_barrier
	ds_read_b128 v[210:213], v229 offset:16384
	ds_read_b128 v[214:217], v229 offset:17408
	ds_read_b128 v[202:205], v229 offset:18432
	ds_read_b128 v[206:209], v229 offset:19456
	ds_read_b128 v[194:197], v229 offset:20480
	ds_read_b128 v[198:201], v229 offset:21504
	ds_read_b128 v[186:189], v229 offset:22528
	ds_read_b128 v[190:193], v229 offset:23552
	s_and_b64 vcc, exec, s[28:29]
	s_cbranch_vccnz .LBB0_1539
	s_waitcnt vmcnt(2)
	s_mov_b64 s[0:1], 0

.LBB0_1688:
	s_waitcnt lgkmcnt(0)
	s_barrier
	s_setprio 1
	s_waitcnt lgkmcnt(0)
	v_mfma_f32_16x16x32_bf16 v[6:9], v[158:161], v[186:189], v[6:9]
	v_mfma_f32_16x16x32_bf16 v[10:13], v[166:169], v[186:189], v[10:13]
	v_mfma_f32_16x16x32_bf16 v[18:21], v[166:169], v[178:181], v[18:21]
	v_mfma_f32_16x16x32_bf16 v[14:17], v[158:161], v[178:181], v[14:17]
	v_mfma_f32_16x16x32_bf16 v[22:25], v[158:161], v[106:109], v[22:25]
	v_mfma_f32_16x16x32_bf16 v[26:29], v[166:169], v[106:109], v[26:29]
	v_mfma_f32_16x16x32_bf16 v[34:37], v[166:169], v[98:101], v[34:37]
	v_mfma_f32_16x16x32_bf16 v[30:33], v[158:161], v[98:101], v[30:33]
	v_mfma_f32_16x16x32_bf16 v[6:9], v[162:165], v[190:193], v[6:9]
	v_mfma_f32_16x16x32_bf16 v[10:13], v[170:173], v[190:193], v[10:13]
	v_mfma_f32_16x16x32_bf16 v[18:21], v[170:173], v[182:185], v[18:21]
	v_mfma_f32_16x16x32_bf16 v[14:17], v[162:165], v[182:185], v[14:17]
	v_mfma_f32_16x16x32_bf16 v[22:25], v[162:165], v[174:177], v[22:25]
	v_mfma_f32_16x16x32_bf16 v[26:29], v[170:173], v[174:177], v[26:29]
	v_mfma_f32_16x16x32_bf16 v[34:37], v[170:173], v[102:105], v[34:37]
	v_mfma_f32_16x16x32_bf16 v[30:33], v[162:165], v[102:105], v[30:33]
	s_setprio 0
	s_setprio 1
	v_mfma_f32_16x16x32_bf16 v[38:41], v[142:145], v[186:189], v[38:41]
	v_mfma_f32_16x16x32_bf16 v[42:45], v[150:153], v[186:189], v[42:45]
	v_mfma_f32_16x16x32_bf16 v[50:53], v[150:153], v[178:181], v[50:53]
	v_mfma_f32_16x16x32_bf16 v[46:49], v[142:145], v[178:181], v[46:49]
	v_mfma_f32_16x16x32_bf16 v[54:57], v[142:145], v[106:109], v[54:57]
	v_mfma_f32_16x16x32_bf16 v[58:61], v[150:153], v[106:109], v[58:61]
	v_mfma_f32_16x16x32_bf16 v[70:73], v[150:153], v[98:101], v[70:73]
	v_mfma_f32_16x16x32_bf16 v[62:65], v[142:145], v[98:101], v[62:65]
	v_mfma_f32_16x16x32_bf16 v[38:41], v[146:149], v[190:193], v[38:41]
	v_mfma_f32_16x16x32_bf16 v[42:45], v[154:157], v[190:193], v[42:45]
	v_mfma_f32_16x16x32_bf16 v[50:53], v[154:157], v[182:185], v[50:53]
	v_mfma_f32_16x16x32_bf16 v[46:49], v[146:149], v[182:185], v[46:49]
	v_mfma_f32_16x16x32_bf16 v[54:57], v[146:149], v[174:177], v[54:57]
	v_mfma_f32_16x16x32_bf16 v[58:61], v[154:157], v[174:177], v[58:61]
	v_mfma_f32_16x16x32_bf16 v[70:73], v[154:157], v[102:105], v[70:73]
	v_mfma_f32_16x16x32_bf16 v[62:65], v[146:149], v[102:105], v[62:65]
	s_setprio 0
	s_barrier
	s_add_i32 s90, s90, 2
	s_add_u32 s56, s56, 0x100
	s_addc_u32 s57, s57, 0
	s_cmp_gt_u32 s90, 13
	s_cbranch_scc1 .LBB0_1701
.LBB0_1689:
	ds_read_b128 v[158:161], v222
	ds_read_b128 v[162:165], v222 offset:1024
	ds_read_b128 v[166:169], v222 offset:2048
	ds_read_b128 v[170:173], v222 offset:3072
	ds_read_b128 v[142:145], v223
	ds_read_b128 v[146:149], v223 offset:1024
	ds_read_b128 v[150:153], v223 offset:2048
	ds_read_b128 v[154:157], v223 offset:3072
	s_add_u32 s16, s94, s56
	s_addc_u32 s17, s95, s57
	s_cmpk_lg_i32 s56, 0x600
	s_cselect_b64 s[62:63], -1, 0
	s_and_b64 s[14:15], s[62:63], exec
	s_cselect_b32 s15, s17, s45
	s_cselect_b32 s14, s16, s93
	v_lshl_add_u64 v[98:99], v[210:211], 0, s[56:57]
	s_mov_b32 m0, s79
	v_lshl_add_u64 v[100:101], v[98:99], 0, s[34:35]
	ds_read_b128 v[102:105], v224
	ds_read_b128 v[106:109], v224 offset:1024
	ds_read_b128 v[174:177], v224 offset:2048
	ds_read_b128 v[178:181], v224 offset:3072
	ds_read_b128 v[182:185], v224 offset:4096
	ds_read_b128 v[186:189], v224 offset:5120
	ds_read_b128 v[190:193], v224 offset:6144
	ds_read_b128 v[194:197], v224 offset:7168
	global_load_lds_dwordx4 v[100:101], off
	v_lshl_add_u64 v[100:101], v[212:213], 0, s[56:57]
	v_lshl_add_u64 v[214:215], v[100:101], 0, s[34:35]
	s_mov_b32 m0, s80
	v_lshl_add_u64 v[98:99], v[98:99], 0, s[42:43]
	global_load_lds_dwordx4 v[214:215], off
	s_mov_b32 m0, s81
	s_nor_b64 s[16:17], s[38:39], s[62:63]
	global_load_lds_dwordx4 v[98:99], off
	v_lshl_add_u64 v[98:99], v[100:101], 0, s[42:43]
	s_mov_b32 m0, s82
	s_nop 0
	global_load_lds_dwordx4 v[98:99], off
	s_waitcnt vmcnt(8)
	s_waitcnt lgkmcnt(0)
	s_barrier
	s_setprio 1
	s_waitcnt lgkmcnt(0)
	v_mfma_f32_16x16x32_bf16 v[2:5], v[158:161], v[102:105], v[2:5]
	v_mfma_f32_16x16x32_bf16 v[66:69], v[166:169], v[102:105], v[66:69]
	v_mfma_f32_16x16x32_bf16 v[78:81], v[166:169], v[174:177], v[78:81]
	v_mfma_f32_16x16x32_bf16 v[74:77], v[158:161], v[174:177], v[74:77]
	v_mfma_f32_16x16x32_bf16 v[82:85], v[158:161], v[182:185], v[82:85]
	v_mfma_f32_16x16x32_bf16 v[86:89], v[166:169], v[182:185], v[86:89]
	v_mfma_f32_16x16x32_bf16 v[94:97], v[166:169], v[190:193], v[94:97]
	v_mfma_f32_16x16x32_bf16 v[90:93], v[158:161], v[190:193], v[90:93]
	v_mfma_f32_16x16x32_bf16 v[2:5], v[162:165], v[106:109], v[2:5]
	v_mfma_f32_16x16x32_bf16 v[66:69], v[170:173], v[106:109], v[66:69]
	v_mfma_f32_16x16x32_bf16 v[78:81], v[170:173], v[178:181], v[78:81]
	v_mfma_f32_16x16x32_bf16 v[74:77], v[162:165], v[178:181], v[74:77]
	v_mfma_f32_16x16x32_bf16 v[82:85], v[162:165], v[186:189], v[82:85]
	v_mfma_f32_16x16x32_bf16 v[86:89], v[170:173], v[186:189], v[86:89]
	v_mfma_f32_16x16x32_bf16 v[94:97], v[170:173], v[194:197], v[94:97]
	v_mfma_f32_16x16x32_bf16 v[90:93], v[162:165], v[194:197], v[90:93]
	s_setprio 0
	s_setprio 1
	v_mfma_f32_16x16x32_bf16 v[98:101], v[142:145], v[102:105], v[110:113]
	v_mfma_f32_16x16x32_bf16 v[110:113], v[150:153], v[174:177], v[122:125]
	v_mfma_f32_16x16x32_bf16 v[122:125], v[154:157], v[178:181], v[110:113]
	v_mfma_f32_16x16x32_bf16 v[110:113], v[142:145], v[182:185], v[126:129]
	v_mfma_f32_16x16x32_bf16 v[126:129], v[146:149], v[186:189], v[110:113]
	v_mfma_f32_16x16x32_bf16 v[110:113], v[150:153], v[182:185], v[130:133]
	v_mfma_f32_16x16x32_bf16 v[102:105], v[150:153], v[102:105], v[114:117]
	v_mfma_f32_16x16x32_bf16 v[130:133], v[154:157], v[186:189], v[110:113]
	v_mfma_f32_16x16x32_bf16 v[110:113], v[142:145], v[190:193], v[134:137]
	v_mfma_f32_16x16x32_bf16 v[98:101], v[146:149], v[106:109], v[98:101]
	v_mfma_f32_16x16x32_bf16 v[102:105], v[154:157], v[106:109], v[102:105]
	v_mfma_f32_16x16x32_bf16 v[106:109], v[142:145], v[174:177], v[118:121]
	v_mfma_f32_16x16x32_bf16 v[134:137], v[146:149], v[194:197], v[110:113]
	v_mfma_f32_16x16x32_bf16 v[110:113], v[150:153], v[190:193], v[138:141]
	v_mfma_f32_16x16x32_bf16 v[106:109], v[146:149], v[178:181], v[106:109]
	v_mfma_f32_16x16x32_bf16 v[138:141], v[154:157], v[194:197], v[110:113]
	s_setprio 0
	s_barrier
	ds_read_b128 v[186:189], v224 offset:16384
	ds_read_b128 v[190:193], v224 offset:17408
	ds_read_b128 v[178:181], v224 offset:18432
	ds_read_b128 v[182:185], v224 offset:19456
	ds_read_b128 v[118:121], v224 offset:20480
	ds_read_b128 v[174:177], v224 offset:21504
	ds_read_b128 v[110:113], v224 offset:22528
	ds_read_b128 v[114:117], v224 offset:23552
	s_mov_b64 s[64:65], -1
	s_and_b64 vcc, exec, s[16:17]
	s_cbranch_vccz .LBB0_1691
	s_waitcnt vmcnt(2)
	s_mov_b64 s[64:65], 0

.LBB0_1693:
	s_waitcnt lgkmcnt(0)
	s_barrier
	s_setprio 1
	s_waitcnt lgkmcnt(0)
	v_mfma_f32_16x16x32_bf16 v[6:9], v[158:161], v[186:189], v[6:9]
	v_mfma_f32_16x16x32_bf16 v[10:13], v[166:169], v[186:189], v[10:13]
	v_mfma_f32_16x16x32_bf16 v[18:21], v[166:169], v[178:181], v[18:21]
	v_mfma_f32_16x16x32_bf16 v[14:17], v[158:161], v[178:181], v[14:17]
	v_mfma_f32_16x16x32_bf16 v[22:25], v[158:161], v[118:121], v[22:25]
	v_mfma_f32_16x16x32_bf16 v[26:29], v[166:169], v[118:121], v[26:29]
	v_mfma_f32_16x16x32_bf16 v[34:37], v[166:169], v[110:113], v[34:37]
	v_mfma_f32_16x16x32_bf16 v[30:33], v[158:161], v[110:113], v[30:33]
	v_mfma_f32_16x16x32_bf16 v[6:9], v[162:165], v[190:193], v[6:9]
	v_mfma_f32_16x16x32_bf16 v[10:13], v[170:173], v[190:193], v[10:13]
	v_mfma_f32_16x16x32_bf16 v[18:21], v[170:173], v[182:185], v[18:21]
	v_mfma_f32_16x16x32_bf16 v[14:17], v[162:165], v[182:185], v[14:17]
	v_mfma_f32_16x16x32_bf16 v[22:25], v[162:165], v[174:177], v[22:25]
	v_mfma_f32_16x16x32_bf16 v[26:29], v[170:173], v[174:177], v[26:29]
	v_mfma_f32_16x16x32_bf16 v[34:37], v[170:173], v[114:117], v[34:37]
	v_mfma_f32_16x16x32_bf16 v[30:33], v[162:165], v[114:117], v[30:33]
	s_setprio 0
	s_setprio 1
	v_mfma_f32_16x16x32_bf16 v[38:41], v[142:145], v[186:189], v[38:41]
	v_mfma_f32_16x16x32_bf16 v[42:45], v[150:153], v[186:189], v[42:45]
	v_mfma_f32_16x16x32_bf16 v[50:53], v[150:153], v[178:181], v[50:53]
	v_mfma_f32_16x16x32_bf16 v[46:49], v[142:145], v[178:181], v[46:49]
	v_mfma_f32_16x16x32_bf16 v[54:57], v[142:145], v[118:121], v[54:57]
	v_mfma_f32_16x16x32_bf16 v[58:61], v[150:153], v[118:121], v[58:61]
	v_mfma_f32_16x16x32_bf16 v[70:73], v[150:153], v[110:113], v[70:73]
	v_mfma_f32_16x16x32_bf16 v[62:65], v[142:145], v[110:113], v[62:65]
	v_mfma_f32_16x16x32_bf16 v[38:41], v[146:149], v[190:193], v[38:41]
	v_mfma_f32_16x16x32_bf16 v[42:45], v[154:157], v[190:193], v[42:45]
	v_mfma_f32_16x16x32_bf16 v[50:53], v[154:157], v[182:185], v[50:53]
	v_mfma_f32_16x16x32_bf16 v[46:49], v[146:149], v[182:185], v[46:49]
	v_mfma_f32_16x16x32_bf16 v[54:57], v[146:149], v[174:177], v[54:57]
	v_mfma_f32_16x16x32_bf16 v[58:61], v[154:157], v[174:177], v[58:61]
	v_mfma_f32_16x16x32_bf16 v[70:73], v[154:157], v[114:117], v[70:73]
	v_mfma_f32_16x16x32_bf16 v[62:65], v[146:149], v[114:117], v[62:65]
	s_setprio 0
	s_barrier
	v_add_u32_e32 v110, 0x18000, v221
	ds_read_b128 v[158:161], v110
	ds_read_b128 v[162:165], v110 offset:1024
	ds_read_b128 v[166:169], v110 offset:2048
	ds_read_b128 v[170:173], v110 offset:3072
	v_add_u32_e32 v110, 0x1c000, v221
	ds_read_b128 v[142:145], v110
	ds_read_b128 v[146:149], v110 offset:1024
	ds_read_b128 v[150:153], v110 offset:2048
	ds_read_b128 v[154:157], v110 offset:3072
	ds_read_b128 v[114:117], v224 offset:32768
	ds_read_b128 v[118:121], v224 offset:33792
	ds_read_b128 v[190:193], v224 offset:34816
	ds_read_b128 v[194:197], v224 offset:35840
	ds_read_b128 v[182:185], v224 offset:36864
	ds_read_b128 v[186:189], v224 offset:37888
	ds_read_b128 v[174:177], v224 offset:38912
	ds_read_b128 v[178:181], v224 offset:39936
	s_mov_b64 s[64:65], -1
	s_and_b64 vcc, exec, s[16:17]
	s_cbranch_vccz .LBB0_1695
	s_waitcnt vmcnt(0)
	s_mov_b64 s[64:65], 0

.LBB0_1697:
	s_waitcnt lgkmcnt(0)
	s_barrier
	s_setprio 1
	s_waitcnt lgkmcnt(0)
	v_mfma_f32_16x16x32_bf16 v[2:5], v[158:161], v[114:117], v[2:5]
	v_mfma_f32_16x16x32_bf16 v[66:69], v[166:169], v[114:117], v[66:69]
	v_mfma_f32_16x16x32_bf16 v[78:81], v[166:169], v[190:193], v[78:81]
	v_mfma_f32_16x16x32_bf16 v[74:77], v[158:161], v[190:193], v[74:77]
	v_mfma_f32_16x16x32_bf16 v[82:85], v[158:161], v[182:185], v[82:85]
	v_mfma_f32_16x16x32_bf16 v[86:89], v[166:169], v[182:185], v[86:89]
	v_mfma_f32_16x16x32_bf16 v[94:97], v[166:169], v[174:177], v[94:97]
	v_mfma_f32_16x16x32_bf16 v[90:93], v[158:161], v[174:177], v[90:93]
	v_mfma_f32_16x16x32_bf16 v[2:5], v[162:165], v[118:121], v[2:5]
	v_mfma_f32_16x16x32_bf16 v[66:69], v[170:173], v[118:121], v[66:69]
	v_mfma_f32_16x16x32_bf16 v[78:81], v[170:173], v[194:197], v[78:81]
	v_mfma_f32_16x16x32_bf16 v[74:77], v[162:165], v[194:197], v[74:77]
	v_mfma_f32_16x16x32_bf16 v[82:85], v[162:165], v[186:189], v[82:85]
	v_mfma_f32_16x16x32_bf16 v[86:89], v[170:173], v[186:189], v[86:89]
	v_mfma_f32_16x16x32_bf16 v[94:97], v[170:173], v[178:181], v[94:97]
	v_mfma_f32_16x16x32_bf16 v[90:93], v[162:165], v[178:181], v[90:93]
	s_setprio 0
	s_setprio 1
	v_mfma_f32_16x16x32_bf16 v[98:101], v[142:145], v[114:117], v[98:101]
	v_mfma_f32_16x16x32_bf16 v[110:113], v[146:149], v[118:121], v[98:101]
	v_mfma_f32_16x16x32_bf16 v[98:101], v[150:153], v[114:117], v[102:105]
	v_mfma_f32_16x16x32_bf16 v[114:117], v[154:157], v[118:121], v[98:101]
	v_mfma_f32_16x16x32_bf16 v[98:101], v[142:145], v[190:193], v[106:109]
	v_mfma_f32_16x16x32_bf16 v[118:121], v[146:149], v[194:197], v[98:101]
	v_mfma_f32_16x16x32_bf16 v[98:101], v[150:153], v[190:193], v[122:125]
	v_mfma_f32_16x16x32_bf16 v[122:125], v[154:157], v[194:197], v[98:101]
	v_mfma_f32_16x16x32_bf16 v[98:101], v[142:145], v[182:185], v[126:129]
	v_mfma_f32_16x16x32_bf16 v[126:129], v[146:149], v[186:189], v[98:101]
	v_mfma_f32_16x16x32_bf16 v[98:101], v[150:153], v[182:185], v[130:133]
	v_mfma_f32_16x16x32_bf16 v[130:133], v[154:157], v[186:189], v[98:101]
	v_mfma_f32_16x16x32_bf16 v[98:101], v[142:145], v[174:177], v[134:137]
	v_mfma_f32_16x16x32_bf16 v[134:137], v[146:149], v[178:181], v[98:101]
	v_mfma_f32_16x16x32_bf16 v[98:101], v[150:153], v[174:177], v[138:141]
	v_mfma_f32_16x16x32_bf16 v[138:141], v[154:157], v[178:181], v[98:101]
	s_setprio 0
	s_barrier
	ds_read_b128 v[186:189], v224 offset:49152
	ds_read_b128 v[190:193], v224 offset:50176
	ds_read_b128 v[178:181], v224 offset:51200
	ds_read_b128 v[182:185], v224 offset:52224
	ds_read_b128 v[106:109], v224 offset:53248
	ds_read_b128 v[174:177], v224 offset:54272
	ds_read_b128 v[98:101], v224 offset:55296
	ds_read_b128 v[102:105], v224 offset:56320
	s_mov_b64 s[62:63], -1
	s_and_b64 vcc, exec, s[16:17]
	s_cbranch_vccz .LBB0_1699
	s_waitcnt vmcnt(0)
	s_mov_b64 s[62:63], 0

.LBB0_1759:
	s_waitcnt lgkmcnt(0)
	s_barrier
	s_setprio 1
	s_waitcnt lgkmcnt(0)
	v_mfma_f32_16x16x32_bf16 v[62:65], v[154:157], v[186:189], v[62:65]
	v_mfma_f32_16x16x32_bf16 v[54:57], v[146:149], v[186:189], v[54:57]
	v_mfma_f32_16x16x32_bf16 v[38:41], v[146:149], v[178:181], v[38:41]
	v_mfma_f32_16x16x32_bf16 v[46:49], v[154:157], v[178:181], v[46:49]
	v_mfma_f32_16x16x32_bf16 v[30:33], v[154:157], v[170:173], v[30:33]
	v_mfma_f32_16x16x32_bf16 v[22:25], v[146:149], v[170:173], v[22:25]
	v_mfma_f32_16x16x32_bf16 v[6:9], v[146:149], v[162:165], v[6:9]
	v_mfma_f32_16x16x32_bf16 v[14:17], v[154:157], v[162:165], v[14:17]
	v_mfma_f32_16x16x32_bf16 v[62:65], v[158:161], v[190:193], v[62:65]
	v_mfma_f32_16x16x32_bf16 v[54:57], v[150:153], v[190:193], v[54:57]
	v_mfma_f32_16x16x32_bf16 v[38:41], v[150:153], v[182:185], v[38:41]
	v_mfma_f32_16x16x32_bf16 v[46:49], v[158:161], v[182:185], v[46:49]
	v_mfma_f32_16x16x32_bf16 v[30:33], v[158:161], v[174:177], v[30:33]
	v_mfma_f32_16x16x32_bf16 v[22:25], v[150:153], v[174:177], v[22:25]
	v_mfma_f32_16x16x32_bf16 v[6:9], v[150:153], v[166:169], v[6:9]
	v_mfma_f32_16x16x32_bf16 v[14:17], v[158:161], v[166:169], v[14:17]
	s_setprio 0
	s_setprio 1
	v_mfma_f32_16x16x32_bf16 v[58:61], v[138:141], v[186:189], v[58:61]
	v_mfma_f32_16x16x32_bf16 v[50:53], v[130:133], v[186:189], v[50:53]
	v_mfma_f32_16x16x32_bf16 v[34:37], v[130:133], v[178:181], v[34:37]
	v_mfma_f32_16x16x32_bf16 v[42:45], v[138:141], v[178:181], v[42:45]
	v_mfma_f32_16x16x32_bf16 v[26:29], v[138:141], v[170:173], v[26:29]
	v_mfma_f32_16x16x32_bf16 v[18:21], v[130:133], v[170:173], v[18:21]
	v_mfma_f32_16x16x32_bf16 v[2:5], v[130:133], v[162:165], v[2:5]
	v_mfma_f32_16x16x32_bf16 v[10:13], v[138:141], v[162:165], v[10:13]
	v_mfma_f32_16x16x32_bf16 v[58:61], v[142:145], v[190:193], v[58:61]
	v_mfma_f32_16x16x32_bf16 v[50:53], v[134:137], v[190:193], v[50:53]
	v_mfma_f32_16x16x32_bf16 v[34:37], v[134:137], v[182:185], v[34:37]
	v_mfma_f32_16x16x32_bf16 v[42:45], v[142:145], v[182:185], v[42:45]
	v_mfma_f32_16x16x32_bf16 v[26:29], v[142:145], v[174:177], v[26:29]
	v_mfma_f32_16x16x32_bf16 v[18:21], v[134:137], v[174:177], v[18:21]
	v_mfma_f32_16x16x32_bf16 v[2:5], v[134:137], v[166:169], v[2:5]
	v_mfma_f32_16x16x32_bf16 v[10:13], v[142:145], v[166:169], v[10:13]
	s_setprio 0
	s_barrier
	s_add_i32 s94, s94, 2
	s_add_u32 s56, s56, 0x100
	s_addc_u32 s57, s57, 0
	s_cmp_gt_u32 s94, 13
	s_cbranch_scc1 .LBB0_1772
.LBB0_1760:
	ds_read_b128 v[146:149], v217
	ds_read_b128 v[150:153], v217 offset:1024
	ds_read_b128 v[154:157], v217 offset:2048
	ds_read_b128 v[158:161], v217 offset:3072
	ds_read_b128 v[130:133], v218
	ds_read_b128 v[134:137], v218 offset:1024
	ds_read_b128 v[138:141], v218 offset:2048
	ds_read_b128 v[142:145], v218 offset:3072
	s_add_u32 s16, s92, s56
	s_addc_u32 s17, s93, s57
	s_cmpk_lg_i32 s56, 0x600
	s_cselect_b64 s[62:63], -1, 0
	s_and_b64 s[14:15], s[62:63], exec
	s_cselect_b32 s15, s17, s29
	s_cselect_b32 s14, s16, s97
	v_lshl_add_u64 v[202:203], v[206:207], 0, s[56:57]
	s_mov_b32 m0, s80
	v_lshl_add_u64 v[210:211], v[202:203], 0, s[30:31]
	ds_read_b128 v[162:165], v219
	ds_read_b128 v[166:169], v219 offset:1024
	ds_read_b128 v[170:173], v219 offset:2048
	ds_read_b128 v[174:177], v219 offset:3072
	ds_read_b128 v[178:181], v219 offset:4096
	ds_read_b128 v[182:185], v219 offset:5120
	ds_read_b128 v[186:189], v219 offset:6144
	ds_read_b128 v[190:193], v219 offset:7168
	global_load_lds_dwordx4 v[210:211], off
	v_lshl_add_u64 v[210:211], v[208:209], 0, s[56:57]
	v_lshl_add_u64 v[212:213], v[210:211], 0, s[30:31]
	s_mov_b32 m0, s81
	v_lshl_add_u64 v[202:203], v[202:203], 0, s[34:35]
	global_load_lds_dwordx4 v[212:213], off
	s_mov_b32 m0, s82
	s_nor_b64 s[16:17], s[38:39], s[62:63]
	global_load_lds_dwordx4 v[202:203], off
	v_lshl_add_u64 v[202:203], v[210:211], 0, s[34:35]
	s_mov_b32 m0, s83
	s_nop 0
	global_load_lds_dwordx4 v[202:203], off
	s_waitcnt vmcnt(8)
	s_waitcnt lgkmcnt(0)
	s_barrier
	s_setprio 1
	s_waitcnt lgkmcnt(0)
	v_mfma_f32_16x16x32_bf16 v[126:129], v[146:149], v[162:165], v[126:129]
	v_mfma_f32_16x16x32_bf16 v[118:121], v[154:157], v[162:165], v[118:121]
	v_mfma_f32_16x16x32_bf16 v[106:109], v[154:157], v[170:173], v[106:109]
	v_mfma_f32_16x16x32_bf16 v[110:113], v[146:149], v[170:173], v[110:113]
	v_mfma_f32_16x16x32_bf16 v[94:97], v[146:149], v[178:181], v[94:97]
	v_mfma_f32_16x16x32_bf16 v[90:93], v[154:157], v[178:181], v[90:93]
	v_mfma_f32_16x16x32_bf16 v[74:77], v[154:157], v[186:189], v[74:77]
	v_mfma_f32_16x16x32_bf16 v[78:81], v[146:149], v[186:189], v[78:81]
	v_mfma_f32_16x16x32_bf16 v[126:129], v[150:153], v[166:169], v[126:129]
	v_mfma_f32_16x16x32_bf16 v[118:121], v[158:161], v[166:169], v[118:121]
	v_mfma_f32_16x16x32_bf16 v[106:109], v[158:161], v[174:177], v[106:109]
	v_mfma_f32_16x16x32_bf16 v[110:113], v[150:153], v[174:177], v[110:113]
	v_mfma_f32_16x16x32_bf16 v[94:97], v[150:153], v[182:185], v[94:97]
	v_mfma_f32_16x16x32_bf16 v[90:93], v[158:161], v[182:185], v[90:93]
	v_mfma_f32_16x16x32_bf16 v[74:77], v[158:161], v[190:193], v[74:77]
	v_mfma_f32_16x16x32_bf16 v[78:81], v[150:153], v[190:193], v[78:81]
	s_setprio 0
	s_setprio 1
	v_mfma_f32_16x16x32_bf16 v[122:125], v[130:133], v[162:165], v[122:125]
	v_mfma_f32_16x16x32_bf16 v[114:117], v[138:141], v[162:165], v[114:117]
	v_mfma_f32_16x16x32_bf16 v[98:101], v[138:141], v[170:173], v[98:101]
	v_mfma_f32_16x16x32_bf16 v[102:105], v[130:133], v[170:173], v[102:105]
	v_mfma_f32_16x16x32_bf16 v[86:89], v[130:133], v[178:181], v[86:89]
	v_mfma_f32_16x16x32_bf16 v[82:85], v[138:141], v[178:181], v[82:85]
	v_mfma_f32_16x16x32_bf16 v[66:69], v[138:141], v[186:189], v[66:69]
	v_mfma_f32_16x16x32_bf16 v[70:73], v[130:133], v[186:189], v[70:73]
	v_mfma_f32_16x16x32_bf16 v[122:125], v[134:137], v[166:169], v[122:125]
	v_mfma_f32_16x16x32_bf16 v[114:117], v[142:145], v[166:169], v[114:117]
	v_mfma_f32_16x16x32_bf16 v[98:101], v[142:145], v[174:177], v[98:101]
	v_mfma_f32_16x16x32_bf16 v[102:105], v[134:137], v[174:177], v[102:105]
	v_mfma_f32_16x16x32_bf16 v[86:89], v[134:137], v[182:185], v[86:89]
	v_mfma_f32_16x16x32_bf16 v[82:85], v[142:145], v[182:185], v[82:85]
	v_mfma_f32_16x16x32_bf16 v[66:69], v[142:145], v[190:193], v[66:69]
	v_mfma_f32_16x16x32_bf16 v[70:73], v[134:137], v[190:193], v[70:73]
	s_setprio 0
	s_barrier
	ds_read_b128 v[186:189], v219 offset:16384
	ds_read_b128 v[190:193], v219 offset:17408
	ds_read_b128 v[178:181], v219 offset:18432
	ds_read_b128 v[182:185], v219 offset:19456
	ds_read_b128 v[170:173], v219 offset:20480
	ds_read_b128 v[174:177], v219 offset:21504
	ds_read_b128 v[162:165], v219 offset:22528
	ds_read_b128 v[166:169], v219 offset:23552
	s_mov_b64 s[64:65], -1
	s_and_b64 vcc, exec, s[16:17]
	s_cbranch_vccz .LBB0_1762
	s_waitcnt vmcnt(2)
	s_mov_b64 s[64:65], 0

.LBB0_1764:
	s_waitcnt lgkmcnt(0)
	s_barrier
	s_setprio 1
	s_waitcnt lgkmcnt(0)
	v_mfma_f32_16x16x32_bf16 v[62:65], v[146:149], v[186:189], v[62:65]
	v_mfma_f32_16x16x32_bf16 v[54:57], v[154:157], v[186:189], v[54:57]
	v_mfma_f32_16x16x32_bf16 v[38:41], v[154:157], v[178:181], v[38:41]
	v_mfma_f32_16x16x32_bf16 v[46:49], v[146:149], v[178:181], v[46:49]
	v_mfma_f32_16x16x32_bf16 v[30:33], v[146:149], v[170:173], v[30:33]
	v_mfma_f32_16x16x32_bf16 v[22:25], v[154:157], v[170:173], v[22:25]
	v_mfma_f32_16x16x32_bf16 v[6:9], v[154:157], v[162:165], v[6:9]
	v_mfma_f32_16x16x32_bf16 v[14:17], v[146:149], v[162:165], v[14:17]
	v_mfma_f32_16x16x32_bf16 v[62:65], v[150:153], v[190:193], v[62:65]
	v_mfma_f32_16x16x32_bf16 v[54:57], v[158:161], v[190:193], v[54:57]
	v_mfma_f32_16x16x32_bf16 v[38:41], v[158:161], v[182:185], v[38:41]
	v_mfma_f32_16x16x32_bf16 v[46:49], v[150:153], v[182:185], v[46:49]
	v_mfma_f32_16x16x32_bf16 v[30:33], v[150:153], v[174:177], v[30:33]
	v_mfma_f32_16x16x32_bf16 v[22:25], v[158:161], v[174:177], v[22:25]
	v_mfma_f32_16x16x32_bf16 v[6:9], v[158:161], v[166:169], v[6:9]
	v_mfma_f32_16x16x32_bf16 v[14:17], v[150:153], v[166:169], v[14:17]
	s_setprio 0
	s_setprio 1
	v_mfma_f32_16x16x32_bf16 v[58:61], v[130:133], v[186:189], v[58:61]
	v_mfma_f32_16x16x32_bf16 v[50:53], v[138:141], v[186:189], v[50:53]
	v_mfma_f32_16x16x32_bf16 v[34:37], v[138:141], v[178:181], v[34:37]
	v_mfma_f32_16x16x32_bf16 v[42:45], v[130:133], v[178:181], v[42:45]
	v_mfma_f32_16x16x32_bf16 v[26:29], v[130:133], v[170:173], v[26:29]
	v_mfma_f32_16x16x32_bf16 v[18:21], v[138:141], v[170:173], v[18:21]
	v_mfma_f32_16x16x32_bf16 v[2:5], v[138:141], v[162:165], v[2:5]
	v_mfma_f32_16x16x32_bf16 v[10:13], v[130:133], v[162:165], v[10:13]
	v_mfma_f32_16x16x32_bf16 v[58:61], v[134:137], v[190:193], v[58:61]
	v_mfma_f32_16x16x32_bf16 v[50:53], v[142:145], v[190:193], v[50:53]
	v_mfma_f32_16x16x32_bf16 v[34:37], v[142:145], v[182:185], v[34:37]
	v_mfma_f32_16x16x32_bf16 v[42:45], v[134:137], v[182:185], v[42:45]
	v_mfma_f32_16x16x32_bf16 v[26:29], v[134:137], v[174:177], v[26:29]
	v_mfma_f32_16x16x32_bf16 v[18:21], v[142:145], v[174:177], v[18:21]
	v_mfma_f32_16x16x32_bf16 v[2:5], v[142:145], v[166:169], v[2:5]
	v_mfma_f32_16x16x32_bf16 v[10:13], v[134:137], v[166:169], v[10:13]
	s_setprio 0
	s_barrier
	v_add_u32_e32 v130, 0x18000, v216
	v_add_u32_e32 v134, 0x1c000, v216
	ds_read_b128 v[154:157], v130
	ds_read_b128 v[158:161], v130 offset:1024
	ds_read_b128 v[146:149], v130 offset:2048
	ds_read_b128 v[150:153], v130 offset:3072
	ds_read_b128 v[138:141], v134
	ds_read_b128 v[142:145], v134 offset:1024
	ds_read_b128 v[130:133], v134 offset:2048
	ds_read_b128 v[134:137], v134 offset:3072
	ds_read_b128 v[186:189], v219 offset:32768
	ds_read_b128 v[190:193], v219 offset:33792
	ds_read_b128 v[178:181], v219 offset:34816
	ds_read_b128 v[182:185], v219 offset:35840
	ds_read_b128 v[170:173], v219 offset:36864
	ds_read_b128 v[174:177], v219 offset:37888
	ds_read_b128 v[162:165], v219 offset:38912
	ds_read_b128 v[166:169], v219 offset:39936
	s_mov_b64 s[64:65], -1
	s_and_b64 vcc, exec, s[16:17]
	s_cbranch_vccz .LBB0_1766
	s_waitcnt vmcnt(0)
	s_mov_b64 s[64:65], 0

.LBB0_1768:
	s_waitcnt lgkmcnt(0)
	s_barrier
	s_setprio 1
	s_waitcnt lgkmcnt(0)
	v_mfma_f32_16x16x32_bf16 v[126:129], v[154:157], v[186:189], v[126:129]
	v_mfma_f32_16x16x32_bf16 v[118:121], v[146:149], v[186:189], v[118:121]
	v_mfma_f32_16x16x32_bf16 v[106:109], v[146:149], v[178:181], v[106:109]
	v_mfma_f32_16x16x32_bf16 v[110:113], v[154:157], v[178:181], v[110:113]
	v_mfma_f32_16x16x32_bf16 v[94:97], v[154:157], v[170:173], v[94:97]
	v_mfma_f32_16x16x32_bf16 v[90:93], v[146:149], v[170:173], v[90:93]
	v_mfma_f32_16x16x32_bf16 v[74:77], v[146:149], v[162:165], v[74:77]
	v_mfma_f32_16x16x32_bf16 v[78:81], v[154:157], v[162:165], v[78:81]
	v_mfma_f32_16x16x32_bf16 v[126:129], v[158:161], v[190:193], v[126:129]
	v_mfma_f32_16x16x32_bf16 v[118:121], v[150:153], v[190:193], v[118:121]
	v_mfma_f32_16x16x32_bf16 v[106:109], v[150:153], v[182:185], v[106:109]
	v_mfma_f32_16x16x32_bf16 v[110:113], v[158:161], v[182:185], v[110:113]
	v_mfma_f32_16x16x32_bf16 v[94:97], v[158:161], v[174:177], v[94:97]
	v_mfma_f32_16x16x32_bf16 v[90:93], v[150:153], v[174:177], v[90:93]
	v_mfma_f32_16x16x32_bf16 v[74:77], v[150:153], v[166:169], v[74:77]
	v_mfma_f32_16x16x32_bf16 v[78:81], v[158:161], v[166:169], v[78:81]
	s_setprio 0
	s_setprio 1
	v_mfma_f32_16x16x32_bf16 v[122:125], v[138:141], v[186:189], v[122:125]
	v_mfma_f32_16x16x32_bf16 v[114:117], v[130:133], v[186:189], v[114:117]
	v_mfma_f32_16x16x32_bf16 v[98:101], v[130:133], v[178:181], v[98:101]
	v_mfma_f32_16x16x32_bf16 v[102:105], v[138:141], v[178:181], v[102:105]
	v_mfma_f32_16x16x32_bf16 v[86:89], v[138:141], v[170:173], v[86:89]
	v_mfma_f32_16x16x32_bf16 v[82:85], v[130:133], v[170:173], v[82:85]
	v_mfma_f32_16x16x32_bf16 v[66:69], v[130:133], v[162:165], v[66:69]
	v_mfma_f32_16x16x32_bf16 v[70:73], v[138:141], v[162:165], v[70:73]
	v_mfma_f32_16x16x32_bf16 v[122:125], v[142:145], v[190:193], v[122:125]
	v_mfma_f32_16x16x32_bf16 v[114:117], v[134:137], v[190:193], v[114:117]
	v_mfma_f32_16x16x32_bf16 v[98:101], v[134:137], v[182:185], v[98:101]
	v_mfma_f32_16x16x32_bf16 v[102:105], v[142:145], v[182:185], v[102:105]
	v_mfma_f32_16x16x32_bf16 v[86:89], v[142:145], v[174:177], v[86:89]
	v_mfma_f32_16x16x32_bf16 v[82:85], v[134:137], v[174:177], v[82:85]
	v_mfma_f32_16x16x32_bf16 v[66:69], v[134:137], v[166:169], v[66:69]
	v_mfma_f32_16x16x32_bf16 v[70:73], v[142:145], v[166:169], v[70:73]
	s_setprio 0
	s_barrier
	ds_read_b128 v[186:189], v219 offset:49152
	ds_read_b128 v[190:193], v219 offset:50176
	ds_read_b128 v[178:181], v219 offset:51200
	ds_read_b128 v[182:185], v219 offset:52224
	ds_read_b128 v[170:173], v219 offset:53248
	ds_read_b128 v[174:177], v219 offset:54272
	ds_read_b128 v[162:165], v219 offset:55296
	ds_read_b128 v[166:169], v219 offset:56320
	s_mov_b64 s[62:63], -1
	s_and_b64 vcc, exec, s[16:17]
	s_cbranch_vccz .LBB0_1770
	s_waitcnt vmcnt(0)
	s_mov_b64 s[62:63], 0

.LBB0_1927:
	s_waitcnt lgkmcnt(0)
	s_barrier
	s_setprio 1
	s_waitcnt lgkmcnt(0)
	v_mfma_f32_16x16x32_bf16 v[58:61], v[146:149], v[186:189], v[58:61]
	v_mfma_f32_16x16x32_bf16 v[50:53], v[154:157], v[186:189], v[50:53]
	v_mfma_f32_16x16x32_bf16 v[34:37], v[154:157], v[178:181], v[34:37]
	v_mfma_f32_16x16x32_bf16 v[42:45], v[146:149], v[178:181], v[42:45]
	v_mfma_f32_16x16x32_bf16 v[26:29], v[146:149], v[170:173], v[26:29]
	v_mfma_f32_16x16x32_bf16 v[18:21], v[154:157], v[170:173], v[18:21]
	v_mfma_f32_16x16x32_bf16 v[2:5], v[154:157], v[162:165], v[2:5]
	v_mfma_f32_16x16x32_bf16 v[10:13], v[146:149], v[162:165], v[10:13]
	v_mfma_f32_16x16x32_bf16 v[58:61], v[150:153], v[190:193], v[58:61]
	v_mfma_f32_16x16x32_bf16 v[50:53], v[158:161], v[190:193], v[50:53]
	v_mfma_f32_16x16x32_bf16 v[34:37], v[158:161], v[182:185], v[34:37]
	v_mfma_f32_16x16x32_bf16 v[42:45], v[150:153], v[182:185], v[42:45]
	v_mfma_f32_16x16x32_bf16 v[26:29], v[150:153], v[174:177], v[26:29]
	v_mfma_f32_16x16x32_bf16 v[18:21], v[158:161], v[174:177], v[18:21]
	v_mfma_f32_16x16x32_bf16 v[2:5], v[158:161], v[166:169], v[2:5]
	v_mfma_f32_16x16x32_bf16 v[10:13], v[150:153], v[166:169], v[10:13]
	s_setprio 0
	s_setprio 1
	v_mfma_f32_16x16x32_bf16 v[62:65], v[130:133], v[186:189], v[62:65]
	v_mfma_f32_16x16x32_bf16 v[54:57], v[138:141], v[186:189], v[54:57]
	v_mfma_f32_16x16x32_bf16 v[38:41], v[138:141], v[178:181], v[38:41]
	v_mfma_f32_16x16x32_bf16 v[46:49], v[130:133], v[178:181], v[46:49]
	v_mfma_f32_16x16x32_bf16 v[30:33], v[130:133], v[170:173], v[30:33]
	v_mfma_f32_16x16x32_bf16 v[22:25], v[138:141], v[170:173], v[22:25]
	v_mfma_f32_16x16x32_bf16 v[6:9], v[138:141], v[162:165], v[6:9]
	v_mfma_f32_16x16x32_bf16 v[14:17], v[130:133], v[162:165], v[14:17]
	v_mfma_f32_16x16x32_bf16 v[62:65], v[134:137], v[190:193], v[62:65]
	v_mfma_f32_16x16x32_bf16 v[54:57], v[142:145], v[190:193], v[54:57]
	v_mfma_f32_16x16x32_bf16 v[38:41], v[142:145], v[182:185], v[38:41]
	v_mfma_f32_16x16x32_bf16 v[46:49], v[134:137], v[182:185], v[46:49]
	v_mfma_f32_16x16x32_bf16 v[30:33], v[134:137], v[174:177], v[30:33]
	v_mfma_f32_16x16x32_bf16 v[22:25], v[142:145], v[174:177], v[22:25]
	v_mfma_f32_16x16x32_bf16 v[6:9], v[142:145], v[166:169], v[6:9]
	v_mfma_f32_16x16x32_bf16 v[14:17], v[134:137], v[166:169], v[14:17]
	s_setprio 0
	s_barrier
	s_add_i32 s94, s94, 2
	s_add_u32 s44, s44, 0x100
	s_addc_u32 s45, s45, 0
	s_cmp_gt_u32 s94, 13
	s_cbranch_scc1 .LBB0_1940
.LBB0_1928:
	ds_read_b128 v[146:149], v222
	ds_read_b128 v[150:153], v222 offset:1024
	ds_read_b128 v[154:157], v222 offset:2048
	ds_read_b128 v[158:161], v222 offset:3072
	ds_read_b128 v[130:133], v223
	ds_read_b128 v[134:137], v223 offset:1024
	ds_read_b128 v[138:141], v223 offset:2048
	ds_read_b128 v[142:145], v223 offset:3072
	s_add_u32 s16, s90, s44
	s_addc_u32 s17, s91, s45
	s_cmpk_lg_i32 s44, 0x600
	s_cselect_b64 s[46:47], -1, 0
	s_and_b64 s[14:15], s[46:47], exec
	s_cselect_b32 s15, s17, s29
	s_cselect_b32 s14, s16, s93
	v_lshl_add_u64 v[214:215], v[212:213], 0, s[44:45]
	s_mov_b32 m0, s69
	v_lshl_add_u64 v[216:217], v[214:215], 0, s[24:25]
	ds_read_b128 v[162:165], v224
	ds_read_b128 v[166:169], v224 offset:1024
	ds_read_b128 v[170:173], v224 offset:2048
	ds_read_b128 v[174:177], v224 offset:3072
	ds_read_b128 v[178:181], v224 offset:4096
	ds_read_b128 v[182:185], v224 offset:5120
	ds_read_b128 v[186:189], v224 offset:6144
	ds_read_b128 v[190:193], v224 offset:7168
	global_load_lds_dwordx4 v[216:217], off
	v_lshl_add_u64 v[216:217], v[210:211], 0, s[44:45]
	v_lshl_add_u64 v[226:227], v[216:217], 0, s[24:25]
	s_mov_b32 m0, s70
	v_lshl_add_u64 v[214:215], v[214:215], 0, s[26:27]
	global_load_lds_dwordx4 v[226:227], off
	s_mov_b32 m0, s71
	s_nor_b64 s[16:17], s[36:37], s[46:47]
	global_load_lds_dwordx4 v[214:215], off
	v_lshl_add_u64 v[214:215], v[216:217], 0, s[26:27]
	s_mov_b32 m0, s72
	s_nop 0
	global_load_lds_dwordx4 v[214:215], off
	s_waitcnt vmcnt(8)
	s_waitcnt lgkmcnt(0)
	s_barrier
	s_setprio 1
	s_waitcnt lgkmcnt(0)
	v_mfma_f32_16x16x32_bf16 v[122:125], v[146:149], v[162:165], v[122:125]
	v_mfma_f32_16x16x32_bf16 v[114:117], v[154:157], v[162:165], v[114:117]
	v_mfma_f32_16x16x32_bf16 v[98:101], v[154:157], v[170:173], v[98:101]
	v_mfma_f32_16x16x32_bf16 v[106:109], v[146:149], v[170:173], v[106:109]
	v_mfma_f32_16x16x32_bf16 v[90:93], v[146:149], v[178:181], v[90:93]
	v_mfma_f32_16x16x32_bf16 v[82:85], v[154:157], v[178:181], v[82:85]
	v_mfma_f32_16x16x32_bf16 v[66:69], v[154:157], v[186:189], v[66:69]
	v_mfma_f32_16x16x32_bf16 v[74:77], v[146:149], v[186:189], v[74:77]
	v_mfma_f32_16x16x32_bf16 v[122:125], v[150:153], v[166:169], v[122:125]
	v_mfma_f32_16x16x32_bf16 v[114:117], v[158:161], v[166:169], v[114:117]
	v_mfma_f32_16x16x32_bf16 v[98:101], v[158:161], v[174:177], v[98:101]
	v_mfma_f32_16x16x32_bf16 v[106:109], v[150:153], v[174:177], v[106:109]
	v_mfma_f32_16x16x32_bf16 v[90:93], v[150:153], v[182:185], v[90:93]
	v_mfma_f32_16x16x32_bf16 v[82:85], v[158:161], v[182:185], v[82:85]
	v_mfma_f32_16x16x32_bf16 v[66:69], v[158:161], v[190:193], v[66:69]
	v_mfma_f32_16x16x32_bf16 v[74:77], v[150:153], v[190:193], v[74:77]
	s_setprio 0
	s_setprio 1
	v_mfma_f32_16x16x32_bf16 v[126:129], v[130:133], v[162:165], v[126:129]
	v_mfma_f32_16x16x32_bf16 v[118:121], v[138:141], v[162:165], v[118:121]
	v_mfma_f32_16x16x32_bf16 v[102:105], v[138:141], v[170:173], v[102:105]
	v_mfma_f32_16x16x32_bf16 v[110:113], v[130:133], v[170:173], v[110:113]
	v_mfma_f32_16x16x32_bf16 v[94:97], v[130:133], v[178:181], v[94:97]
	v_mfma_f32_16x16x32_bf16 v[86:89], v[138:141], v[178:181], v[86:89]
	v_mfma_f32_16x16x32_bf16 v[70:73], v[138:141], v[186:189], v[70:73]
	v_mfma_f32_16x16x32_bf16 v[78:81], v[130:133], v[186:189], v[78:81]
	v_mfma_f32_16x16x32_bf16 v[126:129], v[134:137], v[166:169], v[126:129]
	v_mfma_f32_16x16x32_bf16 v[118:121], v[142:145], v[166:169], v[118:121]
	v_mfma_f32_16x16x32_bf16 v[102:105], v[142:145], v[174:177], v[102:105]
	v_mfma_f32_16x16x32_bf16 v[110:113], v[134:137], v[174:177], v[110:113]
	v_mfma_f32_16x16x32_bf16 v[94:97], v[134:137], v[182:185], v[94:97]
	v_mfma_f32_16x16x32_bf16 v[86:89], v[142:145], v[182:185], v[86:89]
	v_mfma_f32_16x16x32_bf16 v[70:73], v[142:145], v[190:193], v[70:73]
	v_mfma_f32_16x16x32_bf16 v[78:81], v[134:137], v[190:193], v[78:81]
	s_setprio 0
	s_barrier
	ds_read_b128 v[186:189], v224 offset:16384
	ds_read_b128 v[190:193], v224 offset:17408
	ds_read_b128 v[178:181], v224 offset:18432
	ds_read_b128 v[182:185], v224 offset:19456
	ds_read_b128 v[170:173], v224 offset:20480
	ds_read_b128 v[174:177], v224 offset:21504
	ds_read_b128 v[162:165], v224 offset:22528
	ds_read_b128 v[166:169], v224 offset:23552
	s_mov_b64 s[48:49], -1
	s_and_b64 vcc, exec, s[16:17]
	s_cbranch_vccz .LBB0_1930
	s_waitcnt vmcnt(2)
	s_mov_b64 s[48:49], 0

.LBB0_1932:
	s_waitcnt lgkmcnt(0)
	s_barrier
	s_setprio 1
	s_waitcnt lgkmcnt(0)
	v_mfma_f32_16x16x32_bf16 v[58:61], v[146:149], v[186:189], v[58:61]
	v_mfma_f32_16x16x32_bf16 v[50:53], v[154:157], v[186:189], v[50:53]
	v_mfma_f32_16x16x32_bf16 v[34:37], v[154:157], v[178:181], v[34:37]
	v_mfma_f32_16x16x32_bf16 v[42:45], v[146:149], v[178:181], v[42:45]
	v_mfma_f32_16x16x32_bf16 v[26:29], v[146:149], v[170:173], v[26:29]
	v_mfma_f32_16x16x32_bf16 v[18:21], v[154:157], v[170:173], v[18:21]
	v_mfma_f32_16x16x32_bf16 v[2:5], v[154:157], v[162:165], v[2:5]
	v_mfma_f32_16x16x32_bf16 v[10:13], v[146:149], v[162:165], v[10:13]
	v_mfma_f32_16x16x32_bf16 v[58:61], v[150:153], v[190:193], v[58:61]
	v_mfma_f32_16x16x32_bf16 v[50:53], v[158:161], v[190:193], v[50:53]
	v_mfma_f32_16x16x32_bf16 v[34:37], v[158:161], v[182:185], v[34:37]
	v_mfma_f32_16x16x32_bf16 v[42:45], v[150:153], v[182:185], v[42:45]
	v_mfma_f32_16x16x32_bf16 v[26:29], v[150:153], v[174:177], v[26:29]
	v_mfma_f32_16x16x32_bf16 v[18:21], v[158:161], v[174:177], v[18:21]
	v_mfma_f32_16x16x32_bf16 v[2:5], v[158:161], v[166:169], v[2:5]
	v_mfma_f32_16x16x32_bf16 v[10:13], v[150:153], v[166:169], v[10:13]
	s_setprio 0
	s_setprio 1
	v_mfma_f32_16x16x32_bf16 v[62:65], v[130:133], v[186:189], v[62:65]
	v_mfma_f32_16x16x32_bf16 v[54:57], v[138:141], v[186:189], v[54:57]
	v_mfma_f32_16x16x32_bf16 v[38:41], v[138:141], v[178:181], v[38:41]
	v_mfma_f32_16x16x32_bf16 v[46:49], v[130:133], v[178:181], v[46:49]
	v_mfma_f32_16x16x32_bf16 v[30:33], v[130:133], v[170:173], v[30:33]
	v_mfma_f32_16x16x32_bf16 v[22:25], v[138:141], v[170:173], v[22:25]
	v_mfma_f32_16x16x32_bf16 v[6:9], v[138:141], v[162:165], v[6:9]
	v_mfma_f32_16x16x32_bf16 v[14:17], v[130:133], v[162:165], v[14:17]
	v_mfma_f32_16x16x32_bf16 v[62:65], v[134:137], v[190:193], v[62:65]
	v_mfma_f32_16x16x32_bf16 v[54:57], v[142:145], v[190:193], v[54:57]
	v_mfma_f32_16x16x32_bf16 v[38:41], v[142:145], v[182:185], v[38:41]
	v_mfma_f32_16x16x32_bf16 v[46:49], v[134:137], v[182:185], v[46:49]
	v_mfma_f32_16x16x32_bf16 v[30:33], v[134:137], v[174:177], v[30:33]
	v_mfma_f32_16x16x32_bf16 v[22:25], v[142:145], v[174:177], v[22:25]
	v_mfma_f32_16x16x32_bf16 v[6:9], v[142:145], v[166:169], v[6:9]
	v_mfma_f32_16x16x32_bf16 v[14:17], v[134:137], v[166:169], v[14:17]
	s_setprio 0
	s_barrier
	v_add_u32_e32 v130, 0x18000, v221
	v_add_u32_e32 v142, 0x1c000, v221
	ds_read_b128 v[146:149], v130
	ds_read_b128 v[150:153], v130 offset:1024
	ds_read_b128 v[154:157], v130 offset:2048
	ds_read_b128 v[158:161], v130 offset:3072
	ds_read_b128 v[130:133], v142
	ds_read_b128 v[134:137], v142 offset:1024
	ds_read_b128 v[138:141], v142 offset:2048
	ds_read_b128 v[142:145], v142 offset:3072
	ds_read_b128 v[186:189], v224 offset:32768
	ds_read_b128 v[190:193], v224 offset:33792
	ds_read_b128 v[178:181], v224 offset:34816
	ds_read_b128 v[182:185], v224 offset:35840
	ds_read_b128 v[170:173], v224 offset:36864
	ds_read_b128 v[174:177], v224 offset:37888
	ds_read_b128 v[162:165], v224 offset:38912
	ds_read_b128 v[166:169], v224 offset:39936
	s_mov_b64 s[48:49], -1
	s_and_b64 vcc, exec, s[16:17]
	s_cbranch_vccz .LBB0_1934
	s_waitcnt vmcnt(0)
	s_mov_b64 s[48:49], 0

.LBB0_1936:
	s_waitcnt lgkmcnt(0)
	s_barrier
	s_setprio 1
	s_waitcnt lgkmcnt(0)
	v_mfma_f32_16x16x32_bf16 v[122:125], v[146:149], v[186:189], v[122:125]
	v_mfma_f32_16x16x32_bf16 v[114:117], v[154:157], v[186:189], v[114:117]
	v_mfma_f32_16x16x32_bf16 v[98:101], v[154:157], v[178:181], v[98:101]
	v_mfma_f32_16x16x32_bf16 v[106:109], v[146:149], v[178:181], v[106:109]
	v_mfma_f32_16x16x32_bf16 v[90:93], v[146:149], v[170:173], v[90:93]
	v_mfma_f32_16x16x32_bf16 v[82:85], v[154:157], v[170:173], v[82:85]
	v_mfma_f32_16x16x32_bf16 v[66:69], v[154:157], v[162:165], v[66:69]
	v_mfma_f32_16x16x32_bf16 v[74:77], v[146:149], v[162:165], v[74:77]
	v_mfma_f32_16x16x32_bf16 v[122:125], v[150:153], v[190:193], v[122:125]
	v_mfma_f32_16x16x32_bf16 v[114:117], v[158:161], v[190:193], v[114:117]
	v_mfma_f32_16x16x32_bf16 v[98:101], v[158:161], v[182:185], v[98:101]
	v_mfma_f32_16x16x32_bf16 v[106:109], v[150:153], v[182:185], v[106:109]
	v_mfma_f32_16x16x32_bf16 v[90:93], v[150:153], v[174:177], v[90:93]
	v_mfma_f32_16x16x32_bf16 v[82:85], v[158:161], v[174:177], v[82:85]
	v_mfma_f32_16x16x32_bf16 v[66:69], v[158:161], v[166:169], v[66:69]
	v_mfma_f32_16x16x32_bf16 v[74:77], v[150:153], v[166:169], v[74:77]
	s_setprio 0
	s_setprio 1
	v_mfma_f32_16x16x32_bf16 v[126:129], v[130:133], v[186:189], v[126:129]
	v_mfma_f32_16x16x32_bf16 v[118:121], v[138:141], v[186:189], v[118:121]
	v_mfma_f32_16x16x32_bf16 v[102:105], v[138:141], v[178:181], v[102:105]
	v_mfma_f32_16x16x32_bf16 v[110:113], v[130:133], v[178:181], v[110:113]
	v_mfma_f32_16x16x32_bf16 v[94:97], v[130:133], v[170:173], v[94:97]
	v_mfma_f32_16x16x32_bf16 v[86:89], v[138:141], v[170:173], v[86:89]
	v_mfma_f32_16x16x32_bf16 v[70:73], v[138:141], v[162:165], v[70:73]
	v_mfma_f32_16x16x32_bf16 v[78:81], v[130:133], v[162:165], v[78:81]
	v_mfma_f32_16x16x32_bf16 v[126:129], v[134:137], v[190:193], v[126:129]
	v_mfma_f32_16x16x32_bf16 v[118:121], v[142:145], v[190:193], v[118:121]
	v_mfma_f32_16x16x32_bf16 v[102:105], v[142:145], v[182:185], v[102:105]
	v_mfma_f32_16x16x32_bf16 v[110:113], v[134:137], v[182:185], v[110:113]
	v_mfma_f32_16x16x32_bf16 v[94:97], v[134:137], v[174:177], v[94:97]
	v_mfma_f32_16x16x32_bf16 v[86:89], v[142:145], v[174:177], v[86:89]
	v_mfma_f32_16x16x32_bf16 v[70:73], v[142:145], v[166:169], v[70:73]
	v_mfma_f32_16x16x32_bf16 v[78:81], v[134:137], v[166:169], v[78:81]
	s_setprio 0
	s_barrier
	ds_read_b128 v[186:189], v224 offset:49152
	ds_read_b128 v[190:193], v224 offset:50176
	ds_read_b128 v[178:181], v224 offset:51200
	ds_read_b128 v[182:185], v224 offset:52224
	ds_read_b128 v[170:173], v224 offset:53248
	ds_read_b128 v[174:177], v224 offset:54272
	ds_read_b128 v[162:165], v224 offset:55296
	ds_read_b128 v[166:169], v224 offset:56320
	s_mov_b64 s[46:47], -1
	s_and_b64 vcc, exec, s[16:17]
	s_cbranch_vccz .LBB0_1938
	s_waitcnt vmcnt(0)
	s_mov_b64 s[46:47], 0

.LBB0_2052:
	s_waitcnt lgkmcnt(0)
	s_barrier
	s_setprio 1
	s_waitcnt lgkmcnt(0)
	v_mfma_f32_16x16x32_bf16 v[2:5], v[146:149], v[186:189], v[2:5]
	v_mfma_f32_16x16x32_bf16 v[6:9], v[154:157], v[186:189], v[6:9]
	v_mfma_f32_16x16x32_bf16 v[14:17], v[154:157], v[178:181], v[14:17]
	v_mfma_f32_16x16x32_bf16 v[10:13], v[146:149], v[178:181], v[10:13]
	v_mfma_f32_16x16x32_bf16 v[18:21], v[146:149], v[170:173], v[18:21]
	v_mfma_f32_16x16x32_bf16 v[22:25], v[154:157], v[170:173], v[22:25]
	v_mfma_f32_16x16x32_bf16 v[30:33], v[154:157], v[162:165], v[30:33]
	v_mfma_f32_16x16x32_bf16 v[26:29], v[146:149], v[162:165], v[26:29]
	v_mfma_f32_16x16x32_bf16 v[2:5], v[150:153], v[190:193], v[2:5]
	v_mfma_f32_16x16x32_bf16 v[6:9], v[158:161], v[190:193], v[6:9]
	v_mfma_f32_16x16x32_bf16 v[14:17], v[158:161], v[182:185], v[14:17]
	v_mfma_f32_16x16x32_bf16 v[10:13], v[150:153], v[182:185], v[10:13]
	v_mfma_f32_16x16x32_bf16 v[18:21], v[150:153], v[174:177], v[18:21]
	v_mfma_f32_16x16x32_bf16 v[22:25], v[158:161], v[174:177], v[22:25]
	v_mfma_f32_16x16x32_bf16 v[30:33], v[158:161], v[166:169], v[30:33]
	v_mfma_f32_16x16x32_bf16 v[26:29], v[150:153], v[166:169], v[26:29]
	s_setprio 0
	s_setprio 1
	v_mfma_f32_16x16x32_bf16 v[34:37], v[130:133], v[186:189], v[34:37]
	v_mfma_f32_16x16x32_bf16 v[38:41], v[138:141], v[186:189], v[38:41]
	v_mfma_f32_16x16x32_bf16 v[46:49], v[138:141], v[178:181], v[46:49]
	v_mfma_f32_16x16x32_bf16 v[42:45], v[130:133], v[178:181], v[42:45]
	v_mfma_f32_16x16x32_bf16 v[50:53], v[130:133], v[170:173], v[50:53]
	v_mfma_f32_16x16x32_bf16 v[54:57], v[138:141], v[170:173], v[54:57]
	v_mfma_f32_16x16x32_bf16 v[62:65], v[138:141], v[162:165], v[62:65]
	v_mfma_f32_16x16x32_bf16 v[58:61], v[130:133], v[162:165], v[58:61]
	v_mfma_f32_16x16x32_bf16 v[34:37], v[134:137], v[190:193], v[34:37]
	v_mfma_f32_16x16x32_bf16 v[38:41], v[142:145], v[190:193], v[38:41]
	v_mfma_f32_16x16x32_bf16 v[46:49], v[142:145], v[182:185], v[46:49]
	v_mfma_f32_16x16x32_bf16 v[42:45], v[134:137], v[182:185], v[42:45]
	v_mfma_f32_16x16x32_bf16 v[50:53], v[134:137], v[174:177], v[50:53]
	v_mfma_f32_16x16x32_bf16 v[54:57], v[142:145], v[174:177], v[54:57]
	v_mfma_f32_16x16x32_bf16 v[62:65], v[142:145], v[166:169], v[62:65]
	v_mfma_f32_16x16x32_bf16 v[58:61], v[134:137], v[166:169], v[58:61]
	s_setprio 0
	s_barrier
	s_add_i32 s69, s69, 2
	s_add_u32 s26, s26, 0x100
	s_addc_u32 s27, s27, 0
	s_cmp_gt_u32 s69, 41
	s_cbranch_scc1 .LBB0_2065
.LBB0_2053:
	ds_read_b128 v[146:149], v218
	ds_read_b128 v[150:153], v218 offset:1024
	ds_read_b128 v[154:157], v218 offset:2048
	ds_read_b128 v[158:161], v218 offset:3072
	ds_read_b128 v[130:133], v219
	ds_read_b128 v[134:137], v219 offset:1024
	ds_read_b128 v[138:141], v219 offset:2048
	ds_read_b128 v[142:145], v219 offset:3072
	s_add_u32 s30, s67, s26
	s_addc_u32 s31, s68, s27
	s_cmpk_lg_i32 s26, 0x1400
	s_cselect_b64 s[34:35], -1, 0
	s_and_b64 s[28:29], s[34:35], exec
	s_cselect_b32 s29, s31, s25
	s_cselect_b32 s28, s30, s24
	v_lshl_add_u64 v[210:211], v[206:207], 0, s[26:27]
	s_mov_b32 m0, s60
	v_lshl_add_u64 v[212:213], v[210:211], 0, s[18:19]
	ds_read_b128 v[162:165], v220
	ds_read_b128 v[166:169], v220 offset:1024
	ds_read_b128 v[170:173], v220 offset:2048
	ds_read_b128 v[174:177], v220 offset:3072
	ds_read_b128 v[178:181], v220 offset:4096
	ds_read_b128 v[182:185], v220 offset:5120
	ds_read_b128 v[186:189], v220 offset:6144
	ds_read_b128 v[190:193], v220 offset:7168
	global_load_lds_dwordx4 v[212:213], off
	v_lshl_add_u64 v[212:213], v[208:209], 0, s[26:27]
	v_lshl_add_u64 v[222:223], v[212:213], 0, s[18:19]
	s_mov_b32 m0, s61
	v_lshl_add_u64 v[210:211], v[210:211], 0, s[20:21]
	global_load_lds_dwordx4 v[222:223], off
	s_mov_b32 m0, s62
	s_nor_b64 s[30:31], s[6:7], s[34:35]
	global_load_lds_dwordx4 v[210:211], off
	v_lshl_add_u64 v[210:211], v[212:213], 0, s[20:21]
	s_mov_b32 m0, s63
	s_nop 0
	global_load_lds_dwordx4 v[210:211], off
	s_waitcnt vmcnt(8)
	s_waitcnt lgkmcnt(0)
	s_barrier
	s_setprio 1
	s_waitcnt lgkmcnt(0)
	v_mfma_f32_16x16x32_bf16 v[66:69], v[146:149], v[162:165], v[66:69]
	v_mfma_f32_16x16x32_bf16 v[70:73], v[154:157], v[162:165], v[70:73]
	v_mfma_f32_16x16x32_bf16 v[78:81], v[154:157], v[170:173], v[78:81]
	v_mfma_f32_16x16x32_bf16 v[74:77], v[146:149], v[170:173], v[74:77]
	v_mfma_f32_16x16x32_bf16 v[82:85], v[146:149], v[178:181], v[82:85]
	v_mfma_f32_16x16x32_bf16 v[86:89], v[154:157], v[178:181], v[86:89]
	v_mfma_f32_16x16x32_bf16 v[94:97], v[154:157], v[186:189], v[94:97]
	v_mfma_f32_16x16x32_bf16 v[90:93], v[146:149], v[186:189], v[90:93]
	v_mfma_f32_16x16x32_bf16 v[66:69], v[150:153], v[166:169], v[66:69]
	v_mfma_f32_16x16x32_bf16 v[70:73], v[158:161], v[166:169], v[70:73]
	v_mfma_f32_16x16x32_bf16 v[78:81], v[158:161], v[174:177], v[78:81]
	v_mfma_f32_16x16x32_bf16 v[74:77], v[150:153], v[174:177], v[74:77]
	v_mfma_f32_16x16x32_bf16 v[82:85], v[150:153], v[182:185], v[82:85]
	v_mfma_f32_16x16x32_bf16 v[86:89], v[158:161], v[182:185], v[86:89]
	v_mfma_f32_16x16x32_bf16 v[94:97], v[158:161], v[190:193], v[94:97]
	v_mfma_f32_16x16x32_bf16 v[90:93], v[150:153], v[190:193], v[90:93]
	s_setprio 0
	s_setprio 1
	v_mfma_f32_16x16x32_bf16 v[98:101], v[130:133], v[162:165], v[98:101]
	v_mfma_f32_16x16x32_bf16 v[102:105], v[138:141], v[162:165], v[102:105]
	v_mfma_f32_16x16x32_bf16 v[110:113], v[138:141], v[170:173], v[110:113]
	v_mfma_f32_16x16x32_bf16 v[106:109], v[130:133], v[170:173], v[106:109]
	v_mfma_f32_16x16x32_bf16 v[114:117], v[130:133], v[178:181], v[114:117]
	v_mfma_f32_16x16x32_bf16 v[118:121], v[138:141], v[178:181], v[118:121]
	v_mfma_f32_16x16x32_bf16 v[126:129], v[138:141], v[186:189], v[126:129]
	v_mfma_f32_16x16x32_bf16 v[122:125], v[130:133], v[186:189], v[122:125]
	v_mfma_f32_16x16x32_bf16 v[98:101], v[134:137], v[166:169], v[98:101]
	v_mfma_f32_16x16x32_bf16 v[102:105], v[142:145], v[166:169], v[102:105]
	v_mfma_f32_16x16x32_bf16 v[110:113], v[142:145], v[174:177], v[110:113]
	v_mfma_f32_16x16x32_bf16 v[106:109], v[134:137], v[174:177], v[106:109]
	v_mfma_f32_16x16x32_bf16 v[114:117], v[134:137], v[182:185], v[114:117]
	v_mfma_f32_16x16x32_bf16 v[118:121], v[142:145], v[182:185], v[118:121]
	v_mfma_f32_16x16x32_bf16 v[126:129], v[142:145], v[190:193], v[126:129]
	v_mfma_f32_16x16x32_bf16 v[122:125], v[134:137], v[190:193], v[122:125]
	s_setprio 0
	s_barrier
	ds_read_b128 v[186:189], v220 offset:16384
	ds_read_b128 v[190:193], v220 offset:17408
	ds_read_b128 v[178:181], v220 offset:18432
	ds_read_b128 v[182:185], v220 offset:19456
	ds_read_b128 v[170:173], v220 offset:20480
	ds_read_b128 v[174:177], v220 offset:21504
	ds_read_b128 v[162:165], v220 offset:22528
	ds_read_b128 v[166:169], v220 offset:23552
	s_mov_b64 s[36:37], -1
	s_and_b64 vcc, exec, s[30:31]
	s_cbranch_vccz .LBB0_2055
	s_waitcnt vmcnt(2)
	s_mov_b64 s[36:37], 0

.LBB0_2057:
	s_waitcnt lgkmcnt(0)
	s_barrier
	s_setprio 1
	s_waitcnt lgkmcnt(0)
	v_mfma_f32_16x16x32_bf16 v[2:5], v[146:149], v[186:189], v[2:5]
	v_mfma_f32_16x16x32_bf16 v[6:9], v[154:157], v[186:189], v[6:9]
	v_mfma_f32_16x16x32_bf16 v[14:17], v[154:157], v[178:181], v[14:17]
	v_mfma_f32_16x16x32_bf16 v[10:13], v[146:149], v[178:181], v[10:13]
	v_mfma_f32_16x16x32_bf16 v[18:21], v[146:149], v[170:173], v[18:21]
	v_mfma_f32_16x16x32_bf16 v[22:25], v[154:157], v[170:173], v[22:25]
	v_mfma_f32_16x16x32_bf16 v[30:33], v[154:157], v[162:165], v[30:33]
	v_mfma_f32_16x16x32_bf16 v[26:29], v[146:149], v[162:165], v[26:29]
	v_mfma_f32_16x16x32_bf16 v[2:5], v[150:153], v[190:193], v[2:5]
	v_mfma_f32_16x16x32_bf16 v[6:9], v[158:161], v[190:193], v[6:9]
	v_mfma_f32_16x16x32_bf16 v[14:17], v[158:161], v[182:185], v[14:17]
	v_mfma_f32_16x16x32_bf16 v[10:13], v[150:153], v[182:185], v[10:13]
	v_mfma_f32_16x16x32_bf16 v[18:21], v[150:153], v[174:177], v[18:21]
	v_mfma_f32_16x16x32_bf16 v[22:25], v[158:161], v[174:177], v[22:25]
	v_mfma_f32_16x16x32_bf16 v[30:33], v[158:161], v[166:169], v[30:33]
	v_mfma_f32_16x16x32_bf16 v[26:29], v[150:153], v[166:169], v[26:29]
	s_setprio 0
	s_setprio 1
	v_mfma_f32_16x16x32_bf16 v[34:37], v[130:133], v[186:189], v[34:37]
	v_mfma_f32_16x16x32_bf16 v[38:41], v[138:141], v[186:189], v[38:41]
	v_mfma_f32_16x16x32_bf16 v[46:49], v[138:141], v[178:181], v[46:49]
	v_mfma_f32_16x16x32_bf16 v[42:45], v[130:133], v[178:181], v[42:45]
	v_mfma_f32_16x16x32_bf16 v[50:53], v[130:133], v[170:173], v[50:53]
	v_mfma_f32_16x16x32_bf16 v[54:57], v[138:141], v[170:173], v[54:57]
	v_mfma_f32_16x16x32_bf16 v[62:65], v[138:141], v[162:165], v[62:65]
	v_mfma_f32_16x16x32_bf16 v[58:61], v[130:133], v[162:165], v[58:61]
	v_mfma_f32_16x16x32_bf16 v[34:37], v[134:137], v[190:193], v[34:37]
	v_mfma_f32_16x16x32_bf16 v[38:41], v[142:145], v[190:193], v[38:41]
	v_mfma_f32_16x16x32_bf16 v[46:49], v[142:145], v[182:185], v[46:49]
	v_mfma_f32_16x16x32_bf16 v[42:45], v[134:137], v[182:185], v[42:45]
	v_mfma_f32_16x16x32_bf16 v[50:53], v[134:137], v[174:177], v[50:53]
	v_mfma_f32_16x16x32_bf16 v[54:57], v[142:145], v[174:177], v[54:57]
	v_mfma_f32_16x16x32_bf16 v[62:65], v[142:145], v[166:169], v[62:65]
	v_mfma_f32_16x16x32_bf16 v[58:61], v[134:137], v[166:169], v[58:61]
	s_setprio 0
	s_barrier
	v_add_u32_e32 v130, 0x18000, v217
	v_add_u32_e32 v142, 0x1c000, v217
	ds_read_b128 v[146:149], v130
	ds_read_b128 v[150:153], v130 offset:1024
	ds_read_b128 v[154:157], v130 offset:2048
	ds_read_b128 v[158:161], v130 offset:3072
	ds_read_b128 v[130:133], v142
	ds_read_b128 v[134:137], v142 offset:1024
	ds_read_b128 v[138:141], v142 offset:2048
	ds_read_b128 v[142:145], v142 offset:3072
	ds_read_b128 v[186:189], v220 offset:32768
	ds_read_b128 v[190:193], v220 offset:33792
	ds_read_b128 v[178:181], v220 offset:34816
	ds_read_b128 v[182:185], v220 offset:35840
	ds_read_b128 v[170:173], v220 offset:36864
	ds_read_b128 v[174:177], v220 offset:37888
	ds_read_b128 v[162:165], v220 offset:38912
	ds_read_b128 v[166:169], v220 offset:39936
	s_mov_b64 s[36:37], -1
	s_and_b64 vcc, exec, s[30:31]
	s_cbranch_vccz .LBB0_2059
	s_waitcnt vmcnt(0)
	s_mov_b64 s[36:37], 0

.LBB0_2061:
	s_waitcnt lgkmcnt(0)
	s_barrier
	s_setprio 1
	s_waitcnt lgkmcnt(0)
	v_mfma_f32_16x16x32_bf16 v[66:69], v[146:149], v[186:189], v[66:69]
	v_mfma_f32_16x16x32_bf16 v[70:73], v[154:157], v[186:189], v[70:73]
	v_mfma_f32_16x16x32_bf16 v[78:81], v[154:157], v[178:181], v[78:81]
	v_mfma_f32_16x16x32_bf16 v[74:77], v[146:149], v[178:181], v[74:77]
	v_mfma_f32_16x16x32_bf16 v[82:85], v[146:149], v[170:173], v[82:85]
	v_mfma_f32_16x16x32_bf16 v[86:89], v[154:157], v[170:173], v[86:89]
	v_mfma_f32_16x16x32_bf16 v[94:97], v[154:157], v[162:165], v[94:97]
	v_mfma_f32_16x16x32_bf16 v[90:93], v[146:149], v[162:165], v[90:93]
	v_mfma_f32_16x16x32_bf16 v[66:69], v[150:153], v[190:193], v[66:69]
	v_mfma_f32_16x16x32_bf16 v[70:73], v[158:161], v[190:193], v[70:73]
	v_mfma_f32_16x16x32_bf16 v[78:81], v[158:161], v[182:185], v[78:81]
	v_mfma_f32_16x16x32_bf16 v[74:77], v[150:153], v[182:185], v[74:77]
	v_mfma_f32_16x16x32_bf16 v[82:85], v[150:153], v[174:177], v[82:85]
	v_mfma_f32_16x16x32_bf16 v[86:89], v[158:161], v[174:177], v[86:89]
	v_mfma_f32_16x16x32_bf16 v[94:97], v[158:161], v[166:169], v[94:97]
	v_mfma_f32_16x16x32_bf16 v[90:93], v[150:153], v[166:169], v[90:93]
	s_setprio 0
	s_setprio 1
	v_mfma_f32_16x16x32_bf16 v[98:101], v[130:133], v[186:189], v[98:101]
	v_mfma_f32_16x16x32_bf16 v[102:105], v[138:141], v[186:189], v[102:105]
	v_mfma_f32_16x16x32_bf16 v[110:113], v[138:141], v[178:181], v[110:113]
	v_mfma_f32_16x16x32_bf16 v[106:109], v[130:133], v[178:181], v[106:109]
	v_mfma_f32_16x16x32_bf16 v[114:117], v[130:133], v[170:173], v[114:117]
	v_mfma_f32_16x16x32_bf16 v[118:121], v[138:141], v[170:173], v[118:121]
	v_mfma_f32_16x16x32_bf16 v[126:129], v[138:141], v[162:165], v[126:129]
	v_mfma_f32_16x16x32_bf16 v[122:125], v[130:133], v[162:165], v[122:125]
	v_mfma_f32_16x16x32_bf16 v[98:101], v[134:137], v[190:193], v[98:101]
	v_mfma_f32_16x16x32_bf16 v[102:105], v[142:145], v[190:193], v[102:105]
	v_mfma_f32_16x16x32_bf16 v[110:113], v[142:145], v[182:185], v[110:113]
	v_mfma_f32_16x16x32_bf16 v[106:109], v[134:137], v[182:185], v[106:109]
	v_mfma_f32_16x16x32_bf16 v[114:117], v[134:137], v[174:177], v[114:117]
	v_mfma_f32_16x16x32_bf16 v[118:121], v[142:145], v[174:177], v[118:121]
	v_mfma_f32_16x16x32_bf16 v[126:129], v[142:145], v[166:169], v[126:129]
	v_mfma_f32_16x16x32_bf16 v[122:125], v[134:137], v[166:169], v[122:125]
	s_setprio 0
	s_barrier
	ds_read_b128 v[186:189], v220 offset:49152
	ds_read_b128 v[190:193], v220 offset:50176
	ds_read_b128 v[178:181], v220 offset:51200
	ds_read_b128 v[182:185], v220 offset:52224
	ds_read_b128 v[170:173], v220 offset:53248
	ds_read_b128 v[174:177], v220 offset:54272
	ds_read_b128 v[162:165], v220 offset:55296
	ds_read_b128 v[166:169], v220 offset:56320
	s_mov_b64 s[34:35], -1
	s_and_b64 vcc, exec, s[30:31]
	s_cbranch_vccz .LBB0_2063
	s_waitcnt vmcnt(0)
	s_mov_b64 s[34:35], 0

.LBB0_2113:
	s_waitcnt lgkmcnt(0)
	s_barrier
	s_setprio 1
	s_waitcnt lgkmcnt(0)
	v_mfma_f32_16x16x32_bf16 v[48:51], v[152:155], v[184:187], v[48:51]
	v_mfma_f32_16x16x32_bf16 v[52:55], v[144:147], v[184:187], v[52:55]
	v_mfma_f32_16x16x32_bf16 v[36:39], v[144:147], v[176:179], v[36:39]
	v_mfma_f32_16x16x32_bf16 v[32:35], v[152:155], v[176:179], v[32:35]
	v_mfma_f32_16x16x32_bf16 v[16:19], v[152:155], v[168:171], v[16:19]
	v_mfma_f32_16x16x32_bf16 v[20:23], v[144:147], v[168:171], v[20:23]
	v_mfma_f32_16x16x32_bf16 v[4:7], v[144:147], v[160:163], v[4:7]
	v_mfma_f32_16x16x32_bf16 v[12:15], v[152:155], v[160:163], v[12:15]
	v_mfma_f32_16x16x32_bf16 v[48:51], v[156:159], v[188:191], v[48:51]
	v_mfma_f32_16x16x32_bf16 v[52:55], v[148:151], v[188:191], v[52:55]
	v_mfma_f32_16x16x32_bf16 v[36:39], v[148:151], v[180:183], v[36:39]
	v_mfma_f32_16x16x32_bf16 v[32:35], v[156:159], v[180:183], v[32:35]
	v_mfma_f32_16x16x32_bf16 v[16:19], v[156:159], v[172:175], v[16:19]
	v_mfma_f32_16x16x32_bf16 v[20:23], v[148:151], v[172:175], v[20:23]
	v_mfma_f32_16x16x32_bf16 v[4:7], v[148:151], v[164:167], v[4:7]
	v_mfma_f32_16x16x32_bf16 v[12:15], v[156:159], v[164:167], v[12:15]
	s_setprio 0
	s_setprio 1
	v_mfma_f32_16x16x32_bf16 v[56:59], v[136:139], v[184:187], v[56:59]
	v_mfma_f32_16x16x32_bf16 v[60:63], v[128:131], v[184:187], v[60:63]
	v_mfma_f32_16x16x32_bf16 v[44:47], v[128:131], v[176:179], v[44:47]
	v_mfma_f32_16x16x32_bf16 v[40:43], v[136:139], v[176:179], v[40:43]
	v_mfma_f32_16x16x32_bf16 v[24:27], v[136:139], v[168:171], v[24:27]
	v_mfma_f32_16x16x32_bf16 v[28:31], v[128:131], v[168:171], v[28:31]
	v_mfma_f32_16x16x32_bf16 v[0:3], v[128:131], v[160:163], v[0:3]
	v_mfma_f32_16x16x32_bf16 v[8:11], v[136:139], v[160:163], v[8:11]
	v_mfma_f32_16x16x32_bf16 v[56:59], v[140:143], v[188:191], v[56:59]
	v_mfma_f32_16x16x32_bf16 v[60:63], v[132:135], v[188:191], v[60:63]
	v_mfma_f32_16x16x32_bf16 v[44:47], v[132:135], v[180:183], v[44:47]
	v_mfma_f32_16x16x32_bf16 v[40:43], v[140:143], v[180:183], v[40:43]
	v_mfma_f32_16x16x32_bf16 v[24:27], v[140:143], v[172:175], v[24:27]
	v_mfma_f32_16x16x32_bf16 v[28:31], v[132:135], v[172:175], v[28:31]
	v_mfma_f32_16x16x32_bf16 v[0:3], v[132:135], v[164:167], v[0:3]
	v_mfma_f32_16x16x32_bf16 v[8:11], v[140:143], v[164:167], v[8:11]
	s_setprio 0
	s_barrier
	s_add_i32 s75, s75, 2
	s_add_u32 s36, s36, 0x100
	s_addc_u32 s37, s37, 0
	s_cmp_gt_u32 s75, 41
	s_cbranch_scc1 .LBB0_2126
.LBB0_2114:
	ds_read_b128 v[144:147], v216
	ds_read_b128 v[148:151], v216 offset:1024
	ds_read_b128 v[152:155], v216 offset:2048
	ds_read_b128 v[156:159], v216 offset:3072
	ds_read_b128 v[128:131], v217
	ds_read_b128 v[132:135], v217 offset:1024
	ds_read_b128 v[136:139], v217 offset:2048
	ds_read_b128 v[140:143], v217 offset:3072
	s_add_u32 s40, s73, s36
	s_addc_u32 s41, s74, s37
	s_cmpk_lg_i32 s36, 0x1400
	s_cselect_b64 s[42:43], -1, 0
	s_and_b64 s[38:39], s[42:43], exec
	s_cselect_b32 s39, s41, s31
	s_cselect_b32 s38, s40, s30
	v_lshl_add_u64 v[208:209], v[204:205], 0, s[36:37]
	s_mov_b32 m0, s65
	v_lshl_add_u64 v[210:211], v[208:209], 0, s[16:17]
	ds_read_b128 v[160:163], v218
	ds_read_b128 v[164:167], v218 offset:1024
	ds_read_b128 v[168:171], v218 offset:2048
	ds_read_b128 v[172:175], v218 offset:3072
	ds_read_b128 v[176:179], v218 offset:4096
	ds_read_b128 v[180:183], v218 offset:5120
	ds_read_b128 v[184:187], v218 offset:6144
	ds_read_b128 v[188:191], v218 offset:7168
	global_load_lds_dwordx4 v[210:211], off
	v_lshl_add_u64 v[210:211], v[206:207], 0, s[36:37]
	v_lshl_add_u64 v[220:221], v[210:211], 0, s[16:17]
	s_mov_b32 m0, s66
	v_lshl_add_u64 v[208:209], v[208:209], 0, s[18:19]
	global_load_lds_dwordx4 v[220:221], off
	s_mov_b32 m0, s67
	s_nor_b64 s[40:41], s[4:5], s[42:43]
	global_load_lds_dwordx4 v[208:209], off
	v_lshl_add_u64 v[208:209], v[210:211], 0, s[18:19]
	s_mov_b32 m0, s68
	s_nop 0
	global_load_lds_dwordx4 v[208:209], off
	s_waitcnt vmcnt(8)
	s_waitcnt lgkmcnt(0)
	s_barrier
	s_setprio 1
	s_waitcnt lgkmcnt(0)
	v_mfma_f32_16x16x32_bf16 v[116:119], v[144:147], v[160:163], v[116:119]
	v_mfma_f32_16x16x32_bf16 v[112:115], v[152:155], v[160:163], v[112:115]
	v_mfma_f32_16x16x32_bf16 v[96:99], v[152:155], v[168:171], v[96:99]
	v_mfma_f32_16x16x32_bf16 v[100:103], v[144:147], v[168:171], v[100:103]
	v_mfma_f32_16x16x32_bf16 v[84:87], v[144:147], v[176:179], v[84:87]
	v_mfma_f32_16x16x32_bf16 v[80:83], v[152:155], v[176:179], v[80:83]
	v_mfma_f32_16x16x32_bf16 v[64:67], v[152:155], v[184:187], v[64:67]
	v_mfma_f32_16x16x32_bf16 v[68:71], v[144:147], v[184:187], v[68:71]
	v_mfma_f32_16x16x32_bf16 v[116:119], v[148:151], v[164:167], v[116:119]
	v_mfma_f32_16x16x32_bf16 v[112:115], v[156:159], v[164:167], v[112:115]
	v_mfma_f32_16x16x32_bf16 v[96:99], v[156:159], v[172:175], v[96:99]
	v_mfma_f32_16x16x32_bf16 v[100:103], v[148:151], v[172:175], v[100:103]
	v_mfma_f32_16x16x32_bf16 v[84:87], v[148:151], v[180:183], v[84:87]
	v_mfma_f32_16x16x32_bf16 v[80:83], v[156:159], v[180:183], v[80:83]
	v_mfma_f32_16x16x32_bf16 v[64:67], v[156:159], v[188:191], v[64:67]
	v_mfma_f32_16x16x32_bf16 v[68:71], v[148:151], v[188:191], v[68:71]
	s_setprio 0
	s_setprio 1
	v_mfma_f32_16x16x32_bf16 v[124:127], v[128:131], v[160:163], v[124:127]
	v_mfma_f32_16x16x32_bf16 v[120:123], v[136:139], v[160:163], v[120:123]
	v_mfma_f32_16x16x32_bf16 v[104:107], v[136:139], v[168:171], v[104:107]
	v_mfma_f32_16x16x32_bf16 v[108:111], v[128:131], v[168:171], v[108:111]
	v_mfma_f32_16x16x32_bf16 v[92:95], v[128:131], v[176:179], v[92:95]
	v_mfma_f32_16x16x32_bf16 v[88:91], v[136:139], v[176:179], v[88:91]
	v_mfma_f32_16x16x32_bf16 v[72:75], v[136:139], v[184:187], v[72:75]
	v_mfma_f32_16x16x32_bf16 v[76:79], v[128:131], v[184:187], v[76:79]
	v_mfma_f32_16x16x32_bf16 v[124:127], v[132:135], v[164:167], v[124:127]
	v_mfma_f32_16x16x32_bf16 v[120:123], v[140:143], v[164:167], v[120:123]
	v_mfma_f32_16x16x32_bf16 v[104:107], v[140:143], v[172:175], v[104:107]
	v_mfma_f32_16x16x32_bf16 v[108:111], v[132:135], v[172:175], v[108:111]
	v_mfma_f32_16x16x32_bf16 v[92:95], v[132:135], v[180:183], v[92:95]
	v_mfma_f32_16x16x32_bf16 v[88:91], v[140:143], v[180:183], v[88:91]
	v_mfma_f32_16x16x32_bf16 v[72:75], v[140:143], v[188:191], v[72:75]
	v_mfma_f32_16x16x32_bf16 v[76:79], v[132:135], v[188:191], v[76:79]
	s_setprio 0
	s_barrier
	ds_read_b128 v[184:187], v218 offset:16384
	ds_read_b128 v[188:191], v218 offset:17408
	ds_read_b128 v[176:179], v218 offset:18432
	ds_read_b128 v[180:183], v218 offset:19456
	ds_read_b128 v[168:171], v218 offset:20480
	ds_read_b128 v[172:175], v218 offset:21504
	ds_read_b128 v[160:163], v218 offset:22528
	ds_read_b128 v[164:167], v218 offset:23552
	s_mov_b64 s[44:45], -1
	s_and_b64 vcc, exec, s[40:41]
	s_cbranch_vccz .LBB0_2116
	s_waitcnt vmcnt(2)
	s_mov_b64 s[44:45], 0

.LBB0_2118:
	s_waitcnt lgkmcnt(0)
	s_barrier
	s_setprio 1
	s_waitcnt lgkmcnt(0)
	v_mfma_f32_16x16x32_bf16 v[48:51], v[144:147], v[184:187], v[48:51]
	v_mfma_f32_16x16x32_bf16 v[52:55], v[152:155], v[184:187], v[52:55]
	v_mfma_f32_16x16x32_bf16 v[36:39], v[152:155], v[176:179], v[36:39]
	v_mfma_f32_16x16x32_bf16 v[32:35], v[144:147], v[176:179], v[32:35]
	v_mfma_f32_16x16x32_bf16 v[16:19], v[144:147], v[168:171], v[16:19]
	v_mfma_f32_16x16x32_bf16 v[20:23], v[152:155], v[168:171], v[20:23]
	v_mfma_f32_16x16x32_bf16 v[4:7], v[152:155], v[160:163], v[4:7]
	v_mfma_f32_16x16x32_bf16 v[12:15], v[144:147], v[160:163], v[12:15]
	v_mfma_f32_16x16x32_bf16 v[48:51], v[148:151], v[188:191], v[48:51]
	v_mfma_f32_16x16x32_bf16 v[52:55], v[156:159], v[188:191], v[52:55]
	v_mfma_f32_16x16x32_bf16 v[36:39], v[156:159], v[180:183], v[36:39]
	v_mfma_f32_16x16x32_bf16 v[32:35], v[148:151], v[180:183], v[32:35]
	v_mfma_f32_16x16x32_bf16 v[16:19], v[148:151], v[172:175], v[16:19]
	v_mfma_f32_16x16x32_bf16 v[20:23], v[156:159], v[172:175], v[20:23]
	v_mfma_f32_16x16x32_bf16 v[4:7], v[156:159], v[164:167], v[4:7]
	v_mfma_f32_16x16x32_bf16 v[12:15], v[148:151], v[164:167], v[12:15]
	s_setprio 0
	s_setprio 1
	v_mfma_f32_16x16x32_bf16 v[56:59], v[128:131], v[184:187], v[56:59]
	v_mfma_f32_16x16x32_bf16 v[60:63], v[136:139], v[184:187], v[60:63]
	v_mfma_f32_16x16x32_bf16 v[44:47], v[136:139], v[176:179], v[44:47]
	v_mfma_f32_16x16x32_bf16 v[40:43], v[128:131], v[176:179], v[40:43]
	v_mfma_f32_16x16x32_bf16 v[24:27], v[128:131], v[168:171], v[24:27]
	v_mfma_f32_16x16x32_bf16 v[28:31], v[136:139], v[168:171], v[28:31]
	v_mfma_f32_16x16x32_bf16 v[0:3], v[136:139], v[160:163], v[0:3]
	v_mfma_f32_16x16x32_bf16 v[8:11], v[128:131], v[160:163], v[8:11]
	v_mfma_f32_16x16x32_bf16 v[56:59], v[132:135], v[188:191], v[56:59]
	v_mfma_f32_16x16x32_bf16 v[60:63], v[140:143], v[188:191], v[60:63]
	v_mfma_f32_16x16x32_bf16 v[44:47], v[140:143], v[180:183], v[44:47]
	v_mfma_f32_16x16x32_bf16 v[40:43], v[132:135], v[180:183], v[40:43]
	v_mfma_f32_16x16x32_bf16 v[24:27], v[132:135], v[172:175], v[24:27]
	v_mfma_f32_16x16x32_bf16 v[28:31], v[140:143], v[172:175], v[28:31]
	v_mfma_f32_16x16x32_bf16 v[0:3], v[140:143], v[164:167], v[0:3]
	v_mfma_f32_16x16x32_bf16 v[8:11], v[132:135], v[164:167], v[8:11]
	s_setprio 0
	s_barrier
	v_add_u32_e32 v128, 0x18000, v215
	v_add_u32_e32 v132, 0x1c000, v215
	ds_read_b128 v[152:155], v128
	ds_read_b128 v[156:159], v128 offset:1024
	ds_read_b128 v[144:147], v128 offset:2048
	ds_read_b128 v[148:151], v128 offset:3072
	ds_read_b128 v[136:139], v132
	ds_read_b128 v[140:143], v132 offset:1024
	ds_read_b128 v[128:131], v132 offset:2048
	ds_read_b128 v[132:135], v132 offset:3072
	ds_read_b128 v[184:187], v218 offset:32768
	ds_read_b128 v[188:191], v218 offset:33792
	ds_read_b128 v[176:179], v218 offset:34816
	ds_read_b128 v[180:183], v218 offset:35840
	ds_read_b128 v[168:171], v218 offset:36864
	ds_read_b128 v[172:175], v218 offset:37888
	ds_read_b128 v[160:163], v218 offset:38912
	ds_read_b128 v[164:167], v218 offset:39936
	s_mov_b64 s[44:45], -1
	s_and_b64 vcc, exec, s[40:41]
	s_cbranch_vccz .LBB0_2120
	s_waitcnt vmcnt(0)
	s_mov_b64 s[44:45], 0

.LBB0_2122:
	s_waitcnt lgkmcnt(0)
	s_barrier
	s_setprio 1
	s_waitcnt lgkmcnt(0)
	v_mfma_f32_16x16x32_bf16 v[116:119], v[152:155], v[184:187], v[116:119]
	v_mfma_f32_16x16x32_bf16 v[112:115], v[144:147], v[184:187], v[112:115]
	v_mfma_f32_16x16x32_bf16 v[96:99], v[144:147], v[176:179], v[96:99]
	v_mfma_f32_16x16x32_bf16 v[100:103], v[152:155], v[176:179], v[100:103]
	v_mfma_f32_16x16x32_bf16 v[84:87], v[152:155], v[168:171], v[84:87]
	v_mfma_f32_16x16x32_bf16 v[80:83], v[144:147], v[168:171], v[80:83]
	v_mfma_f32_16x16x32_bf16 v[64:67], v[144:147], v[160:163], v[64:67]
	v_mfma_f32_16x16x32_bf16 v[68:71], v[152:155], v[160:163], v[68:71]
	v_mfma_f32_16x16x32_bf16 v[116:119], v[156:159], v[188:191], v[116:119]
	v_mfma_f32_16x16x32_bf16 v[112:115], v[148:151], v[188:191], v[112:115]
	v_mfma_f32_16x16x32_bf16 v[96:99], v[148:151], v[180:183], v[96:99]
	v_mfma_f32_16x16x32_bf16 v[100:103], v[156:159], v[180:183], v[100:103]
	v_mfma_f32_16x16x32_bf16 v[84:87], v[156:159], v[172:175], v[84:87]
	v_mfma_f32_16x16x32_bf16 v[80:83], v[148:151], v[172:175], v[80:83]
	v_mfma_f32_16x16x32_bf16 v[64:67], v[148:151], v[164:167], v[64:67]
	v_mfma_f32_16x16x32_bf16 v[68:71], v[156:159], v[164:167], v[68:71]
	s_setprio 0
	s_setprio 1
	v_mfma_f32_16x16x32_bf16 v[124:127], v[136:139], v[184:187], v[124:127]
	v_mfma_f32_16x16x32_bf16 v[120:123], v[128:131], v[184:187], v[120:123]
	v_mfma_f32_16x16x32_bf16 v[104:107], v[128:131], v[176:179], v[104:107]
	v_mfma_f32_16x16x32_bf16 v[108:111], v[136:139], v[176:179], v[108:111]
	v_mfma_f32_16x16x32_bf16 v[92:95], v[136:139], v[168:171], v[92:95]
	v_mfma_f32_16x16x32_bf16 v[88:91], v[128:131], v[168:171], v[88:91]
	v_mfma_f32_16x16x32_bf16 v[72:75], v[128:131], v[160:163], v[72:75]
	v_mfma_f32_16x16x32_bf16 v[76:79], v[136:139], v[160:163], v[76:79]
	v_mfma_f32_16x16x32_bf16 v[124:127], v[140:143], v[188:191], v[124:127]
	v_mfma_f32_16x16x32_bf16 v[120:123], v[132:135], v[188:191], v[120:123]
	v_mfma_f32_16x16x32_bf16 v[104:107], v[132:135], v[180:183], v[104:107]
	v_mfma_f32_16x16x32_bf16 v[108:111], v[140:143], v[180:183], v[108:111]
	v_mfma_f32_16x16x32_bf16 v[92:95], v[140:143], v[172:175], v[92:95]
	v_mfma_f32_16x16x32_bf16 v[88:91], v[132:135], v[172:175], v[88:91]
	v_mfma_f32_16x16x32_bf16 v[72:75], v[132:135], v[164:167], v[72:75]
	v_mfma_f32_16x16x32_bf16 v[76:79], v[140:143], v[164:167], v[76:79]
	s_setprio 0
	s_barrier
	ds_read_b128 v[184:187], v218 offset:49152
	ds_read_b128 v[188:191], v218 offset:50176
	ds_read_b128 v[176:179], v218 offset:51200
	ds_read_b128 v[180:183], v218 offset:52224
	ds_read_b128 v[168:171], v218 offset:53248
	ds_read_b128 v[172:175], v218 offset:54272
	ds_read_b128 v[160:163], v218 offset:55296
	ds_read_b128 v[164:167], v218 offset:56320
	s_mov_b64 s[42:43], -1
	s_and_b64 vcc, exec, s[40:41]
	s_cbranch_vccz .LBB0_2124
	s_waitcnt vmcnt(0)
	s_mov_b64 s[42:43], 0
